# stack: priority-staged early closing barrier N=2 + leading-half realign barrier moved into the epilogue + SwiGLU address increments
# baseline (speedup 1.0000x reference)
.Lmid_gemm0:
	s_add_i32 s18, 0, 0x18000
	s_add_i32 s19, 0, 0x1c000
	v_add_u32_e32 v158, s18, v145
	v_add_u32_e32 v174, s19, v145
	ds_read_b128 v[140:143], v158
	ds_read_b128 v[150:153], v158 offset:1024
	ds_read_b128 v[154:157], v158 offset:2048
	ds_read_b128 v[158:161], v158 offset:3072
	ds_read_b128 v[162:165], v174
	ds_read_b128 v[166:169], v174 offset:1024
	ds_read_b128 v[170:173], v174 offset:2048
	ds_read_b128 v[174:177], v174 offset:3072
	s_add_u32 s48, s48, 0x40000
	s_addc_u32 s49, s49, 0
	s_mov_b32 m0, s57
	v_lshl_add_u64 v[222:223], s[48:49], 0, v[130:131]
	ds_read_b128 v[184:187], v149 offset:32768
	ds_read_b128 v[188:191], v149 offset:33792
	ds_read_b128 v[192:195], v149 offset:34816
	ds_read_b128 v[196:199], v149 offset:35840
	ds_read_b128 v[200:203], v149 offset:36864
	ds_read_b128 v[204:207], v149 offset:37888
	ds_read_b128 v[208:211], v149 offset:38912
	ds_read_b128 v[212:215], v149 offset:39936
	global_load_lds_dwordx4 v[222:223], off
	v_lshl_add_u64 v[222:223], s[48:49], 0, v[128:129]
	s_mov_b32 m0, s58
	s_nop 0
	global_load_lds_dwordx4 v[222:223], off
	s_waitcnt vmcnt(8)
	s_waitcnt lgkmcnt(0)
	s_barrier
	s_waitcnt lgkmcnt(0)
	v_mfma_f32_16x16x32_bf16 v[124:127], v[140:143], v[184:187], v[124:127]
	v_mfma_f32_16x16x32_bf16 v[124:127], v[150:153], v[188:191], v[124:127]
	s_setprio 1
	v_mfma_f32_16x16x32_bf16 v[120:123], v[154:157], v[184:187], v[120:123]
	v_mfma_f32_16x16x32_bf16 v[120:123], v[158:161], v[188:191], v[120:123]
	v_mfma_f32_16x16x32_bf16 v[108:111], v[140:143], v[192:195], v[108:111]
	v_mfma_f32_16x16x32_bf16 v[108:111], v[150:153], v[196:199], v[108:111]
	v_mfma_f32_16x16x32_bf16 v[104:107], v[154:157], v[192:195], v[104:107]
	v_mfma_f32_16x16x32_bf16 v[104:107], v[158:161], v[196:199], v[104:107]
	v_mfma_f32_16x16x32_bf16 v[92:95], v[140:143], v[200:203], v[92:95]
	v_mfma_f32_16x16x32_bf16 v[92:95], v[150:153], v[204:207], v[92:95]
	v_mfma_f32_16x16x32_bf16 v[88:91], v[154:157], v[200:203], v[88:91]
	v_mfma_f32_16x16x32_bf16 v[88:91], v[158:161], v[204:207], v[88:91]
	v_mfma_f32_16x16x32_bf16 v[76:79], v[140:143], v[208:211], v[76:79]
	v_mfma_f32_16x16x32_bf16 v[76:79], v[150:153], v[212:215], v[76:79]
	v_mfma_f32_16x16x32_bf16 v[72:75], v[154:157], v[208:211], v[72:75]
	v_mfma_f32_16x16x32_bf16 v[72:75], v[158:161], v[212:215], v[72:75]
	v_mfma_f32_16x16x32_bf16 v[116:119], v[162:165], v[184:187], v[116:119]
	v_mfma_f32_16x16x32_bf16 v[116:119], v[166:169], v[188:191], v[116:119]
	v_mfma_f32_16x16x32_bf16 v[112:115], v[170:173], v[184:187], v[112:115]
	v_mfma_f32_16x16x32_bf16 v[112:115], v[174:177], v[188:191], v[112:115]
	v_mfma_f32_16x16x32_bf16 v[100:103], v[162:165], v[192:195], v[100:103]
	v_mfma_f32_16x16x32_bf16 v[100:103], v[166:169], v[196:199], v[100:103]
	v_mfma_f32_16x16x32_bf16 v[96:99], v[170:173], v[192:195], v[96:99]
	v_mfma_f32_16x16x32_bf16 v[96:99], v[174:177], v[196:199], v[96:99]
	v_mfma_f32_16x16x32_bf16 v[84:87], v[162:165], v[200:203], v[84:87]
	v_mfma_f32_16x16x32_bf16 v[84:87], v[166:169], v[204:207], v[84:87]
	v_mfma_f32_16x16x32_bf16 v[80:83], v[170:173], v[200:203], v[80:83]
	v_mfma_f32_16x16x32_bf16 v[80:83], v[174:177], v[204:207], v[80:83]
	v_mfma_f32_16x16x32_bf16 v[68:71], v[162:165], v[208:211], v[68:71]
	v_mfma_f32_16x16x32_bf16 v[68:71], v[166:169], v[212:215], v[68:71]
	s_barrier
	v_mfma_f32_16x16x32_bf16 v[64:67], v[170:173], v[208:211], v[64:67]
	v_mfma_f32_16x16x32_bf16 v[64:67], v[174:177], v[212:215], v[64:67]
	s_setprio 0
	s_add_i32 s18, s18, s54
	v_lshl_add_u64 v[178:179], v[178:179], 0, s[6:7]
	s_mov_b32 m0, s18
	ds_read_b128 v[184:187], v149 offset:49152
	ds_read_b128 v[188:191], v149 offset:50176
	ds_read_b128 v[192:195], v149 offset:51200
	ds_read_b128 v[196:199], v149 offset:52224
	ds_read_b128 v[200:203], v149 offset:53248
	ds_read_b128 v[204:207], v149 offset:54272
	ds_read_b128 v[208:211], v149 offset:55296
	ds_read_b128 v[212:215], v149 offset:56320
	global_load_lds_dwordx4 v[178:179], off
	s_add_i32 m0, s18, 0x2000
	s_add_u32 s46, s46, 0x40080
	v_lshl_add_u64 v[178:179], v[216:217], 0, s[6:7]
	s_addc_u32 s47, s47, 0
	s_add_i32 s18, s19, s54
	global_load_lds_dwordx4 v[178:179], off
	v_lshl_add_u64 v[178:179], s[46:47], 0, v[130:131]
	s_mov_b32 m0, s18
	s_nop 0
	global_load_lds_dwordx4 v[178:179], off
	v_lshl_add_u64 v[178:179], s[46:47], 0, v[128:129]
	s_add_i32 m0, s18, 0x2000
	s_nop 0
	global_load_lds_dwordx4 v[178:179], off
	v_lshl_add_u64 v[178:179], v[218:219], 0, s[6:7]
	s_mov_b32 m0, s60
	s_nop 0
	global_load_lds_dwordx4 v[178:179], off
	v_lshl_add_u64 v[178:179], v[220:221], 0, s[6:7]
	s_mov_b32 m0, s61
	s_nop 0
	global_load_lds_dwordx4 v[178:179], off
	s_waitcnt vmcnt(8)
	s_waitcnt lgkmcnt(0)
	s_barrier
	s_waitcnt lgkmcnt(0)
	v_mfma_f32_16x16x32_bf16 v[60:63], v[140:143], v[184:187], v[60:63]
	v_mfma_f32_16x16x32_bf16 v[60:63], v[150:153], v[188:191], v[60:63]
	s_setprio 1
	v_mfma_f32_16x16x32_bf16 v[56:59], v[154:157], v[184:187], v[56:59]
	v_mfma_f32_16x16x32_bf16 v[56:59], v[158:161], v[188:191], v[56:59]
	v_mfma_f32_16x16x32_bf16 v[44:47], v[140:143], v[192:195], v[44:47]
	v_mfma_f32_16x16x32_bf16 v[44:47], v[150:153], v[196:199], v[44:47]
	v_mfma_f32_16x16x32_bf16 v[40:43], v[154:157], v[192:195], v[40:43]
	v_mfma_f32_16x16x32_bf16 v[40:43], v[158:161], v[196:199], v[40:43]
	v_mfma_f32_16x16x32_bf16 v[28:31], v[140:143], v[200:203], v[28:31]
	v_mfma_f32_16x16x32_bf16 v[28:31], v[150:153], v[204:207], v[28:31]
	v_mfma_f32_16x16x32_bf16 v[24:27], v[154:157], v[200:203], v[24:27]
	v_mfma_f32_16x16x32_bf16 v[24:27], v[158:161], v[204:207], v[24:27]
	v_mfma_f32_16x16x32_bf16 v[12:15], v[140:143], v[208:211], v[12:15]
	v_mfma_f32_16x16x32_bf16 v[12:15], v[150:153], v[212:215], v[12:15]
	v_mfma_f32_16x16x32_bf16 v[8:11], v[154:157], v[208:211], v[8:11]
	v_mfma_f32_16x16x32_bf16 v[8:11], v[158:161], v[212:215], v[8:11]
	v_mfma_f32_16x16x32_bf16 v[52:55], v[162:165], v[184:187], v[52:55]
	v_mfma_f32_16x16x32_bf16 v[52:55], v[166:169], v[188:191], v[52:55]
	v_mfma_f32_16x16x32_bf16 v[48:51], v[170:173], v[184:187], v[48:51]
	v_mfma_f32_16x16x32_bf16 v[48:51], v[174:177], v[188:191], v[48:51]
	v_mfma_f32_16x16x32_bf16 v[36:39], v[162:165], v[192:195], v[36:39]
	v_mfma_f32_16x16x32_bf16 v[36:39], v[166:169], v[196:199], v[36:39]
	v_mfma_f32_16x16x32_bf16 v[32:35], v[170:173], v[192:195], v[32:35]
	v_mfma_f32_16x16x32_bf16 v[32:35], v[174:177], v[196:199], v[32:35]
	v_mfma_f32_16x16x32_bf16 v[20:23], v[162:165], v[200:203], v[20:23]
	v_mfma_f32_16x16x32_bf16 v[20:23], v[166:169], v[204:207], v[20:23]
	v_mfma_f32_16x16x32_bf16 v[16:19], v[170:173], v[200:203], v[16:19]
	v_mfma_f32_16x16x32_bf16 v[16:19], v[174:177], v[204:207], v[16:19]
	v_mfma_f32_16x16x32_bf16 v[4:7], v[162:165], v[208:211], v[4:7]
	v_mfma_f32_16x16x32_bf16 v[4:7], v[166:169], v[212:215], v[4:7]
	s_barrier
	v_mfma_f32_16x16x32_bf16 v[0:3], v[170:173], v[208:211], v[0:3]
	v_mfma_f32_16x16x32_bf16 v[0:3], v[174:177], v[212:215], v[0:3]
	s_setprio 0
	s_add_i32 s70, s70, 2
	s_add_u32 s44, s44, 0x100
	s_addc_u32 s45, s45, 0
	s_add_u32 s68, s68, 0x100
	s_addc_u32 s69, s69, 0
	s_cmp_gt_u32 s70, 13
	s_cbranch_scc0 .LBB0_184
.LBB0_187:
	s_mov_b64 s[98:99], 0x16000
	s_mov_b64 s[100:101], 0x6e000
	v_mul_f32_e32 v151, 0xbfb8aa3b, v124
	v_exp_f32_e32 v151, v151
	v_mul_f32_e32 v154, 0xbfb8aa3b, v125
	v_exp_f32_e32 v154, v154
	v_lshl_or_b32 v142, s65, 7, v146
	v_add_f32_e32 v151, 1.0, v151
	v_rcp_f32_e32 v151, v151
	v_lshl_add_u32 v150, s36, 8, v144
	v_ashrrev_i32_e32 v143, 31, v142
	v_mov_b64_e32 v[140:141], s[22:23]
	v_mul_f32_e32 v124, v124, v151
	v_mul_f32_e32 v120, v120, v124
	v_add_f32_e32 v124, 1.0, v154
	v_mul_f32_e32 v151, 0xbfb8aa3b, v126
	v_rcp_f32_e32 v124, v124
	v_exp_f32_e32 v151, v151
	v_mul_f32_e32 v154, 0xbfb8aa3b, v127
	v_exp_f32_e32 v154, v154
	v_mul_f32_e32 v124, v125, v124
	v_add_f32_e32 v125, 1.0, v151
	v_rcp_f32_e32 v125, v125
	v_add_f32_e32 v151, 1.0, v154
	v_rcp_f32_e32 v151, v151
	v_mul_f32_e32 v121, v121, v124
	v_mul_f32_e32 v124, v126, v125
	v_mul_f32_e32 v125, 0xbfb8aa3b, v116
	v_exp_f32_e32 v125, v125
	v_mul_f32_e32 v122, v122, v124
	v_mul_f32_e32 v124, v127, v151
	v_mul_f32_e32 v123, v123, v124
	v_cvt_pk_bf16_f32 v120, v120, v121
	v_cvt_pk_bf16_f32 v121, v122, v123
	v_add_f32_e32 v122, 1.0, v125
	v_rcp_f32_e32 v122, v122
	v_mul_f32_e32 v123, 0xbfb8aa3b, v117
	v_exp_f32_e32 v123, v123
	v_mad_i64_i32 v[152:153], s[44:45], v150, s64, v[140:141]
	v_lshlrev_b64 v[142:143], 1, v[142:143]
	v_lshl_add_u64 v[152:153], v[152:153], 0, v[142:143]
	v_mul_f32_e32 v116, v116, v122
	global_store_dwordx2 v[152:153], v[120:121], off
	v_mul_f32_e32 v112, v112, v116
	v_add_f32_e32 v116, 1.0, v123
	v_mul_f32_e32 v120, 0xbfb8aa3b, v118
	v_rcp_f32_e32 v116, v116
	v_exp_f32_e32 v120, v120
	v_mul_f32_e32 v121, 0xbfb8aa3b, v119
	v_exp_f32_e32 v121, v121
	v_mul_f32_e32 v116, v117, v116
	v_add_f32_e32 v117, 1.0, v120
	v_rcp_f32_e32 v117, v117
	v_add_f32_e32 v120, 1.0, v121
	v_rcp_f32_e32 v120, v120
	v_mul_f32_e32 v113, v113, v116
	v_mul_f32_e32 v116, v118, v117
	v_mul_f32_e32 v114, v114, v116
	v_mul_f32_e32 v116, v119, v120
	v_cvt_pk_bf16_f32 v112, v112, v113
	v_mul_f32_e32 v115, v115, v116
	v_cvt_pk_bf16_f32 v113, v114, v115
	global_store_dwordx2 v[152:153], v[112:113], off offset:128
	v_mul_f32_e32 v112, 0xbfb8aa3b, v108
	v_exp_f32_e32 v114, v112
	v_mul_f32_e32 v115, 0xbfb8aa3b, v109
	s_and_b64 vcc, exec, s[8:9]
	s_cbranch_vccz .Lxb_0
	s_barrier
.Lxb_0:
	v_exp_f32_e32 v115, v115
	v_add_f32_e32 v114, 1.0, v114
	v_rcp_f32_e32 v114, v114
	v_lshl_add_u64 v[112:113], v[152:153], 0, s[98:99]
	v_mul_f32_e32 v108, v108, v114
	v_mul_f32_e32 v104, v104, v108
	v_add_f32_e32 v108, 1.0, v115
	v_mul_f32_e32 v114, 0xbfb8aa3b, v110
	v_rcp_f32_e32 v108, v108
	v_exp_f32_e32 v114, v114
	v_mul_f32_e32 v115, 0xbfb8aa3b, v111
	v_exp_f32_e32 v115, v115
	v_mul_f32_e32 v108, v109, v108
	v_add_f32_e32 v109, 1.0, v114
	v_rcp_f32_e32 v109, v109
	v_add_f32_e32 v114, 1.0, v115
	v_rcp_f32_e32 v114, v114
	v_mul_f32_e32 v105, v105, v108
	v_mul_f32_e32 v108, v110, v109
	v_mul_f32_e32 v109, 0xbfb8aa3b, v100
	v_exp_f32_e32 v109, v109
	v_mul_f32_e32 v106, v106, v108
	v_mul_f32_e32 v108, v111, v114
	v_mul_f32_e32 v107, v107, v108
	v_cvt_pk_bf16_f32 v104, v104, v105
	v_cvt_pk_bf16_f32 v105, v106, v107
	v_add_f32_e32 v106, 1.0, v109
	v_rcp_f32_e32 v106, v106
	v_mul_f32_e32 v107, 0xbfb8aa3b, v101
	v_exp_f32_e32 v107, v107
	global_store_dwordx2 v[112:113], v[104:105], off
	v_mul_f32_e32 v100, v100, v106
	v_mul_f32_e32 v96, v96, v100
	v_add_f32_e32 v100, 1.0, v107
	v_mul_f32_e32 v104, 0xbfb8aa3b, v102
	v_rcp_f32_e32 v100, v100
	v_exp_f32_e32 v104, v104
	v_mul_f32_e32 v105, 0xbfb8aa3b, v103
	v_exp_f32_e32 v105, v105
	v_mul_f32_e32 v100, v101, v100
	v_add_f32_e32 v101, 1.0, v104
	v_rcp_f32_e32 v101, v101
	v_add_f32_e32 v104, 1.0, v105
	v_rcp_f32_e32 v104, v104
	v_mul_f32_e32 v97, v97, v100
	v_mul_f32_e32 v100, v102, v101
	v_mul_f32_e32 v98, v98, v100
	v_mul_f32_e32 v100, v103, v104
	v_cvt_pk_bf16_f32 v96, v96, v97
	v_mul_f32_e32 v99, v99, v100
	v_cvt_pk_bf16_f32 v97, v98, v99
	global_store_dwordx2 v[112:113], v[96:97], off offset:128
	v_mul_f32_e32 v96, 0xbfb8aa3b, v92
	v_exp_f32_e32 v98, v96
	v_mul_f32_e32 v99, 0xbfb8aa3b, v93
	v_exp_f32_e32 v99, v99
	v_add_f32_e32 v98, 1.0, v98
	v_rcp_f32_e32 v98, v98
	v_lshl_add_u64 v[96:97], v[112:113], 0, s[98:99]
	v_mul_f32_e32 v92, v92, v98
	v_mul_f32_e32 v88, v88, v92
	v_add_f32_e32 v92, 1.0, v99
	v_mul_f32_e32 v98, 0xbfb8aa3b, v94
	v_rcp_f32_e32 v92, v92
	v_exp_f32_e32 v98, v98
	v_mul_f32_e32 v99, 0xbfb8aa3b, v95
	v_exp_f32_e32 v99, v99
	v_mul_f32_e32 v92, v93, v92
	v_add_f32_e32 v93, 1.0, v98
	v_rcp_f32_e32 v93, v93
	v_add_f32_e32 v98, 1.0, v99
	v_rcp_f32_e32 v98, v98
	v_mul_f32_e32 v89, v89, v92
	v_mul_f32_e32 v92, v94, v93
	v_mul_f32_e32 v93, 0xbfb8aa3b, v84
	v_exp_f32_e32 v93, v93
	v_mul_f32_e32 v90, v90, v92
	v_mul_f32_e32 v92, v95, v98
	v_mul_f32_e32 v91, v91, v92
	v_cvt_pk_bf16_f32 v88, v88, v89
	v_cvt_pk_bf16_f32 v89, v90, v91
	v_add_f32_e32 v90, 1.0, v93
	v_rcp_f32_e32 v90, v90
	v_mul_f32_e32 v91, 0xbfb8aa3b, v85
	v_exp_f32_e32 v91, v91
	global_store_dwordx2 v[96:97], v[88:89], off
	v_mul_f32_e32 v84, v84, v90
	v_mul_f32_e32 v80, v80, v84
	v_add_f32_e32 v84, 1.0, v91
	v_mul_f32_e32 v88, 0xbfb8aa3b, v86
	v_rcp_f32_e32 v84, v84
	v_exp_f32_e32 v88, v88
	v_mul_f32_e32 v89, 0xbfb8aa3b, v87
	v_exp_f32_e32 v89, v89
	v_mul_f32_e32 v84, v85, v84
	v_add_f32_e32 v85, 1.0, v88
	v_rcp_f32_e32 v85, v85
	v_add_f32_e32 v88, 1.0, v89
	v_rcp_f32_e32 v88, v88
	v_mul_f32_e32 v81, v81, v84
	v_mul_f32_e32 v84, v86, v85
	v_mul_f32_e32 v82, v82, v84
	v_mul_f32_e32 v84, v87, v88
	v_cvt_pk_bf16_f32 v80, v80, v81
	v_mul_f32_e32 v83, v83, v84
	v_cvt_pk_bf16_f32 v81, v82, v83
	global_store_dwordx2 v[96:97], v[80:81], off offset:128
	v_mul_f32_e32 v80, 0xbfb8aa3b, v76
	v_exp_f32_e32 v82, v80
	v_mul_f32_e32 v83, 0xbfb8aa3b, v77
	v_exp_f32_e32 v83, v83
	v_add_f32_e32 v82, 1.0, v82
	v_rcp_f32_e32 v82, v82
	v_lshl_add_u64 v[80:81], v[96:97], 0, s[98:99]
	v_mul_f32_e32 v76, v76, v82
	v_mul_f32_e32 v72, v72, v76
	v_add_f32_e32 v76, 1.0, v83
	v_mul_f32_e32 v82, 0xbfb8aa3b, v78
	v_rcp_f32_e32 v76, v76
	v_exp_f32_e32 v82, v82
	v_mul_f32_e32 v83, 0xbfb8aa3b, v79
	v_exp_f32_e32 v83, v83
	v_mul_f32_e32 v76, v77, v76
	v_add_f32_e32 v77, 1.0, v82
	v_rcp_f32_e32 v77, v77
	v_add_f32_e32 v82, 1.0, v83
	v_rcp_f32_e32 v82, v82
	v_mul_f32_e32 v73, v73, v76
	v_mul_f32_e32 v76, v78, v77
	v_mul_f32_e32 v77, 0xbfb8aa3b, v68
	v_exp_f32_e32 v77, v77
	v_mul_f32_e32 v74, v74, v76
	v_mul_f32_e32 v76, v79, v82
	v_mul_f32_e32 v75, v75, v76
	v_cvt_pk_bf16_f32 v72, v72, v73
	v_cvt_pk_bf16_f32 v73, v74, v75
	v_add_f32_e32 v74, 1.0, v77
	v_rcp_f32_e32 v74, v74
	v_mul_f32_e32 v75, 0xbfb8aa3b, v69
	v_exp_f32_e32 v75, v75
	global_store_dwordx2 v[80:81], v[72:73], off
	v_mul_f32_e32 v68, v68, v74
	v_mul_f32_e32 v64, v64, v68
	v_add_f32_e32 v68, 1.0, v75
	v_mul_f32_e32 v72, 0xbfb8aa3b, v70
	v_rcp_f32_e32 v68, v68
	v_exp_f32_e32 v72, v72
	v_mul_f32_e32 v73, 0xbfb8aa3b, v71
	v_exp_f32_e32 v73, v73
	v_mul_f32_e32 v68, v69, v68
	v_add_f32_e32 v69, 1.0, v72
	v_rcp_f32_e32 v69, v69
	v_add_f32_e32 v72, 1.0, v73
	v_rcp_f32_e32 v72, v72
	v_mul_f32_e32 v65, v65, v68
	v_mul_f32_e32 v68, v70, v69
	v_mul_f32_e32 v66, v66, v68
	v_mul_f32_e32 v68, v71, v72
	v_cvt_pk_bf16_f32 v64, v64, v65
	v_mul_f32_e32 v67, v67, v68
	v_cvt_pk_bf16_f32 v65, v66, v67
	global_store_dwordx2 v[80:81], v[64:65], off offset:128
	v_mul_f32_e32 v64, 0xbfb8aa3b, v60
	v_exp_f32_e32 v66, v64
	v_mul_f32_e32 v67, 0xbfb8aa3b, v61
	v_exp_f32_e32 v67, v67
	v_add_f32_e32 v66, 1.0, v66
	v_rcp_f32_e32 v66, v66
	v_lshl_add_u64 v[64:65], v[80:81], 0, s[100:101]
	v_mul_f32_e32 v60, v60, v66
	v_mul_f32_e32 v56, v56, v60
	v_add_f32_e32 v60, 1.0, v67
	v_mul_f32_e32 v66, 0xbfb8aa3b, v62
	v_rcp_f32_e32 v60, v60
	v_exp_f32_e32 v66, v66
	v_mul_f32_e32 v67, 0xbfb8aa3b, v63
	v_exp_f32_e32 v67, v67
	v_mul_f32_e32 v60, v61, v60
	v_add_f32_e32 v61, 1.0, v66
	v_rcp_f32_e32 v61, v61
	v_add_f32_e32 v66, 1.0, v67
	v_rcp_f32_e32 v66, v66
	v_mul_f32_e32 v57, v57, v60
	v_mul_f32_e32 v60, v62, v61
	v_mul_f32_e32 v61, 0xbfb8aa3b, v52
	v_exp_f32_e32 v61, v61
	v_mul_f32_e32 v58, v58, v60
	v_mul_f32_e32 v60, v63, v66
	v_mul_f32_e32 v59, v59, v60
	v_cvt_pk_bf16_f32 v56, v56, v57
	v_cvt_pk_bf16_f32 v57, v58, v59
	v_add_f32_e32 v58, 1.0, v61
	v_rcp_f32_e32 v58, v58
	v_mul_f32_e32 v59, 0xbfb8aa3b, v53
	v_exp_f32_e32 v59, v59
	global_store_dwordx2 v[64:65], v[56:57], off
	v_mul_f32_e32 v52, v52, v58
	v_mul_f32_e32 v48, v48, v52
	v_add_f32_e32 v52, 1.0, v59
	v_mul_f32_e32 v56, 0xbfb8aa3b, v54
	v_rcp_f32_e32 v52, v52
	v_exp_f32_e32 v56, v56
	v_mul_f32_e32 v57, 0xbfb8aa3b, v55
	v_exp_f32_e32 v57, v57
	v_mul_f32_e32 v52, v53, v52
	v_add_f32_e32 v53, 1.0, v56
	v_rcp_f32_e32 v53, v53
	v_add_f32_e32 v56, 1.0, v57
	v_rcp_f32_e32 v56, v56
	v_mul_f32_e32 v49, v49, v52
	v_mul_f32_e32 v52, v54, v53
	v_mul_f32_e32 v50, v50, v52
	v_mul_f32_e32 v52, v55, v56
	v_cvt_pk_bf16_f32 v48, v48, v49
	v_mul_f32_e32 v51, v51, v52
	v_cvt_pk_bf16_f32 v49, v50, v51
	global_store_dwordx2 v[64:65], v[48:49], off offset:128
	v_mul_f32_e32 v48, 0xbfb8aa3b, v44
	v_exp_f32_e32 v50, v48
	v_mul_f32_e32 v51, 0xbfb8aa3b, v45
	v_exp_f32_e32 v51, v51
	v_add_f32_e32 v50, 1.0, v50
	v_rcp_f32_e32 v50, v50
	v_lshl_add_u64 v[48:49], v[64:65], 0, s[98:99]
	v_mul_f32_e32 v44, v44, v50
	v_mul_f32_e32 v40, v40, v44
	v_add_f32_e32 v44, 1.0, v51
	v_mul_f32_e32 v50, 0xbfb8aa3b, v46
	v_rcp_f32_e32 v44, v44
	v_exp_f32_e32 v50, v50
	v_mul_f32_e32 v51, 0xbfb8aa3b, v47
	v_exp_f32_e32 v51, v51
	v_mul_f32_e32 v44, v45, v44
	v_add_f32_e32 v45, 1.0, v50
	v_rcp_f32_e32 v45, v45
	v_add_f32_e32 v50, 1.0, v51
	v_rcp_f32_e32 v50, v50
	v_mul_f32_e32 v41, v41, v44
	v_mul_f32_e32 v44, v46, v45
	v_mul_f32_e32 v45, 0xbfb8aa3b, v36
	v_exp_f32_e32 v45, v45
	v_mul_f32_e32 v42, v42, v44
	v_mul_f32_e32 v44, v47, v50
	v_mul_f32_e32 v43, v43, v44
	v_cvt_pk_bf16_f32 v40, v40, v41
	v_cvt_pk_bf16_f32 v41, v42, v43
	v_add_f32_e32 v42, 1.0, v45
	v_rcp_f32_e32 v42, v42
	v_mul_f32_e32 v43, 0xbfb8aa3b, v37
	v_exp_f32_e32 v43, v43
	global_store_dwordx2 v[48:49], v[40:41], off
	v_mul_f32_e32 v36, v36, v42
	v_mul_f32_e32 v32, v32, v36
	v_add_f32_e32 v36, 1.0, v43
	v_mul_f32_e32 v40, 0xbfb8aa3b, v38
	v_rcp_f32_e32 v36, v36
	v_exp_f32_e32 v40, v40
	v_mul_f32_e32 v41, 0xbfb8aa3b, v39
	v_exp_f32_e32 v41, v41
	v_mul_f32_e32 v36, v37, v36
	v_add_f32_e32 v37, 1.0, v40
	v_rcp_f32_e32 v37, v37
	v_add_f32_e32 v40, 1.0, v41
	v_rcp_f32_e32 v40, v40
	v_mul_f32_e32 v33, v33, v36
	v_mul_f32_e32 v36, v38, v37
	v_mul_f32_e32 v34, v34, v36
	v_mul_f32_e32 v36, v39, v40
	v_cvt_pk_bf16_f32 v32, v32, v33
	v_mul_f32_e32 v35, v35, v36
	v_cvt_pk_bf16_f32 v33, v34, v35
	global_store_dwordx2 v[48:49], v[32:33], off offset:128
	v_mul_f32_e32 v32, 0xbfb8aa3b, v28
	v_exp_f32_e32 v34, v32
	v_mul_f32_e32 v35, 0xbfb8aa3b, v29
	v_exp_f32_e32 v35, v35
	v_add_f32_e32 v34, 1.0, v34
	v_rcp_f32_e32 v34, v34
	v_lshl_add_u64 v[32:33], v[48:49], 0, s[98:99]
	v_mul_f32_e32 v28, v28, v34
	v_mul_f32_e32 v24, v24, v28
	v_add_f32_e32 v28, 1.0, v35
	v_mul_f32_e32 v34, 0xbfb8aa3b, v30
	v_rcp_f32_e32 v28, v28
	v_exp_f32_e32 v34, v34
	v_mul_f32_e32 v35, 0xbfb8aa3b, v31
	v_exp_f32_e32 v35, v35
	v_mul_f32_e32 v28, v29, v28
	v_add_f32_e32 v29, 1.0, v34
	v_rcp_f32_e32 v29, v29
	v_add_f32_e32 v34, 1.0, v35
	v_rcp_f32_e32 v34, v34
	v_mul_f32_e32 v25, v25, v28
	v_mul_f32_e32 v28, v30, v29
	v_mul_f32_e32 v29, 0xbfb8aa3b, v20
	v_exp_f32_e32 v29, v29
	v_mul_f32_e32 v26, v26, v28
	v_mul_f32_e32 v28, v31, v34
	v_mul_f32_e32 v27, v27, v28
	v_cvt_pk_bf16_f32 v24, v24, v25
	v_cvt_pk_bf16_f32 v25, v26, v27
	v_add_f32_e32 v26, 1.0, v29
	v_rcp_f32_e32 v26, v26
	v_mul_f32_e32 v27, 0xbfb8aa3b, v21
	v_exp_f32_e32 v27, v27
	global_store_dwordx2 v[32:33], v[24:25], off
	v_mul_f32_e32 v20, v20, v26
	v_mul_f32_e32 v16, v16, v20
	v_add_f32_e32 v20, 1.0, v27
	v_mul_f32_e32 v24, 0xbfb8aa3b, v22
	v_rcp_f32_e32 v20, v20
	v_exp_f32_e32 v24, v24
	v_mul_f32_e32 v25, 0xbfb8aa3b, v23
	v_exp_f32_e32 v25, v25
	v_mul_f32_e32 v20, v21, v20
	v_add_f32_e32 v21, 1.0, v24
	v_rcp_f32_e32 v21, v21
	v_add_f32_e32 v24, 1.0, v25
	v_rcp_f32_e32 v24, v24
	v_mul_f32_e32 v17, v17, v20
	v_mul_f32_e32 v20, v22, v21
	v_mul_f32_e32 v18, v18, v20
	v_mul_f32_e32 v20, v23, v24
	v_cvt_pk_bf16_f32 v16, v16, v17
	v_mul_f32_e32 v19, v19, v20
	v_cvt_pk_bf16_f32 v17, v18, v19
	global_store_dwordx2 v[32:33], v[16:17], off offset:128
	v_mul_f32_e32 v16, 0xbfb8aa3b, v12
	v_exp_f32_e32 v18, v16
	v_mul_f32_e32 v19, 0xbfb8aa3b, v13
	v_exp_f32_e32 v19, v19
	v_add_f32_e32 v18, 1.0, v18
	v_rcp_f32_e32 v18, v18
	v_lshl_add_u64 v[16:17], v[32:33], 0, s[98:99]
	v_mul_f32_e32 v12, v12, v18
	v_mul_f32_e32 v8, v8, v12
	v_add_f32_e32 v12, 1.0, v19
	v_mul_f32_e32 v18, 0xbfb8aa3b, v14
	v_rcp_f32_e32 v12, v12
	v_exp_f32_e32 v18, v18
	v_mul_f32_e32 v19, 0xbfb8aa3b, v15
	v_exp_f32_e32 v19, v19
	v_mul_f32_e32 v12, v13, v12
	v_add_f32_e32 v13, 1.0, v18
	v_rcp_f32_e32 v13, v13
	v_add_f32_e32 v18, 1.0, v19
	v_rcp_f32_e32 v18, v18
	v_mul_f32_e32 v9, v9, v12
	v_mul_f32_e32 v12, v14, v13
	v_mul_f32_e32 v13, 0xbfb8aa3b, v4
	v_exp_f32_e32 v13, v13
	v_mul_f32_e32 v10, v10, v12
	v_mul_f32_e32 v12, v15, v18
	v_mul_f32_e32 v11, v11, v12
	v_cvt_pk_bf16_f32 v8, v8, v9
	v_cvt_pk_bf16_f32 v9, v10, v11
	v_add_f32_e32 v10, 1.0, v13
	v_rcp_f32_e32 v10, v10
	v_mul_f32_e32 v11, 0xbfb8aa3b, v5
	v_exp_f32_e32 v11, v11
	global_store_dwordx2 v[16:17], v[8:9], off
	v_mul_f32_e32 v4, v4, v10
	v_mul_f32_e32 v0, v0, v4
	v_add_f32_e32 v4, 1.0, v11
	v_mul_f32_e32 v8, 0xbfb8aa3b, v6
	v_rcp_f32_e32 v4, v4
	v_exp_f32_e32 v8, v8
	v_mul_f32_e32 v9, 0xbfb8aa3b, v7
	v_exp_f32_e32 v9, v9
	v_mul_f32_e32 v4, v5, v4
	v_add_f32_e32 v5, 1.0, v8
	v_rcp_f32_e32 v5, v5
	v_add_f32_e32 v8, 1.0, v9
	v_rcp_f32_e32 v8, v8
	v_mul_f32_e32 v1, v1, v4
	v_mul_f32_e32 v4, v6, v5
	v_mul_f32_e32 v2, v2, v4
	v_mul_f32_e32 v4, v7, v8
	s_andn2_b64 vcc, exec, s[4:5]
	s_mov_b64 s[4:5], -1
	v_mul_f32_e32 v3, v3, v4
	v_cvt_pk_bf16_f32 v0, v0, v1
	v_cvt_pk_bf16_f32 v1, v2, v3
	global_store_dwordx2 v[16:17], v[0:1], off offset:128
	s_cbranch_vccnz .LBB0_180
	s_andn2_b64 vcc, exec, s[0:1]
	s_cbranch_vccnz .LBB0_179
	s_barrier
	s_branch .LBB0_179

.Lmid_gemm1:
	s_add_i32 s18, 0, 0x18000
	s_add_i32 s19, 0, 0x1c000
	v_add_u32_e32 v164, s18, v147
	v_add_u32_e32 v181, s19, v147
	ds_read_b128 v[152:155], v164
	ds_read_b128 v[156:159], v164 offset:1024
	ds_read_b128 v[160:163], v164 offset:2048
	ds_read_b128 v[164:167], v164 offset:3072
	ds_read_b128 v[168:171], v181
	ds_read_b128 v[172:175], v181 offset:1024
	ds_read_b128 v[176:179], v181 offset:2048
	ds_read_b128 v[184:187], v181 offset:3072
	s_add_u32 s52, s58, 0xb0000
	s_addc_u32 s53, s59, 0
	s_mov_b32 m0, s65
	v_lshl_add_u64 v[226:227], s[52:53], 0, v[128:129]
	ds_read_b128 v[188:191], v151 offset:32768
	ds_read_b128 v[192:195], v151 offset:33792
	ds_read_b128 v[196:199], v151 offset:34816
	ds_read_b128 v[200:203], v151 offset:35840
	ds_read_b128 v[204:207], v151 offset:36864
	ds_read_b128 v[208:211], v151 offset:37888
	ds_read_b128 v[212:215], v151 offset:38912
	ds_read_b128 v[216:219], v151 offset:39936
	global_load_lds_dwordx4 v[226:227], off
	v_lshl_add_u64 v[226:227], s[52:53], 0, v[132:133]
	s_mov_b32 m0, s66
	s_nop 0
	global_load_lds_dwordx4 v[226:227], off
	s_waitcnt vmcnt(8)
	s_waitcnt lgkmcnt(0)
	s_barrier
	s_waitcnt lgkmcnt(0)
	v_mfma_f32_16x16x32_bf16 v[124:127], v[152:155], v[188:191], v[124:127]
	v_mfma_f32_16x16x32_bf16 v[124:127], v[156:159], v[192:195], v[124:127]
	s_setprio 1
	v_mfma_f32_16x16x32_bf16 v[120:123], v[160:163], v[188:191], v[120:123]
	v_mfma_f32_16x16x32_bf16 v[120:123], v[164:167], v[192:195], v[120:123]
	v_mfma_f32_16x16x32_bf16 v[116:119], v[152:155], v[196:199], v[116:119]
	v_mfma_f32_16x16x32_bf16 v[116:119], v[156:159], v[200:203], v[116:119]
	v_mfma_f32_16x16x32_bf16 v[108:111], v[160:163], v[196:199], v[108:111]
	v_mfma_f32_16x16x32_bf16 v[108:111], v[164:167], v[200:203], v[108:111]
	v_mfma_f32_16x16x32_bf16 v[100:103], v[152:155], v[204:207], v[100:103]
	v_mfma_f32_16x16x32_bf16 v[100:103], v[156:159], v[208:211], v[100:103]
	v_mfma_f32_16x16x32_bf16 v[92:95], v[160:163], v[204:207], v[92:95]
	v_mfma_f32_16x16x32_bf16 v[92:95], v[164:167], v[208:211], v[92:95]
	v_mfma_f32_16x16x32_bf16 v[84:87], v[152:155], v[212:215], v[84:87]
	v_mfma_f32_16x16x32_bf16 v[84:87], v[156:159], v[216:219], v[84:87]
	v_mfma_f32_16x16x32_bf16 v[76:79], v[160:163], v[212:215], v[76:79]
	v_mfma_f32_16x16x32_bf16 v[76:79], v[164:167], v[216:219], v[76:79]
	v_mfma_f32_16x16x32_bf16 v[112:115], v[168:171], v[188:191], v[112:115]
	v_mfma_f32_16x16x32_bf16 v[112:115], v[172:175], v[192:195], v[112:115]
	v_mfma_f32_16x16x32_bf16 v[104:107], v[176:179], v[188:191], v[104:107]
	v_mfma_f32_16x16x32_bf16 v[104:107], v[184:187], v[192:195], v[104:107]
	v_mfma_f32_16x16x32_bf16 v[96:99], v[168:171], v[196:199], v[96:99]
	v_mfma_f32_16x16x32_bf16 v[96:99], v[172:175], v[200:203], v[96:99]
	v_mfma_f32_16x16x32_bf16 v[88:91], v[176:179], v[196:199], v[88:91]
	v_mfma_f32_16x16x32_bf16 v[88:91], v[184:187], v[200:203], v[88:91]
	v_mfma_f32_16x16x32_bf16 v[80:83], v[168:171], v[204:207], v[80:83]
	v_mfma_f32_16x16x32_bf16 v[80:83], v[172:175], v[208:211], v[80:83]
	v_mfma_f32_16x16x32_bf16 v[72:75], v[176:179], v[204:207], v[72:75]
	v_mfma_f32_16x16x32_bf16 v[72:75], v[184:187], v[208:211], v[72:75]
	v_mfma_f32_16x16x32_bf16 v[68:71], v[168:171], v[212:215], v[68:71]
	v_mfma_f32_16x16x32_bf16 v[68:71], v[172:175], v[216:219], v[68:71]
	s_barrier
	v_mfma_f32_16x16x32_bf16 v[64:67], v[176:179], v[212:215], v[64:67]
	v_mfma_f32_16x16x32_bf16 v[64:67], v[184:187], v[216:219], v[64:67]
	s_setprio 0
	s_add_i32 s18, s18, s62
	v_lshl_add_u64 v[144:145], v[144:145], 0, s[8:9]
	s_mov_b32 m0, s18
	ds_read_b128 v[188:191], v151 offset:49152
	ds_read_b128 v[192:195], v151 offset:50176
	ds_read_b128 v[196:199], v151 offset:51200
	ds_read_b128 v[200:203], v151 offset:52224
	ds_read_b128 v[204:207], v151 offset:53248
	ds_read_b128 v[208:211], v151 offset:54272
	ds_read_b128 v[212:215], v151 offset:55296
	ds_read_b128 v[216:219], v151 offset:56320
	global_load_lds_dwordx4 v[144:145], off
	s_add_i32 m0, s18, 0x2000
	s_add_u32 s52, s56, 0xb0080
	v_lshl_add_u64 v[144:145], v[220:221], 0, s[8:9]
	s_addc_u32 s53, s57, 0
	s_add_i32 s18, s19, s62
	global_load_lds_dwordx4 v[144:145], off
	v_lshl_add_u64 v[144:145], s[52:53], 0, v[130:131]
	s_mov_b32 m0, s18
	s_nop 0
	global_load_lds_dwordx4 v[144:145], off
	v_lshl_add_u64 v[144:145], s[52:53], 0, v[134:135]
	s_add_i32 m0, s18, 0x2000
	s_nop 0
	global_load_lds_dwordx4 v[144:145], off
	v_lshl_add_u64 v[144:145], v[222:223], 0, s[8:9]
	s_mov_b32 m0, s68
	s_nop 0
	global_load_lds_dwordx4 v[144:145], off
	v_lshl_add_u64 v[144:145], v[224:225], 0, s[8:9]
	s_mov_b32 m0, s69
	s_nop 0
	global_load_lds_dwordx4 v[144:145], off
	s_waitcnt vmcnt(8)
	s_waitcnt lgkmcnt(0)
	s_barrier
	s_waitcnt lgkmcnt(0)
	v_mfma_f32_16x16x32_bf16 v[60:63], v[152:155], v[188:191], v[60:63]
	v_mfma_f32_16x16x32_bf16 v[60:63], v[156:159], v[192:195], v[60:63]
	s_setprio 1
	v_mfma_f32_16x16x32_bf16 v[56:59], v[160:163], v[188:191], v[56:59]
	v_mfma_f32_16x16x32_bf16 v[56:59], v[164:167], v[192:195], v[56:59]
	v_mfma_f32_16x16x32_bf16 v[52:55], v[152:155], v[196:199], v[52:55]
	v_mfma_f32_16x16x32_bf16 v[52:55], v[156:159], v[200:203], v[52:55]
	v_mfma_f32_16x16x32_bf16 v[44:47], v[160:163], v[196:199], v[44:47]
	v_mfma_f32_16x16x32_bf16 v[44:47], v[164:167], v[200:203], v[44:47]
	v_mfma_f32_16x16x32_bf16 v[36:39], v[152:155], v[204:207], v[36:39]
	v_mfma_f32_16x16x32_bf16 v[36:39], v[156:159], v[208:211], v[36:39]
	v_mfma_f32_16x16x32_bf16 v[28:31], v[160:163], v[204:207], v[28:31]
	v_mfma_f32_16x16x32_bf16 v[28:31], v[164:167], v[208:211], v[28:31]
	v_mfma_f32_16x16x32_bf16 v[20:23], v[152:155], v[212:215], v[20:23]
	v_mfma_f32_16x16x32_bf16 v[20:23], v[156:159], v[216:219], v[20:23]
	v_mfma_f32_16x16x32_bf16 v[12:15], v[160:163], v[212:215], v[12:15]
	v_mfma_f32_16x16x32_bf16 v[12:15], v[164:167], v[216:219], v[12:15]
	v_mfma_f32_16x16x32_bf16 v[48:51], v[168:171], v[188:191], v[48:51]
	v_mfma_f32_16x16x32_bf16 v[48:51], v[172:175], v[192:195], v[48:51]
	v_mfma_f32_16x16x32_bf16 v[40:43], v[176:179], v[188:191], v[40:43]
	v_mfma_f32_16x16x32_bf16 v[40:43], v[184:187], v[192:195], v[40:43]
	v_mfma_f32_16x16x32_bf16 v[32:35], v[168:171], v[196:199], v[32:35]
	v_mfma_f32_16x16x32_bf16 v[32:35], v[172:175], v[200:203], v[32:35]
	v_mfma_f32_16x16x32_bf16 v[24:27], v[176:179], v[196:199], v[24:27]
	v_mfma_f32_16x16x32_bf16 v[24:27], v[184:187], v[200:203], v[24:27]
	v_mfma_f32_16x16x32_bf16 v[16:19], v[168:171], v[204:207], v[16:19]
	v_mfma_f32_16x16x32_bf16 v[16:19], v[172:175], v[208:211], v[16:19]
	v_mfma_f32_16x16x32_bf16 v[8:11], v[176:179], v[204:207], v[8:11]
	v_mfma_f32_16x16x32_bf16 v[8:11], v[184:187], v[208:211], v[8:11]
	v_mfma_f32_16x16x32_bf16 v[4:7], v[168:171], v[212:215], v[4:7]
	v_mfma_f32_16x16x32_bf16 v[4:7], v[172:175], v[216:219], v[4:7]
	s_barrier
	v_mfma_f32_16x16x32_bf16 v[0:3], v[176:179], v[212:215], v[0:3]
	v_mfma_f32_16x16x32_bf16 v[0:3], v[184:187], v[216:219], v[0:3]
	s_setprio 0
	s_add_i32 s86, s86, 2
	s_add_u32 s84, s84, 0x100
	s_addc_u32 s85, s85, 0
	s_cmp_gt_u32 s86, 41
	s_mov_b64 s[52:53], s[54:55]
	s_cbranch_scc0 .LBB0_264

.Lmid_gemm2:
	s_add_i32 s18, 0, 0x18000
	s_add_i32 s19, 0, 0x1c000
	v_add_u32_e32 v164, s18, v147
	v_add_u32_e32 v181, s19, v147
	ds_read_b128 v[152:155], v164
	ds_read_b128 v[156:159], v164 offset:1024
	ds_read_b128 v[160:163], v164 offset:2048
	ds_read_b128 v[164:167], v164 offset:3072
	ds_read_b128 v[168:171], v181
	ds_read_b128 v[172:175], v181 offset:1024
	ds_read_b128 v[176:179], v181 offset:2048
	ds_read_b128 v[184:187], v181 offset:3072
	s_add_u32 s62, s62, 0x40000
	s_addc_u32 s63, s63, 0
	s_mov_b32 m0, s70
	v_lshl_add_u64 v[228:229], s[62:63], 0, v[134:135]
	ds_read_b128 v[188:191], v150 offset:32768
	ds_read_b128 v[192:195], v150 offset:33792
	ds_read_b128 v[196:199], v150 offset:34816
	ds_read_b128 v[200:203], v150 offset:35840
	ds_read_b128 v[204:207], v150 offset:36864
	ds_read_b128 v[208:211], v150 offset:37888
	ds_read_b128 v[212:215], v150 offset:38912
	ds_read_b128 v[216:219], v150 offset:39936
	global_load_lds_dwordx4 v[228:229], off
	v_lshl_add_u64 v[228:229], s[62:63], 0, v[130:131]
	s_mov_b32 m0, s71
	s_nop 0
	global_load_lds_dwordx4 v[228:229], off
	s_waitcnt vmcnt(8)
	s_waitcnt lgkmcnt(0)
	s_barrier
	s_waitcnt lgkmcnt(0)
	v_mfma_f32_16x16x32_bf16 v[124:127], v[152:155], v[188:191], v[124:127]
	v_mfma_f32_16x16x32_bf16 v[124:127], v[156:159], v[192:195], v[124:127]
	s_setprio 1
	v_mfma_f32_16x16x32_bf16 v[120:123], v[160:163], v[188:191], v[120:123]
	v_mfma_f32_16x16x32_bf16 v[120:123], v[164:167], v[192:195], v[120:123]
	v_mfma_f32_16x16x32_bf16 v[116:119], v[152:155], v[196:199], v[116:119]
	v_mfma_f32_16x16x32_bf16 v[116:119], v[156:159], v[200:203], v[116:119]
	v_mfma_f32_16x16x32_bf16 v[112:115], v[160:163], v[196:199], v[112:115]
	v_mfma_f32_16x16x32_bf16 v[112:115], v[164:167], v[200:203], v[112:115]
	v_mfma_f32_16x16x32_bf16 v[108:111], v[152:155], v[204:207], v[108:111]
	v_mfma_f32_16x16x32_bf16 v[108:111], v[156:159], v[208:211], v[108:111]
	v_mfma_f32_16x16x32_bf16 v[104:107], v[160:163], v[204:207], v[104:107]
	v_mfma_f32_16x16x32_bf16 v[104:107], v[164:167], v[208:211], v[104:107]
	v_mfma_f32_16x16x32_bf16 v[100:103], v[152:155], v[212:215], v[100:103]
	v_mfma_f32_16x16x32_bf16 v[100:103], v[156:159], v[216:219], v[100:103]
	v_mfma_f32_16x16x32_bf16 v[96:99], v[160:163], v[212:215], v[96:99]
	v_mfma_f32_16x16x32_bf16 v[96:99], v[164:167], v[216:219], v[96:99]
	v_mfma_f32_16x16x32_bf16 v[68:71], v[168:171], v[188:191], v[68:71]
	v_mfma_f32_16x16x32_bf16 v[68:71], v[172:175], v[192:195], v[68:71]
	v_mfma_f32_16x16x32_bf16 v[64:67], v[176:179], v[188:191], v[64:67]
	v_mfma_f32_16x16x32_bf16 v[64:67], v[184:187], v[192:195], v[64:67]
	v_mfma_f32_16x16x32_bf16 v[52:55], v[168:171], v[196:199], v[52:55]
	v_mfma_f32_16x16x32_bf16 v[52:55], v[172:175], v[200:203], v[52:55]
	v_mfma_f32_16x16x32_bf16 v[48:51], v[176:179], v[196:199], v[48:51]
	v_mfma_f32_16x16x32_bf16 v[48:51], v[184:187], v[200:203], v[48:51]
	v_mfma_f32_16x16x32_bf16 v[44:47], v[168:171], v[204:207], v[44:47]
	v_mfma_f32_16x16x32_bf16 v[44:47], v[172:175], v[208:211], v[44:47]
	v_mfma_f32_16x16x32_bf16 v[40:43], v[176:179], v[204:207], v[40:43]
	v_mfma_f32_16x16x32_bf16 v[40:43], v[184:187], v[208:211], v[40:43]
	v_mfma_f32_16x16x32_bf16 v[36:39], v[168:171], v[212:215], v[36:39]
	v_mfma_f32_16x16x32_bf16 v[36:39], v[172:175], v[216:219], v[36:39]
	s_barrier
	v_mfma_f32_16x16x32_bf16 v[32:35], v[176:179], v[212:215], v[32:35]
	v_mfma_f32_16x16x32_bf16 v[32:35], v[184:187], v[216:219], v[32:35]
	s_setprio 0
	s_add_i32 s18, s18, s66
	v_lshl_add_u64 v[220:221], v[220:221], 0, s[6:7]
	s_mov_b32 m0, s18
	ds_read_b128 v[188:191], v150 offset:49152
	ds_read_b128 v[192:195], v150 offset:50176
	ds_read_b128 v[196:199], v150 offset:51200
	ds_read_b128 v[200:203], v150 offset:52224
	ds_read_b128 v[204:207], v150 offset:53248
	ds_read_b128 v[208:211], v150 offset:54272
	ds_read_b128 v[212:215], v150 offset:55296
	ds_read_b128 v[216:219], v150 offset:56320
	global_load_lds_dwordx4 v[220:221], off
	s_add_i32 m0, s18, 0x2000
	s_add_u32 s60, s60, 0x40080
	v_lshl_add_u64 v[220:221], v[222:223], 0, s[6:7]
	s_addc_u32 s61, s61, 0
	s_add_i32 s18, s19, s66
	global_load_lds_dwordx4 v[220:221], off
	v_lshl_add_u64 v[220:221], s[60:61], 0, v[132:133]
	s_mov_b32 m0, s18
	s_nop 0
	global_load_lds_dwordx4 v[220:221], off
	v_lshl_add_u64 v[220:221], s[60:61], 0, v[128:129]
	s_add_i32 m0, s18, 0x2000
	s_nop 0
	global_load_lds_dwordx4 v[220:221], off
	v_lshl_add_u64 v[220:221], v[224:225], 0, s[6:7]
	s_mov_b32 m0, s74
	s_nop 0
	global_load_lds_dwordx4 v[220:221], off
	v_lshl_add_u64 v[220:221], v[226:227], 0, s[6:7]
	s_mov_b32 m0, s75
	s_nop 0
	global_load_lds_dwordx4 v[220:221], off
	s_waitcnt vmcnt(8)
	s_waitcnt lgkmcnt(0)
	s_barrier
	s_waitcnt lgkmcnt(0)
	v_mfma_f32_16x16x32_bf16 v[92:95], v[152:155], v[188:191], v[92:95]
	v_mfma_f32_16x16x32_bf16 v[92:95], v[156:159], v[192:195], v[92:95]
	s_setprio 1
	v_mfma_f32_16x16x32_bf16 v[88:91], v[160:163], v[188:191], v[88:91]
	v_mfma_f32_16x16x32_bf16 v[88:91], v[164:167], v[192:195], v[88:91]
	v_mfma_f32_16x16x32_bf16 v[84:87], v[152:155], v[196:199], v[84:87]
	v_mfma_f32_16x16x32_bf16 v[84:87], v[156:159], v[200:203], v[84:87]
	v_mfma_f32_16x16x32_bf16 v[80:83], v[160:163], v[196:199], v[80:83]
	v_mfma_f32_16x16x32_bf16 v[80:83], v[164:167], v[200:203], v[80:83]
	v_mfma_f32_16x16x32_bf16 v[76:79], v[152:155], v[204:207], v[76:79]
	v_mfma_f32_16x16x32_bf16 v[76:79], v[156:159], v[208:211], v[76:79]
	v_mfma_f32_16x16x32_bf16 v[72:75], v[160:163], v[204:207], v[72:75]
	v_mfma_f32_16x16x32_bf16 v[72:75], v[164:167], v[208:211], v[72:75]
	v_mfma_f32_16x16x32_bf16 v[60:63], v[152:155], v[212:215], v[60:63]
	v_mfma_f32_16x16x32_bf16 v[60:63], v[156:159], v[216:219], v[60:63]
	v_mfma_f32_16x16x32_bf16 v[56:59], v[160:163], v[212:215], v[56:59]
	v_mfma_f32_16x16x32_bf16 v[56:59], v[164:167], v[216:219], v[56:59]
	v_mfma_f32_16x16x32_bf16 v[28:31], v[168:171], v[188:191], v[28:31]
	v_mfma_f32_16x16x32_bf16 v[28:31], v[172:175], v[192:195], v[28:31]
	v_mfma_f32_16x16x32_bf16 v[24:27], v[176:179], v[188:191], v[24:27]
	v_mfma_f32_16x16x32_bf16 v[24:27], v[184:187], v[192:195], v[24:27]
	v_mfma_f32_16x16x32_bf16 v[20:23], v[168:171], v[196:199], v[20:23]
	v_mfma_f32_16x16x32_bf16 v[20:23], v[172:175], v[200:203], v[20:23]
	v_mfma_f32_16x16x32_bf16 v[16:19], v[176:179], v[196:199], v[16:19]
	v_mfma_f32_16x16x32_bf16 v[16:19], v[184:187], v[200:203], v[16:19]
	v_mfma_f32_16x16x32_bf16 v[12:15], v[168:171], v[204:207], v[12:15]
	v_mfma_f32_16x16x32_bf16 v[12:15], v[172:175], v[208:211], v[12:15]
	v_mfma_f32_16x16x32_bf16 v[8:11], v[176:179], v[204:207], v[8:11]
	v_mfma_f32_16x16x32_bf16 v[8:11], v[184:187], v[208:211], v[8:11]
	v_mfma_f32_16x16x32_bf16 v[4:7], v[168:171], v[212:215], v[4:7]
	v_mfma_f32_16x16x32_bf16 v[4:7], v[172:175], v[216:219], v[4:7]
	s_barrier
	v_mfma_f32_16x16x32_bf16 v[0:3], v[176:179], v[212:215], v[0:3]
	v_mfma_f32_16x16x32_bf16 v[0:3], v[184:187], v[216:219], v[0:3]
	s_setprio 0
	s_add_i32 s86, s86, 2
	s_add_u32 s58, s58, 0x100
	s_addc_u32 s59, s59, 0
	s_add_u32 s84, s84, 0x100
	s_addc_u32 s85, s85, 0
	s_cmp_gt_u32 s86, 13
	s_cbranch_scc0 .LBB0_387

.Lmid_gemm3:
	s_add_i32 s79, 0, 0x18000
	s_add_i32 s89, 0, 0x1c000
	v_add_u32_e32 v164, s79, v147
	v_add_u32_e32 v181, s89, v147
	ds_read_b128 v[152:155], v164
	ds_read_b128 v[156:159], v164 offset:1024
	ds_read_b128 v[160:163], v164 offset:2048
	ds_read_b128 v[164:167], v164 offset:3072
	ds_read_b128 v[168:171], v181
	ds_read_b128 v[172:175], v181 offset:1024
	ds_read_b128 v[176:179], v181 offset:2048
	ds_read_b128 v[184:187], v181 offset:3072
	s_add_u32 s18, s62, 0x40000
	s_addc_u32 s19, s63, 0
	s_mov_b32 m0, s68
	v_lshl_add_u64 v[226:227], s[18:19], 0, v[128:129]
	ds_read_b128 v[188:191], v151 offset:32768
	ds_read_b128 v[192:195], v151 offset:33792
	ds_read_b128 v[196:199], v151 offset:34816
	ds_read_b128 v[200:203], v151 offset:35840
	ds_read_b128 v[204:207], v151 offset:36864
	ds_read_b128 v[208:211], v151 offset:37888
	ds_read_b128 v[212:215], v151 offset:38912
	ds_read_b128 v[216:219], v151 offset:39936
	global_load_lds_dwordx4 v[226:227], off
	v_lshl_add_u64 v[226:227], s[18:19], 0, v[132:133]
	s_mov_b32 m0, s69
	s_nop 0
	global_load_lds_dwordx4 v[226:227], off
	s_waitcnt vmcnt(8)
	s_waitcnt lgkmcnt(0)
	s_barrier
	s_waitcnt lgkmcnt(0)
	v_mfma_f32_16x16x32_bf16 v[124:127], v[152:155], v[188:191], v[124:127]
	v_mfma_f32_16x16x32_bf16 v[124:127], v[156:159], v[192:195], v[124:127]
	s_setprio 1
	v_mfma_f32_16x16x32_bf16 v[120:123], v[160:163], v[188:191], v[120:123]
	v_mfma_f32_16x16x32_bf16 v[120:123], v[164:167], v[192:195], v[120:123]
	v_mfma_f32_16x16x32_bf16 v[116:119], v[152:155], v[196:199], v[116:119]
	v_mfma_f32_16x16x32_bf16 v[116:119], v[156:159], v[200:203], v[116:119]
	v_mfma_f32_16x16x32_bf16 v[108:111], v[160:163], v[196:199], v[108:111]
	v_mfma_f32_16x16x32_bf16 v[108:111], v[164:167], v[200:203], v[108:111]
	v_mfma_f32_16x16x32_bf16 v[100:103], v[152:155], v[204:207], v[100:103]
	v_mfma_f32_16x16x32_bf16 v[100:103], v[156:159], v[208:211], v[100:103]
	v_mfma_f32_16x16x32_bf16 v[92:95], v[160:163], v[204:207], v[92:95]
	v_mfma_f32_16x16x32_bf16 v[92:95], v[164:167], v[208:211], v[92:95]
	v_mfma_f32_16x16x32_bf16 v[84:87], v[152:155], v[212:215], v[84:87]
	v_mfma_f32_16x16x32_bf16 v[84:87], v[156:159], v[216:219], v[84:87]
	v_mfma_f32_16x16x32_bf16 v[76:79], v[160:163], v[212:215], v[76:79]
	v_mfma_f32_16x16x32_bf16 v[76:79], v[164:167], v[216:219], v[76:79]
	v_mfma_f32_16x16x32_bf16 v[112:115], v[168:171], v[188:191], v[112:115]
	v_mfma_f32_16x16x32_bf16 v[112:115], v[172:175], v[192:195], v[112:115]
	v_mfma_f32_16x16x32_bf16 v[104:107], v[176:179], v[188:191], v[104:107]
	v_mfma_f32_16x16x32_bf16 v[104:107], v[184:187], v[192:195], v[104:107]
	v_mfma_f32_16x16x32_bf16 v[96:99], v[168:171], v[196:199], v[96:99]
	v_mfma_f32_16x16x32_bf16 v[96:99], v[172:175], v[200:203], v[96:99]
	v_mfma_f32_16x16x32_bf16 v[88:91], v[176:179], v[196:199], v[88:91]
	v_mfma_f32_16x16x32_bf16 v[88:91], v[184:187], v[200:203], v[88:91]
	v_mfma_f32_16x16x32_bf16 v[80:83], v[168:171], v[204:207], v[80:83]
	v_mfma_f32_16x16x32_bf16 v[80:83], v[172:175], v[208:211], v[80:83]
	v_mfma_f32_16x16x32_bf16 v[72:75], v[176:179], v[204:207], v[72:75]
	v_mfma_f32_16x16x32_bf16 v[72:75], v[184:187], v[208:211], v[72:75]
	v_mfma_f32_16x16x32_bf16 v[68:71], v[168:171], v[212:215], v[68:71]
	v_mfma_f32_16x16x32_bf16 v[68:71], v[172:175], v[216:219], v[68:71]
	s_barrier
	v_mfma_f32_16x16x32_bf16 v[64:67], v[176:179], v[212:215], v[64:67]
	v_mfma_f32_16x16x32_bf16 v[64:67], v[184:187], v[216:219], v[64:67]
	s_setprio 0
	s_add_i32 s18, s79, s66
	v_lshl_add_u64 v[144:145], v[144:145], 0, s[10:11]
	s_mov_b32 m0, s18
	ds_read_b128 v[188:191], v151 offset:49152
	ds_read_b128 v[192:195], v151 offset:50176
	ds_read_b128 v[196:199], v151 offset:51200
	ds_read_b128 v[200:203], v151 offset:52224
	ds_read_b128 v[204:207], v151 offset:53248
	ds_read_b128 v[208:211], v151 offset:54272
	ds_read_b128 v[212:215], v151 offset:55296
	ds_read_b128 v[216:219], v151 offset:56320
	global_load_lds_dwordx4 v[144:145], off
	s_add_i32 m0, s18, 0x2000
	s_add_u32 s18, s60, 0x40080
	v_lshl_add_u64 v[144:145], v[220:221], 0, s[10:11]
	s_addc_u32 s19, s61, 0
	s_add_i32 s60, s89, s66
	global_load_lds_dwordx4 v[144:145], off
	v_lshl_add_u64 v[144:145], s[18:19], 0, v[130:131]
	s_mov_b32 m0, s60
	s_nop 0
	global_load_lds_dwordx4 v[144:145], off
	v_lshl_add_u64 v[144:145], s[18:19], 0, v[134:135]
	s_add_i32 m0, s60, 0x2000
	s_nop 0
	global_load_lds_dwordx4 v[144:145], off
	v_lshl_add_u64 v[144:145], v[222:223], 0, s[10:11]
	s_mov_b32 m0, s71
	s_nop 0
	global_load_lds_dwordx4 v[144:145], off
	v_lshl_add_u64 v[144:145], v[224:225], 0, s[10:11]
	s_mov_b32 m0, s72
	s_nop 0
	global_load_lds_dwordx4 v[144:145], off
	s_waitcnt vmcnt(8)
	s_waitcnt lgkmcnt(0)
	s_barrier
	s_waitcnt lgkmcnt(0)
	v_mfma_f32_16x16x32_bf16 v[60:63], v[152:155], v[188:191], v[60:63]
	v_mfma_f32_16x16x32_bf16 v[60:63], v[156:159], v[192:195], v[60:63]
	s_setprio 1
	v_mfma_f32_16x16x32_bf16 v[56:59], v[160:163], v[188:191], v[56:59]
	v_mfma_f32_16x16x32_bf16 v[56:59], v[164:167], v[192:195], v[56:59]
	v_mfma_f32_16x16x32_bf16 v[52:55], v[152:155], v[196:199], v[52:55]
	v_mfma_f32_16x16x32_bf16 v[52:55], v[156:159], v[200:203], v[52:55]
	v_mfma_f32_16x16x32_bf16 v[44:47], v[160:163], v[196:199], v[44:47]
	v_mfma_f32_16x16x32_bf16 v[44:47], v[164:167], v[200:203], v[44:47]
	v_mfma_f32_16x16x32_bf16 v[36:39], v[152:155], v[204:207], v[36:39]
	v_mfma_f32_16x16x32_bf16 v[36:39], v[156:159], v[208:211], v[36:39]
	v_mfma_f32_16x16x32_bf16 v[28:31], v[160:163], v[204:207], v[28:31]
	v_mfma_f32_16x16x32_bf16 v[28:31], v[164:167], v[208:211], v[28:31]
	v_mfma_f32_16x16x32_bf16 v[20:23], v[152:155], v[212:215], v[20:23]
	v_mfma_f32_16x16x32_bf16 v[20:23], v[156:159], v[216:219], v[20:23]
	v_mfma_f32_16x16x32_bf16 v[12:15], v[160:163], v[212:215], v[12:15]
	v_mfma_f32_16x16x32_bf16 v[12:15], v[164:167], v[216:219], v[12:15]
	v_mfma_f32_16x16x32_bf16 v[48:51], v[168:171], v[188:191], v[48:51]
	v_mfma_f32_16x16x32_bf16 v[48:51], v[172:175], v[192:195], v[48:51]
	v_mfma_f32_16x16x32_bf16 v[40:43], v[176:179], v[188:191], v[40:43]
	v_mfma_f32_16x16x32_bf16 v[40:43], v[184:187], v[192:195], v[40:43]
	v_mfma_f32_16x16x32_bf16 v[32:35], v[168:171], v[196:199], v[32:35]
	v_mfma_f32_16x16x32_bf16 v[32:35], v[172:175], v[200:203], v[32:35]
	v_mfma_f32_16x16x32_bf16 v[24:27], v[176:179], v[196:199], v[24:27]
	v_mfma_f32_16x16x32_bf16 v[24:27], v[184:187], v[200:203], v[24:27]
	v_mfma_f32_16x16x32_bf16 v[16:19], v[168:171], v[204:207], v[16:19]
	v_mfma_f32_16x16x32_bf16 v[16:19], v[172:175], v[208:211], v[16:19]
	v_mfma_f32_16x16x32_bf16 v[8:11], v[176:179], v[204:207], v[8:11]
	v_mfma_f32_16x16x32_bf16 v[8:11], v[184:187], v[208:211], v[8:11]
	v_mfma_f32_16x16x32_bf16 v[4:7], v[168:171], v[212:215], v[4:7]
	v_mfma_f32_16x16x32_bf16 v[4:7], v[172:175], v[216:219], v[4:7]
	s_barrier
	v_mfma_f32_16x16x32_bf16 v[0:3], v[176:179], v[212:215], v[0:3]
	v_mfma_f32_16x16x32_bf16 v[0:3], v[184:187], v[216:219], v[0:3]
	s_setprio 0
	s_add_i32 s88, s88, 2
	s_add_u32 s58, s58, 0x100
	s_addc_u32 s59, s59, 0
	s_add_u32 s86, s86, 0x100
	s_addc_u32 s87, s87, 0
	s_cmp_gt_u32 s88, 13
	s_cbranch_scc0 .LBB0_601

.Lmid_gemm4:
	s_add_i32 s75, 0, 0x18000
	s_add_i32 s76, 0, 0x1c000
	v_add_u32_e32 v158, s75, v145
	v_add_u32_e32 v174, s76, v145
	ds_read_b128 v[140:143], v158
	ds_read_b128 v[150:153], v158 offset:1024
	ds_read_b128 v[154:157], v158 offset:2048
	ds_read_b128 v[158:161], v158 offset:3072
	ds_read_b128 v[162:165], v174
	ds_read_b128 v[166:169], v174 offset:1024
	ds_read_b128 v[170:173], v174 offset:2048
	ds_read_b128 v[174:177], v174 offset:3072
	s_add_u32 s54, s54, 0x40000
	s_addc_u32 s55, s55, 0
	s_mov_b32 m0, s61
	v_lshl_add_u64 v[222:223], s[54:55], 0, v[130:131]
	ds_read_b128 v[184:187], v149 offset:32768
	ds_read_b128 v[188:191], v149 offset:33792
	ds_read_b128 v[192:195], v149 offset:34816
	ds_read_b128 v[196:199], v149 offset:35840
	ds_read_b128 v[200:203], v149 offset:36864
	ds_read_b128 v[204:207], v149 offset:37888
	ds_read_b128 v[208:211], v149 offset:38912
	ds_read_b128 v[212:215], v149 offset:39936
	global_load_lds_dwordx4 v[222:223], off
	v_lshl_add_u64 v[222:223], s[54:55], 0, v[128:129]
	s_mov_b32 m0, s62
	s_nop 0
	global_load_lds_dwordx4 v[222:223], off
	s_waitcnt vmcnt(8)
	s_waitcnt lgkmcnt(0)
	s_barrier
	s_waitcnt lgkmcnt(0)
	v_mfma_f32_16x16x32_bf16 v[124:127], v[140:143], v[184:187], v[124:127]
	v_mfma_f32_16x16x32_bf16 v[124:127], v[150:153], v[188:191], v[124:127]
	s_setprio 1
	v_mfma_f32_16x16x32_bf16 v[120:123], v[154:157], v[184:187], v[120:123]
	v_mfma_f32_16x16x32_bf16 v[120:123], v[158:161], v[188:191], v[120:123]
	v_mfma_f32_16x16x32_bf16 v[108:111], v[140:143], v[192:195], v[108:111]
	v_mfma_f32_16x16x32_bf16 v[108:111], v[150:153], v[196:199], v[108:111]
	v_mfma_f32_16x16x32_bf16 v[104:107], v[154:157], v[192:195], v[104:107]
	v_mfma_f32_16x16x32_bf16 v[104:107], v[158:161], v[196:199], v[104:107]
	v_mfma_f32_16x16x32_bf16 v[92:95], v[140:143], v[200:203], v[92:95]
	v_mfma_f32_16x16x32_bf16 v[92:95], v[150:153], v[204:207], v[92:95]
	v_mfma_f32_16x16x32_bf16 v[88:91], v[154:157], v[200:203], v[88:91]
	v_mfma_f32_16x16x32_bf16 v[88:91], v[158:161], v[204:207], v[88:91]
	v_mfma_f32_16x16x32_bf16 v[76:79], v[140:143], v[208:211], v[76:79]
	v_mfma_f32_16x16x32_bf16 v[76:79], v[150:153], v[212:215], v[76:79]
	v_mfma_f32_16x16x32_bf16 v[72:75], v[154:157], v[208:211], v[72:75]
	v_mfma_f32_16x16x32_bf16 v[72:75], v[158:161], v[212:215], v[72:75]
	v_mfma_f32_16x16x32_bf16 v[116:119], v[162:165], v[184:187], v[116:119]
	v_mfma_f32_16x16x32_bf16 v[116:119], v[166:169], v[188:191], v[116:119]
	v_mfma_f32_16x16x32_bf16 v[112:115], v[170:173], v[184:187], v[112:115]
	v_mfma_f32_16x16x32_bf16 v[112:115], v[174:177], v[188:191], v[112:115]
	v_mfma_f32_16x16x32_bf16 v[100:103], v[162:165], v[192:195], v[100:103]
	v_mfma_f32_16x16x32_bf16 v[100:103], v[166:169], v[196:199], v[100:103]
	v_mfma_f32_16x16x32_bf16 v[96:99], v[170:173], v[192:195], v[96:99]
	v_mfma_f32_16x16x32_bf16 v[96:99], v[174:177], v[196:199], v[96:99]
	v_mfma_f32_16x16x32_bf16 v[84:87], v[162:165], v[200:203], v[84:87]
	v_mfma_f32_16x16x32_bf16 v[84:87], v[166:169], v[204:207], v[84:87]
	v_mfma_f32_16x16x32_bf16 v[80:83], v[170:173], v[200:203], v[80:83]
	v_mfma_f32_16x16x32_bf16 v[80:83], v[174:177], v[204:207], v[80:83]
	v_mfma_f32_16x16x32_bf16 v[68:71], v[162:165], v[208:211], v[68:71]
	v_mfma_f32_16x16x32_bf16 v[68:71], v[166:169], v[212:215], v[68:71]
	s_barrier
	v_mfma_f32_16x16x32_bf16 v[64:67], v[170:173], v[208:211], v[64:67]
	v_mfma_f32_16x16x32_bf16 v[64:67], v[174:177], v[212:215], v[64:67]
	s_setprio 0
	s_add_i32 s54, s75, s58
	v_lshl_add_u64 v[178:179], v[178:179], 0, s[12:13]
	s_mov_b32 m0, s54
	ds_read_b128 v[184:187], v149 offset:49152
	ds_read_b128 v[188:191], v149 offset:50176
	ds_read_b128 v[192:195], v149 offset:51200
	ds_read_b128 v[196:199], v149 offset:52224
	ds_read_b128 v[200:203], v149 offset:53248
	ds_read_b128 v[204:207], v149 offset:54272
	ds_read_b128 v[208:211], v149 offset:55296
	ds_read_b128 v[212:215], v149 offset:56320
	global_load_lds_dwordx4 v[178:179], off
	s_add_i32 m0, s54, 0x2000
	s_add_u32 s52, s52, 0x40080
	v_lshl_add_u64 v[178:179], v[216:217], 0, s[12:13]
	s_addc_u32 s53, s53, 0
	s_add_i32 s54, s76, s58
	global_load_lds_dwordx4 v[178:179], off
	v_lshl_add_u64 v[178:179], s[52:53], 0, v[130:131]
	s_mov_b32 m0, s54
	s_nop 0
	global_load_lds_dwordx4 v[178:179], off
	v_lshl_add_u64 v[178:179], s[52:53], 0, v[128:129]
	s_add_i32 m0, s54, 0x2000
	s_nop 0
	global_load_lds_dwordx4 v[178:179], off
	v_lshl_add_u64 v[178:179], v[218:219], 0, s[12:13]
	s_mov_b32 m0, s64
	s_nop 0
	global_load_lds_dwordx4 v[178:179], off
	v_lshl_add_u64 v[178:179], v[220:221], 0, s[12:13]
	s_mov_b32 m0, s65
	s_nop 0
	global_load_lds_dwordx4 v[178:179], off
	s_waitcnt vmcnt(8)
	s_waitcnt lgkmcnt(0)
	s_barrier
	s_waitcnt lgkmcnt(0)
	v_mfma_f32_16x16x32_bf16 v[60:63], v[140:143], v[184:187], v[60:63]
	v_mfma_f32_16x16x32_bf16 v[60:63], v[150:153], v[188:191], v[60:63]
	s_setprio 1
	v_mfma_f32_16x16x32_bf16 v[56:59], v[154:157], v[184:187], v[56:59]
	v_mfma_f32_16x16x32_bf16 v[56:59], v[158:161], v[188:191], v[56:59]
	v_mfma_f32_16x16x32_bf16 v[44:47], v[140:143], v[192:195], v[44:47]
	v_mfma_f32_16x16x32_bf16 v[44:47], v[150:153], v[196:199], v[44:47]
	v_mfma_f32_16x16x32_bf16 v[40:43], v[154:157], v[192:195], v[40:43]
	v_mfma_f32_16x16x32_bf16 v[40:43], v[158:161], v[196:199], v[40:43]
	v_mfma_f32_16x16x32_bf16 v[28:31], v[140:143], v[200:203], v[28:31]
	v_mfma_f32_16x16x32_bf16 v[28:31], v[150:153], v[204:207], v[28:31]
	v_mfma_f32_16x16x32_bf16 v[24:27], v[154:157], v[200:203], v[24:27]
	v_mfma_f32_16x16x32_bf16 v[24:27], v[158:161], v[204:207], v[24:27]
	v_mfma_f32_16x16x32_bf16 v[12:15], v[140:143], v[208:211], v[12:15]
	v_mfma_f32_16x16x32_bf16 v[12:15], v[150:153], v[212:215], v[12:15]
	v_mfma_f32_16x16x32_bf16 v[8:11], v[154:157], v[208:211], v[8:11]
	v_mfma_f32_16x16x32_bf16 v[8:11], v[158:161], v[212:215], v[8:11]
	v_mfma_f32_16x16x32_bf16 v[52:55], v[162:165], v[184:187], v[52:55]
	v_mfma_f32_16x16x32_bf16 v[52:55], v[166:169], v[188:191], v[52:55]
	v_mfma_f32_16x16x32_bf16 v[48:51], v[170:173], v[184:187], v[48:51]
	v_mfma_f32_16x16x32_bf16 v[48:51], v[174:177], v[188:191], v[48:51]
	v_mfma_f32_16x16x32_bf16 v[36:39], v[162:165], v[192:195], v[36:39]
	v_mfma_f32_16x16x32_bf16 v[36:39], v[166:169], v[196:199], v[36:39]
	v_mfma_f32_16x16x32_bf16 v[32:35], v[170:173], v[192:195], v[32:35]
	v_mfma_f32_16x16x32_bf16 v[32:35], v[174:177], v[196:199], v[32:35]
	v_mfma_f32_16x16x32_bf16 v[20:23], v[162:165], v[200:203], v[20:23]
	v_mfma_f32_16x16x32_bf16 v[20:23], v[166:169], v[204:207], v[20:23]
	v_mfma_f32_16x16x32_bf16 v[16:19], v[170:173], v[200:203], v[16:19]
	v_mfma_f32_16x16x32_bf16 v[16:19], v[174:177], v[204:207], v[16:19]
	v_mfma_f32_16x16x32_bf16 v[4:7], v[162:165], v[208:211], v[4:7]
	v_mfma_f32_16x16x32_bf16 v[4:7], v[166:169], v[212:215], v[4:7]
	s_barrier
	v_mfma_f32_16x16x32_bf16 v[0:3], v[170:173], v[208:211], v[0:3]
	v_mfma_f32_16x16x32_bf16 v[0:3], v[174:177], v[212:215], v[0:3]
	s_setprio 0
	s_add_i32 s74, s74, 2
	s_add_u32 s48, s48, 0x100
	s_addc_u32 s49, s49, 0
	s_add_u32 s72, s72, 0x100
	s_addc_u32 s73, s73, 0
	s_cmp_gt_u32 s74, 13
	s_cbranch_scc0 .LBB0_724
.LBB0_727:
	s_mov_b64 s[98:99], 0x16000
	s_mov_b64 s[100:101], 0x6e000
	v_mul_f32_e32 v151, 0xbfb8aa3b, v124
	v_exp_f32_e32 v151, v151
	v_mul_f32_e32 v154, 0xbfb8aa3b, v125
	v_exp_f32_e32 v154, v154
	v_lshl_or_b32 v142, s69, 7, v146
	v_add_f32_e32 v151, 1.0, v151
	v_rcp_f32_e32 v151, v151
	v_lshl_add_u32 v150, s46, 8, v144
	v_ashrrev_i32_e32 v143, 31, v142
	v_mov_b64_e32 v[140:141], s[22:23]
	v_mul_f32_e32 v124, v124, v151
	v_mul_f32_e32 v120, v120, v124
	v_add_f32_e32 v124, 1.0, v154
	v_mul_f32_e32 v151, 0xbfb8aa3b, v126
	v_rcp_f32_e32 v124, v124
	v_exp_f32_e32 v151, v151
	v_mul_f32_e32 v154, 0xbfb8aa3b, v127
	v_exp_f32_e32 v154, v154
	v_mul_f32_e32 v124, v125, v124
	v_add_f32_e32 v125, 1.0, v151
	v_rcp_f32_e32 v125, v125
	v_add_f32_e32 v151, 1.0, v154
	v_rcp_f32_e32 v151, v151
	v_mul_f32_e32 v121, v121, v124
	v_mul_f32_e32 v124, v126, v125
	v_mul_f32_e32 v125, 0xbfb8aa3b, v116
	v_exp_f32_e32 v125, v125
	v_mul_f32_e32 v122, v122, v124
	v_mul_f32_e32 v124, v127, v151
	v_mul_f32_e32 v123, v123, v124
	v_cvt_pk_bf16_f32 v120, v120, v121
	v_cvt_pk_bf16_f32 v121, v122, v123
	v_add_f32_e32 v122, 1.0, v125
	v_rcp_f32_e32 v122, v122
	v_mul_f32_e32 v123, 0xbfb8aa3b, v117
	v_exp_f32_e32 v123, v123
	v_mad_i64_i32 v[152:153], s[48:49], v150, s68, v[140:141]
	v_lshlrev_b64 v[142:143], 1, v[142:143]
	v_lshl_add_u64 v[152:153], v[152:153], 0, v[142:143]
	v_mul_f32_e32 v116, v116, v122
	global_store_dwordx2 v[152:153], v[120:121], off
	v_mul_f32_e32 v112, v112, v116
	v_add_f32_e32 v116, 1.0, v123
	v_mul_f32_e32 v120, 0xbfb8aa3b, v118
	v_rcp_f32_e32 v116, v116
	v_exp_f32_e32 v120, v120
	v_mul_f32_e32 v121, 0xbfb8aa3b, v119
	v_exp_f32_e32 v121, v121
	v_mul_f32_e32 v116, v117, v116
	v_add_f32_e32 v117, 1.0, v120
	v_rcp_f32_e32 v117, v117
	v_add_f32_e32 v120, 1.0, v121
	v_rcp_f32_e32 v120, v120
	v_mul_f32_e32 v113, v113, v116
	v_mul_f32_e32 v116, v118, v117
	v_mul_f32_e32 v114, v114, v116
	v_mul_f32_e32 v116, v119, v120
	v_cvt_pk_bf16_f32 v112, v112, v113
	v_mul_f32_e32 v115, v115, v116
	v_cvt_pk_bf16_f32 v113, v114, v115
	global_store_dwordx2 v[152:153], v[112:113], off offset:128
	v_mul_f32_e32 v112, 0xbfb8aa3b, v108
	v_exp_f32_e32 v114, v112
	v_mul_f32_e32 v115, 0xbfb8aa3b, v109
	s_and_b64 vcc, exec, s[16:17]
	s_cbranch_vccz .Lxb_4
	s_barrier
.Lxb_4:
	v_exp_f32_e32 v115, v115
	v_add_f32_e32 v114, 1.0, v114
	v_rcp_f32_e32 v114, v114
	v_lshl_add_u64 v[112:113], v[152:153], 0, s[98:99]
	v_mul_f32_e32 v108, v108, v114
	v_mul_f32_e32 v104, v104, v108
	v_add_f32_e32 v108, 1.0, v115
	v_mul_f32_e32 v114, 0xbfb8aa3b, v110
	v_rcp_f32_e32 v108, v108
	v_exp_f32_e32 v114, v114
	v_mul_f32_e32 v115, 0xbfb8aa3b, v111
	v_exp_f32_e32 v115, v115
	v_mul_f32_e32 v108, v109, v108
	v_add_f32_e32 v109, 1.0, v114
	v_rcp_f32_e32 v109, v109
	v_add_f32_e32 v114, 1.0, v115
	v_rcp_f32_e32 v114, v114
	v_mul_f32_e32 v105, v105, v108
	v_mul_f32_e32 v108, v110, v109
	v_mul_f32_e32 v109, 0xbfb8aa3b, v100
	v_exp_f32_e32 v109, v109
	v_mul_f32_e32 v106, v106, v108
	v_mul_f32_e32 v108, v111, v114
	v_mul_f32_e32 v107, v107, v108
	v_cvt_pk_bf16_f32 v104, v104, v105
	v_cvt_pk_bf16_f32 v105, v106, v107
	v_add_f32_e32 v106, 1.0, v109
	v_rcp_f32_e32 v106, v106
	v_mul_f32_e32 v107, 0xbfb8aa3b, v101
	v_exp_f32_e32 v107, v107
	global_store_dwordx2 v[112:113], v[104:105], off
	v_mul_f32_e32 v100, v100, v106
	v_mul_f32_e32 v96, v96, v100
	v_add_f32_e32 v100, 1.0, v107
	v_mul_f32_e32 v104, 0xbfb8aa3b, v102
	v_rcp_f32_e32 v100, v100
	v_exp_f32_e32 v104, v104
	v_mul_f32_e32 v105, 0xbfb8aa3b, v103
	v_exp_f32_e32 v105, v105
	v_mul_f32_e32 v100, v101, v100
	v_add_f32_e32 v101, 1.0, v104
	v_rcp_f32_e32 v101, v101
	v_add_f32_e32 v104, 1.0, v105
	v_rcp_f32_e32 v104, v104
	v_mul_f32_e32 v97, v97, v100
	v_mul_f32_e32 v100, v102, v101
	v_mul_f32_e32 v98, v98, v100
	v_mul_f32_e32 v100, v103, v104
	v_cvt_pk_bf16_f32 v96, v96, v97
	v_mul_f32_e32 v99, v99, v100
	v_cvt_pk_bf16_f32 v97, v98, v99
	global_store_dwordx2 v[112:113], v[96:97], off offset:128
	v_mul_f32_e32 v96, 0xbfb8aa3b, v92
	v_exp_f32_e32 v98, v96
	v_mul_f32_e32 v99, 0xbfb8aa3b, v93
	v_exp_f32_e32 v99, v99
	v_add_f32_e32 v98, 1.0, v98
	v_rcp_f32_e32 v98, v98
	v_lshl_add_u64 v[96:97], v[112:113], 0, s[98:99]
	v_mul_f32_e32 v92, v92, v98
	v_mul_f32_e32 v88, v88, v92
	v_add_f32_e32 v92, 1.0, v99
	v_mul_f32_e32 v98, 0xbfb8aa3b, v94
	v_rcp_f32_e32 v92, v92
	v_exp_f32_e32 v98, v98
	v_mul_f32_e32 v99, 0xbfb8aa3b, v95
	v_exp_f32_e32 v99, v99
	v_mul_f32_e32 v92, v93, v92
	v_add_f32_e32 v93, 1.0, v98
	v_rcp_f32_e32 v93, v93
	v_add_f32_e32 v98, 1.0, v99
	v_rcp_f32_e32 v98, v98
	v_mul_f32_e32 v89, v89, v92
	v_mul_f32_e32 v92, v94, v93
	v_mul_f32_e32 v93, 0xbfb8aa3b, v84
	v_exp_f32_e32 v93, v93
	v_mul_f32_e32 v90, v90, v92
	v_mul_f32_e32 v92, v95, v98
	v_mul_f32_e32 v91, v91, v92
	v_cvt_pk_bf16_f32 v88, v88, v89
	v_cvt_pk_bf16_f32 v89, v90, v91
	v_add_f32_e32 v90, 1.0, v93
	v_rcp_f32_e32 v90, v90
	v_mul_f32_e32 v91, 0xbfb8aa3b, v85
	v_exp_f32_e32 v91, v91
	global_store_dwordx2 v[96:97], v[88:89], off
	v_mul_f32_e32 v84, v84, v90
	v_mul_f32_e32 v80, v80, v84
	v_add_f32_e32 v84, 1.0, v91
	v_mul_f32_e32 v88, 0xbfb8aa3b, v86
	v_rcp_f32_e32 v84, v84
	v_exp_f32_e32 v88, v88
	v_mul_f32_e32 v89, 0xbfb8aa3b, v87
	v_exp_f32_e32 v89, v89
	v_mul_f32_e32 v84, v85, v84
	v_add_f32_e32 v85, 1.0, v88
	v_rcp_f32_e32 v85, v85
	v_add_f32_e32 v88, 1.0, v89
	v_rcp_f32_e32 v88, v88
	v_mul_f32_e32 v81, v81, v84
	v_mul_f32_e32 v84, v86, v85
	v_mul_f32_e32 v82, v82, v84
	v_mul_f32_e32 v84, v87, v88
	v_cvt_pk_bf16_f32 v80, v80, v81
	v_mul_f32_e32 v83, v83, v84
	v_cvt_pk_bf16_f32 v81, v82, v83
	global_store_dwordx2 v[96:97], v[80:81], off offset:128
	v_mul_f32_e32 v80, 0xbfb8aa3b, v76
	v_exp_f32_e32 v82, v80
	v_mul_f32_e32 v83, 0xbfb8aa3b, v77
	v_exp_f32_e32 v83, v83
	v_add_f32_e32 v82, 1.0, v82
	v_rcp_f32_e32 v82, v82
	v_lshl_add_u64 v[80:81], v[96:97], 0, s[98:99]
	v_mul_f32_e32 v76, v76, v82
	v_mul_f32_e32 v72, v72, v76
	v_add_f32_e32 v76, 1.0, v83
	v_mul_f32_e32 v82, 0xbfb8aa3b, v78
	v_rcp_f32_e32 v76, v76
	v_exp_f32_e32 v82, v82
	v_mul_f32_e32 v83, 0xbfb8aa3b, v79
	v_exp_f32_e32 v83, v83
	v_mul_f32_e32 v76, v77, v76
	v_add_f32_e32 v77, 1.0, v82
	v_rcp_f32_e32 v77, v77
	v_add_f32_e32 v82, 1.0, v83
	v_rcp_f32_e32 v82, v82
	v_mul_f32_e32 v73, v73, v76
	v_mul_f32_e32 v76, v78, v77
	v_mul_f32_e32 v77, 0xbfb8aa3b, v68
	v_exp_f32_e32 v77, v77
	v_mul_f32_e32 v74, v74, v76
	v_mul_f32_e32 v76, v79, v82
	v_mul_f32_e32 v75, v75, v76
	v_cvt_pk_bf16_f32 v72, v72, v73
	v_cvt_pk_bf16_f32 v73, v74, v75
	v_add_f32_e32 v74, 1.0, v77
	v_rcp_f32_e32 v74, v74
	v_mul_f32_e32 v75, 0xbfb8aa3b, v69
	v_exp_f32_e32 v75, v75
	global_store_dwordx2 v[80:81], v[72:73], off
	v_mul_f32_e32 v68, v68, v74
	v_mul_f32_e32 v64, v64, v68
	v_add_f32_e32 v68, 1.0, v75
	v_mul_f32_e32 v72, 0xbfb8aa3b, v70
	v_rcp_f32_e32 v68, v68
	v_exp_f32_e32 v72, v72
	v_mul_f32_e32 v73, 0xbfb8aa3b, v71
	v_exp_f32_e32 v73, v73
	v_mul_f32_e32 v68, v69, v68
	v_add_f32_e32 v69, 1.0, v72
	v_rcp_f32_e32 v69, v69
	v_add_f32_e32 v72, 1.0, v73
	v_rcp_f32_e32 v72, v72
	v_mul_f32_e32 v65, v65, v68
	v_mul_f32_e32 v68, v70, v69
	v_mul_f32_e32 v66, v66, v68
	v_mul_f32_e32 v68, v71, v72
	v_cvt_pk_bf16_f32 v64, v64, v65
	v_mul_f32_e32 v67, v67, v68
	v_cvt_pk_bf16_f32 v65, v66, v67
	global_store_dwordx2 v[80:81], v[64:65], off offset:128
	v_mul_f32_e32 v64, 0xbfb8aa3b, v60
	v_exp_f32_e32 v66, v64
	v_mul_f32_e32 v67, 0xbfb8aa3b, v61
	v_exp_f32_e32 v67, v67
	v_add_f32_e32 v66, 1.0, v66
	v_rcp_f32_e32 v66, v66
	v_lshl_add_u64 v[64:65], v[80:81], 0, s[100:101]
	v_mul_f32_e32 v60, v60, v66
	v_mul_f32_e32 v56, v56, v60
	v_add_f32_e32 v60, 1.0, v67
	v_mul_f32_e32 v66, 0xbfb8aa3b, v62
	v_rcp_f32_e32 v60, v60
	v_exp_f32_e32 v66, v66
	v_mul_f32_e32 v67, 0xbfb8aa3b, v63
	v_exp_f32_e32 v67, v67
	v_mul_f32_e32 v60, v61, v60
	v_add_f32_e32 v61, 1.0, v66
	v_rcp_f32_e32 v61, v61
	v_add_f32_e32 v66, 1.0, v67
	v_rcp_f32_e32 v66, v66
	v_mul_f32_e32 v57, v57, v60
	v_mul_f32_e32 v60, v62, v61
	v_mul_f32_e32 v61, 0xbfb8aa3b, v52
	v_exp_f32_e32 v61, v61
	v_mul_f32_e32 v58, v58, v60
	v_mul_f32_e32 v60, v63, v66
	v_mul_f32_e32 v59, v59, v60
	v_cvt_pk_bf16_f32 v56, v56, v57
	v_cvt_pk_bf16_f32 v57, v58, v59
	v_add_f32_e32 v58, 1.0, v61
	v_rcp_f32_e32 v58, v58
	v_mul_f32_e32 v59, 0xbfb8aa3b, v53
	v_exp_f32_e32 v59, v59
	global_store_dwordx2 v[64:65], v[56:57], off
	v_mul_f32_e32 v52, v52, v58
	v_mul_f32_e32 v48, v48, v52
	v_add_f32_e32 v52, 1.0, v59
	v_mul_f32_e32 v56, 0xbfb8aa3b, v54
	v_rcp_f32_e32 v52, v52
	v_exp_f32_e32 v56, v56
	v_mul_f32_e32 v57, 0xbfb8aa3b, v55
	v_exp_f32_e32 v57, v57
	v_mul_f32_e32 v52, v53, v52
	v_add_f32_e32 v53, 1.0, v56
	v_rcp_f32_e32 v53, v53
	v_add_f32_e32 v56, 1.0, v57
	v_rcp_f32_e32 v56, v56
	v_mul_f32_e32 v49, v49, v52
	v_mul_f32_e32 v52, v54, v53
	v_mul_f32_e32 v50, v50, v52
	v_mul_f32_e32 v52, v55, v56
	v_cvt_pk_bf16_f32 v48, v48, v49
	v_mul_f32_e32 v51, v51, v52
	v_cvt_pk_bf16_f32 v49, v50, v51
	global_store_dwordx2 v[64:65], v[48:49], off offset:128
	v_mul_f32_e32 v48, 0xbfb8aa3b, v44
	v_exp_f32_e32 v50, v48
	v_mul_f32_e32 v51, 0xbfb8aa3b, v45
	v_exp_f32_e32 v51, v51
	v_add_f32_e32 v50, 1.0, v50
	v_rcp_f32_e32 v50, v50
	v_lshl_add_u64 v[48:49], v[64:65], 0, s[98:99]
	v_mul_f32_e32 v44, v44, v50
	v_mul_f32_e32 v40, v40, v44
	v_add_f32_e32 v44, 1.0, v51
	v_mul_f32_e32 v50, 0xbfb8aa3b, v46
	v_rcp_f32_e32 v44, v44
	v_exp_f32_e32 v50, v50
	v_mul_f32_e32 v51, 0xbfb8aa3b, v47
	v_exp_f32_e32 v51, v51
	v_mul_f32_e32 v44, v45, v44
	v_add_f32_e32 v45, 1.0, v50
	v_rcp_f32_e32 v45, v45
	v_add_f32_e32 v50, 1.0, v51
	v_rcp_f32_e32 v50, v50
	v_mul_f32_e32 v41, v41, v44
	v_mul_f32_e32 v44, v46, v45
	v_mul_f32_e32 v45, 0xbfb8aa3b, v36
	v_exp_f32_e32 v45, v45
	v_mul_f32_e32 v42, v42, v44
	v_mul_f32_e32 v44, v47, v50
	v_mul_f32_e32 v43, v43, v44
	v_cvt_pk_bf16_f32 v40, v40, v41
	v_cvt_pk_bf16_f32 v41, v42, v43
	v_add_f32_e32 v42, 1.0, v45
	v_rcp_f32_e32 v42, v42
	v_mul_f32_e32 v43, 0xbfb8aa3b, v37
	v_exp_f32_e32 v43, v43
	global_store_dwordx2 v[48:49], v[40:41], off
	v_mul_f32_e32 v36, v36, v42
	v_mul_f32_e32 v32, v32, v36
	v_add_f32_e32 v36, 1.0, v43
	v_mul_f32_e32 v40, 0xbfb8aa3b, v38
	v_rcp_f32_e32 v36, v36
	v_exp_f32_e32 v40, v40
	v_mul_f32_e32 v41, 0xbfb8aa3b, v39
	v_exp_f32_e32 v41, v41
	v_mul_f32_e32 v36, v37, v36
	v_add_f32_e32 v37, 1.0, v40
	v_rcp_f32_e32 v37, v37
	v_add_f32_e32 v40, 1.0, v41
	v_rcp_f32_e32 v40, v40
	v_mul_f32_e32 v33, v33, v36
	v_mul_f32_e32 v36, v38, v37
	v_mul_f32_e32 v34, v34, v36
	v_mul_f32_e32 v36, v39, v40
	v_cvt_pk_bf16_f32 v32, v32, v33
	v_mul_f32_e32 v35, v35, v36
	v_cvt_pk_bf16_f32 v33, v34, v35
	global_store_dwordx2 v[48:49], v[32:33], off offset:128
	v_mul_f32_e32 v32, 0xbfb8aa3b, v28
	v_exp_f32_e32 v34, v32
	v_mul_f32_e32 v35, 0xbfb8aa3b, v29
	v_exp_f32_e32 v35, v35
	v_add_f32_e32 v34, 1.0, v34
	v_rcp_f32_e32 v34, v34
	v_lshl_add_u64 v[32:33], v[48:49], 0, s[98:99]
	v_mul_f32_e32 v28, v28, v34
	v_mul_f32_e32 v24, v24, v28
	v_add_f32_e32 v28, 1.0, v35
	v_mul_f32_e32 v34, 0xbfb8aa3b, v30
	v_rcp_f32_e32 v28, v28
	v_exp_f32_e32 v34, v34
	v_mul_f32_e32 v35, 0xbfb8aa3b, v31
	v_exp_f32_e32 v35, v35
	v_mul_f32_e32 v28, v29, v28
	v_add_f32_e32 v29, 1.0, v34
	v_rcp_f32_e32 v29, v29
	v_add_f32_e32 v34, 1.0, v35
	v_rcp_f32_e32 v34, v34
	v_mul_f32_e32 v25, v25, v28
	v_mul_f32_e32 v28, v30, v29
	v_mul_f32_e32 v29, 0xbfb8aa3b, v20
	v_exp_f32_e32 v29, v29
	v_mul_f32_e32 v26, v26, v28
	v_mul_f32_e32 v28, v31, v34
	v_mul_f32_e32 v27, v27, v28
	v_cvt_pk_bf16_f32 v24, v24, v25
	v_cvt_pk_bf16_f32 v25, v26, v27
	v_add_f32_e32 v26, 1.0, v29
	v_rcp_f32_e32 v26, v26
	v_mul_f32_e32 v27, 0xbfb8aa3b, v21
	v_exp_f32_e32 v27, v27
	global_store_dwordx2 v[32:33], v[24:25], off
	v_mul_f32_e32 v20, v20, v26
	v_mul_f32_e32 v16, v16, v20
	v_add_f32_e32 v20, 1.0, v27
	v_mul_f32_e32 v24, 0xbfb8aa3b, v22
	v_rcp_f32_e32 v20, v20
	v_exp_f32_e32 v24, v24
	v_mul_f32_e32 v25, 0xbfb8aa3b, v23
	v_exp_f32_e32 v25, v25
	v_mul_f32_e32 v20, v21, v20
	v_add_f32_e32 v21, 1.0, v24
	v_rcp_f32_e32 v21, v21
	v_add_f32_e32 v24, 1.0, v25
	v_rcp_f32_e32 v24, v24
	v_mul_f32_e32 v17, v17, v20
	v_mul_f32_e32 v20, v22, v21
	v_mul_f32_e32 v18, v18, v20
	v_mul_f32_e32 v20, v23, v24
	v_cvt_pk_bf16_f32 v16, v16, v17
	v_mul_f32_e32 v19, v19, v20
	v_cvt_pk_bf16_f32 v17, v18, v19
	global_store_dwordx2 v[32:33], v[16:17], off offset:128
	v_mul_f32_e32 v16, 0xbfb8aa3b, v12
	v_exp_f32_e32 v18, v16
	v_mul_f32_e32 v19, 0xbfb8aa3b, v13
	v_exp_f32_e32 v19, v19
	v_add_f32_e32 v18, 1.0, v18
	v_rcp_f32_e32 v18, v18
	v_lshl_add_u64 v[16:17], v[32:33], 0, s[98:99]
	v_mul_f32_e32 v12, v12, v18
	v_mul_f32_e32 v8, v8, v12
	v_add_f32_e32 v12, 1.0, v19
	v_mul_f32_e32 v18, 0xbfb8aa3b, v14
	v_rcp_f32_e32 v12, v12
	v_exp_f32_e32 v18, v18
	v_mul_f32_e32 v19, 0xbfb8aa3b, v15
	v_exp_f32_e32 v19, v19
	v_mul_f32_e32 v12, v13, v12
	v_add_f32_e32 v13, 1.0, v18
	v_rcp_f32_e32 v13, v13
	v_add_f32_e32 v18, 1.0, v19
	v_rcp_f32_e32 v18, v18
	v_mul_f32_e32 v9, v9, v12
	v_mul_f32_e32 v12, v14, v13
	v_mul_f32_e32 v13, 0xbfb8aa3b, v4
	v_exp_f32_e32 v13, v13
	v_mul_f32_e32 v10, v10, v12
	v_mul_f32_e32 v12, v15, v18
	v_mul_f32_e32 v11, v11, v12
	v_cvt_pk_bf16_f32 v8, v8, v9
	v_cvt_pk_bf16_f32 v9, v10, v11
	v_add_f32_e32 v10, 1.0, v13
	v_rcp_f32_e32 v10, v10
	v_mul_f32_e32 v11, 0xbfb8aa3b, v5
	v_exp_f32_e32 v11, v11
	global_store_dwordx2 v[16:17], v[8:9], off
	v_mul_f32_e32 v4, v4, v10
	v_mul_f32_e32 v0, v0, v4
	v_add_f32_e32 v4, 1.0, v11
	v_mul_f32_e32 v8, 0xbfb8aa3b, v6
	v_rcp_f32_e32 v4, v4
	v_exp_f32_e32 v8, v8
	v_mul_f32_e32 v9, 0xbfb8aa3b, v7
	v_exp_f32_e32 v9, v9
	v_mul_f32_e32 v4, v5, v4
	v_add_f32_e32 v5, 1.0, v8
	v_rcp_f32_e32 v5, v5
	v_add_f32_e32 v8, 1.0, v9
	v_rcp_f32_e32 v8, v8
	v_mul_f32_e32 v1, v1, v4
	v_mul_f32_e32 v4, v6, v5
	v_mul_f32_e32 v2, v2, v4
	v_mul_f32_e32 v4, v7, v8
	s_andn2_b64 vcc, exec, s[10:11]
	s_mov_b64 s[10:11], -1
	v_mul_f32_e32 v3, v3, v4
	v_cvt_pk_bf16_f32 v0, v0, v1
	v_cvt_pk_bf16_f32 v1, v2, v3
	global_store_dwordx2 v[16:17], v[0:1], off offset:128
	s_cbranch_vccnz .LBB0_720
	s_andn2_b64 vcc, exec, s[0:1]
	s_cbranch_vccnz .LBB0_719
	s_barrier
	s_branch .LBB0_719

.Lmid_gemm5:
	s_add_i32 s79, 0, 0x18000
	s_add_i32 s87, 0, 0x1c000
	v_add_u32_e32 v164, s79, v147
	v_add_u32_e32 v181, s87, v147
	ds_read_b128 v[152:155], v164
	ds_read_b128 v[156:159], v164 offset:1024
	ds_read_b128 v[160:163], v164 offset:2048
	ds_read_b128 v[164:167], v164 offset:3072
	ds_read_b128 v[168:171], v181
	ds_read_b128 v[172:175], v181 offset:1024
	ds_read_b128 v[176:179], v181 offset:2048
	ds_read_b128 v[184:187], v181 offset:3072
	s_add_u32 s52, s58, 0xb0000
	s_addc_u32 s53, s59, 0
	s_mov_b32 m0, s65
	v_lshl_add_u64 v[226:227], s[52:53], 0, v[128:129]
	ds_read_b128 v[188:191], v151 offset:32768
	ds_read_b128 v[192:195], v151 offset:33792
	ds_read_b128 v[196:199], v151 offset:34816
	ds_read_b128 v[200:203], v151 offset:35840
	ds_read_b128 v[204:207], v151 offset:36864
	ds_read_b128 v[208:211], v151 offset:37888
	ds_read_b128 v[212:215], v151 offset:38912
	ds_read_b128 v[216:219], v151 offset:39936
	global_load_lds_dwordx4 v[226:227], off
	v_lshl_add_u64 v[226:227], s[52:53], 0, v[132:133]
	s_mov_b32 m0, s66
	s_nop 0
	global_load_lds_dwordx4 v[226:227], off
	s_waitcnt vmcnt(8)
	s_waitcnt lgkmcnt(0)
	s_barrier
	s_waitcnt lgkmcnt(0)
	v_mfma_f32_16x16x32_bf16 v[124:127], v[152:155], v[188:191], v[124:127]
	v_mfma_f32_16x16x32_bf16 v[124:127], v[156:159], v[192:195], v[124:127]
	s_setprio 1
	v_mfma_f32_16x16x32_bf16 v[120:123], v[160:163], v[188:191], v[120:123]
	v_mfma_f32_16x16x32_bf16 v[120:123], v[164:167], v[192:195], v[120:123]
	v_mfma_f32_16x16x32_bf16 v[116:119], v[152:155], v[196:199], v[116:119]
	v_mfma_f32_16x16x32_bf16 v[116:119], v[156:159], v[200:203], v[116:119]
	v_mfma_f32_16x16x32_bf16 v[108:111], v[160:163], v[196:199], v[108:111]
	v_mfma_f32_16x16x32_bf16 v[108:111], v[164:167], v[200:203], v[108:111]
	v_mfma_f32_16x16x32_bf16 v[100:103], v[152:155], v[204:207], v[100:103]
	v_mfma_f32_16x16x32_bf16 v[100:103], v[156:159], v[208:211], v[100:103]
	v_mfma_f32_16x16x32_bf16 v[92:95], v[160:163], v[204:207], v[92:95]
	v_mfma_f32_16x16x32_bf16 v[92:95], v[164:167], v[208:211], v[92:95]
	v_mfma_f32_16x16x32_bf16 v[84:87], v[152:155], v[212:215], v[84:87]
	v_mfma_f32_16x16x32_bf16 v[84:87], v[156:159], v[216:219], v[84:87]
	v_mfma_f32_16x16x32_bf16 v[76:79], v[160:163], v[212:215], v[76:79]
	v_mfma_f32_16x16x32_bf16 v[76:79], v[164:167], v[216:219], v[76:79]
	v_mfma_f32_16x16x32_bf16 v[112:115], v[168:171], v[188:191], v[112:115]
	v_mfma_f32_16x16x32_bf16 v[112:115], v[172:175], v[192:195], v[112:115]
	v_mfma_f32_16x16x32_bf16 v[104:107], v[176:179], v[188:191], v[104:107]
	v_mfma_f32_16x16x32_bf16 v[104:107], v[184:187], v[192:195], v[104:107]
	v_mfma_f32_16x16x32_bf16 v[96:99], v[168:171], v[196:199], v[96:99]
	v_mfma_f32_16x16x32_bf16 v[96:99], v[172:175], v[200:203], v[96:99]
	v_mfma_f32_16x16x32_bf16 v[88:91], v[176:179], v[196:199], v[88:91]
	v_mfma_f32_16x16x32_bf16 v[88:91], v[184:187], v[200:203], v[88:91]
	v_mfma_f32_16x16x32_bf16 v[80:83], v[168:171], v[204:207], v[80:83]
	v_mfma_f32_16x16x32_bf16 v[80:83], v[172:175], v[208:211], v[80:83]
	v_mfma_f32_16x16x32_bf16 v[72:75], v[176:179], v[204:207], v[72:75]
	v_mfma_f32_16x16x32_bf16 v[72:75], v[184:187], v[208:211], v[72:75]
	v_mfma_f32_16x16x32_bf16 v[68:71], v[168:171], v[212:215], v[68:71]
	v_mfma_f32_16x16x32_bf16 v[68:71], v[172:175], v[216:219], v[68:71]
	s_barrier
	v_mfma_f32_16x16x32_bf16 v[64:67], v[176:179], v[212:215], v[64:67]
	v_mfma_f32_16x16x32_bf16 v[64:67], v[184:187], v[216:219], v[64:67]
	s_setprio 0
	s_add_i32 s52, s79, s62
	v_lshl_add_u64 v[144:145], v[144:145], 0, s[16:17]
	s_mov_b32 m0, s52
	ds_read_b128 v[188:191], v151 offset:49152
	ds_read_b128 v[192:195], v151 offset:50176
	ds_read_b128 v[196:199], v151 offset:51200
	ds_read_b128 v[200:203], v151 offset:52224
	ds_read_b128 v[204:207], v151 offset:53248
	ds_read_b128 v[208:211], v151 offset:54272
	ds_read_b128 v[212:215], v151 offset:55296
	ds_read_b128 v[216:219], v151 offset:56320
	global_load_lds_dwordx4 v[144:145], off
	s_add_i32 m0, s52, 0x2000
	s_add_u32 s52, s56, 0xb0080
	v_lshl_add_u64 v[144:145], v[220:221], 0, s[16:17]
	s_addc_u32 s53, s57, 0
	s_add_i32 s56, s87, s62
	global_load_lds_dwordx4 v[144:145], off
	v_lshl_add_u64 v[144:145], s[52:53], 0, v[130:131]
	s_mov_b32 m0, s56
	s_nop 0
	global_load_lds_dwordx4 v[144:145], off
	v_lshl_add_u64 v[144:145], s[52:53], 0, v[134:135]
	s_add_i32 m0, s56, 0x2000
	s_nop 0
	global_load_lds_dwordx4 v[144:145], off
	v_lshl_add_u64 v[144:145], v[222:223], 0, s[16:17]
	s_mov_b32 m0, s68
	s_nop 0
	global_load_lds_dwordx4 v[144:145], off
	v_lshl_add_u64 v[144:145], v[224:225], 0, s[16:17]
	s_mov_b32 m0, s69
	s_nop 0
	global_load_lds_dwordx4 v[144:145], off
	s_waitcnt vmcnt(8)
	s_waitcnt lgkmcnt(0)
	s_barrier
	s_waitcnt lgkmcnt(0)
	v_mfma_f32_16x16x32_bf16 v[60:63], v[152:155], v[188:191], v[60:63]
	v_mfma_f32_16x16x32_bf16 v[60:63], v[156:159], v[192:195], v[60:63]
	s_setprio 1
	v_mfma_f32_16x16x32_bf16 v[56:59], v[160:163], v[188:191], v[56:59]
	v_mfma_f32_16x16x32_bf16 v[56:59], v[164:167], v[192:195], v[56:59]
	v_mfma_f32_16x16x32_bf16 v[52:55], v[152:155], v[196:199], v[52:55]
	v_mfma_f32_16x16x32_bf16 v[52:55], v[156:159], v[200:203], v[52:55]
	v_mfma_f32_16x16x32_bf16 v[44:47], v[160:163], v[196:199], v[44:47]
	v_mfma_f32_16x16x32_bf16 v[44:47], v[164:167], v[200:203], v[44:47]
	v_mfma_f32_16x16x32_bf16 v[36:39], v[152:155], v[204:207], v[36:39]
	v_mfma_f32_16x16x32_bf16 v[36:39], v[156:159], v[208:211], v[36:39]
	v_mfma_f32_16x16x32_bf16 v[28:31], v[160:163], v[204:207], v[28:31]
	v_mfma_f32_16x16x32_bf16 v[28:31], v[164:167], v[208:211], v[28:31]
	v_mfma_f32_16x16x32_bf16 v[20:23], v[152:155], v[212:215], v[20:23]
	v_mfma_f32_16x16x32_bf16 v[20:23], v[156:159], v[216:219], v[20:23]
	v_mfma_f32_16x16x32_bf16 v[12:15], v[160:163], v[212:215], v[12:15]
	v_mfma_f32_16x16x32_bf16 v[12:15], v[164:167], v[216:219], v[12:15]
	v_mfma_f32_16x16x32_bf16 v[48:51], v[168:171], v[188:191], v[48:51]
	v_mfma_f32_16x16x32_bf16 v[48:51], v[172:175], v[192:195], v[48:51]
	v_mfma_f32_16x16x32_bf16 v[40:43], v[176:179], v[188:191], v[40:43]
	v_mfma_f32_16x16x32_bf16 v[40:43], v[184:187], v[192:195], v[40:43]
	v_mfma_f32_16x16x32_bf16 v[32:35], v[168:171], v[196:199], v[32:35]
	v_mfma_f32_16x16x32_bf16 v[32:35], v[172:175], v[200:203], v[32:35]
	v_mfma_f32_16x16x32_bf16 v[24:27], v[176:179], v[196:199], v[24:27]
	v_mfma_f32_16x16x32_bf16 v[24:27], v[184:187], v[200:203], v[24:27]
	v_mfma_f32_16x16x32_bf16 v[16:19], v[168:171], v[204:207], v[16:19]
	v_mfma_f32_16x16x32_bf16 v[16:19], v[172:175], v[208:211], v[16:19]
	v_mfma_f32_16x16x32_bf16 v[8:11], v[176:179], v[204:207], v[8:11]
	v_mfma_f32_16x16x32_bf16 v[8:11], v[184:187], v[208:211], v[8:11]
	v_mfma_f32_16x16x32_bf16 v[4:7], v[168:171], v[212:215], v[4:7]
	v_mfma_f32_16x16x32_bf16 v[4:7], v[172:175], v[216:219], v[4:7]
	s_barrier
	v_mfma_f32_16x16x32_bf16 v[0:3], v[176:179], v[212:215], v[0:3]
	v_mfma_f32_16x16x32_bf16 v[0:3], v[184:187], v[216:219], v[0:3]
	s_setprio 0
	s_add_i32 s86, s86, 2
	s_add_u32 s84, s84, 0x100
	s_addc_u32 s85, s85, 0
	s_cmp_gt_u32 s86, 41
	s_mov_b64 s[52:53], s[54:55]
	s_cbranch_scc0 .LBB0_804

.Lmid_gemm6:
	s_add_i32 s79, 0, 0x18000
	v_add_u32_e32 v151, s79, v147
	s_add_i32 s88, 0, 0x1c000
	ds_read_b128 v[152:155], v151
	ds_read_b128 v[156:159], v151 offset:1024
	ds_read_b128 v[160:163], v151 offset:2048
	ds_read_b128 v[164:167], v151 offset:3072
	v_add_u32_e32 v151, s88, v147
	ds_read_b128 v[168:171], v151
	ds_read_b128 v[172:175], v151 offset:1024
	ds_read_b128 v[176:179], v151 offset:2048
	ds_read_b128 v[184:187], v151 offset:3072
	s_add_u32 s64, s64, 0x40000
	s_addc_u32 s65, s65, 0
	s_mov_b32 m0, s71
	v_lshl_add_u64 v[228:229], s[64:65], 0, v[128:129]
	ds_read_b128 v[188:191], v150 offset:32768
	ds_read_b128 v[192:195], v150 offset:33792
	ds_read_b128 v[196:199], v150 offset:34816
	ds_read_b128 v[200:203], v150 offset:35840
	ds_read_b128 v[204:207], v150 offset:36864
	ds_read_b128 v[208:211], v150 offset:37888
	ds_read_b128 v[212:215], v150 offset:38912
	ds_read_b128 v[216:219], v150 offset:39936
	global_load_lds_dwordx4 v[228:229], off
	v_lshl_add_u64 v[228:229], s[64:65], 0, v[132:133]
	s_mov_b32 m0, s72
	s_nop 0
	global_load_lds_dwordx4 v[228:229], off
	s_waitcnt vmcnt(8)
	s_waitcnt lgkmcnt(0)
	s_barrier
	s_waitcnt lgkmcnt(0)
	v_mfma_f32_16x16x32_bf16 v[124:127], v[152:155], v[188:191], v[124:127]
	v_mfma_f32_16x16x32_bf16 v[124:127], v[156:159], v[192:195], v[124:127]
	s_setprio 1
	v_mfma_f32_16x16x32_bf16 v[120:123], v[160:163], v[188:191], v[120:123]
	v_mfma_f32_16x16x32_bf16 v[120:123], v[164:167], v[192:195], v[120:123]
	v_mfma_f32_16x16x32_bf16 v[116:119], v[152:155], v[196:199], v[116:119]
	v_mfma_f32_16x16x32_bf16 v[116:119], v[156:159], v[200:203], v[116:119]
	v_mfma_f32_16x16x32_bf16 v[112:115], v[160:163], v[196:199], v[112:115]
	v_mfma_f32_16x16x32_bf16 v[112:115], v[164:167], v[200:203], v[112:115]
	v_mfma_f32_16x16x32_bf16 v[108:111], v[152:155], v[204:207], v[108:111]
	v_mfma_f32_16x16x32_bf16 v[108:111], v[156:159], v[208:211], v[108:111]
	v_mfma_f32_16x16x32_bf16 v[104:107], v[160:163], v[204:207], v[104:107]
	v_mfma_f32_16x16x32_bf16 v[104:107], v[164:167], v[208:211], v[104:107]
	v_mfma_f32_16x16x32_bf16 v[100:103], v[152:155], v[212:215], v[100:103]
	v_mfma_f32_16x16x32_bf16 v[100:103], v[156:159], v[216:219], v[100:103]
	v_mfma_f32_16x16x32_bf16 v[96:99], v[160:163], v[212:215], v[96:99]
	v_mfma_f32_16x16x32_bf16 v[96:99], v[164:167], v[216:219], v[96:99]
	v_mfma_f32_16x16x32_bf16 v[76:79], v[168:171], v[188:191], v[76:79]
	v_mfma_f32_16x16x32_bf16 v[76:79], v[172:175], v[192:195], v[76:79]
	v_mfma_f32_16x16x32_bf16 v[68:71], v[176:179], v[188:191], v[68:71]
	v_mfma_f32_16x16x32_bf16 v[68:71], v[184:187], v[192:195], v[68:71]
	v_mfma_f32_16x16x32_bf16 v[60:63], v[168:171], v[196:199], v[60:63]
	v_mfma_f32_16x16x32_bf16 v[60:63], v[172:175], v[200:203], v[60:63]
	v_mfma_f32_16x16x32_bf16 v[52:55], v[176:179], v[196:199], v[52:55]
	v_mfma_f32_16x16x32_bf16 v[52:55], v[184:187], v[200:203], v[52:55]
	v_mfma_f32_16x16x32_bf16 v[44:47], v[168:171], v[204:207], v[44:47]
	v_mfma_f32_16x16x32_bf16 v[44:47], v[172:175], v[208:211], v[44:47]
	v_mfma_f32_16x16x32_bf16 v[40:43], v[176:179], v[204:207], v[40:43]
	v_mfma_f32_16x16x32_bf16 v[40:43], v[184:187], v[208:211], v[40:43]
	v_mfma_f32_16x16x32_bf16 v[36:39], v[168:171], v[212:215], v[36:39]
	v_mfma_f32_16x16x32_bf16 v[36:39], v[172:175], v[216:219], v[36:39]
	s_barrier
	v_mfma_f32_16x16x32_bf16 v[32:35], v[176:179], v[212:215], v[32:35]
	v_mfma_f32_16x16x32_bf16 v[32:35], v[184:187], v[216:219], v[32:35]
	s_setprio 0
	s_add_i32 s64, s79, s68
	v_lshl_add_u64 v[220:221], v[220:221], 0, s[12:13]
	s_mov_b32 m0, s64
	ds_read_b128 v[188:191], v150 offset:49152
	ds_read_b128 v[192:195], v150 offset:50176
	ds_read_b128 v[196:199], v150 offset:51200
	ds_read_b128 v[200:203], v150 offset:52224
	ds_read_b128 v[204:207], v150 offset:53248
	ds_read_b128 v[208:211], v150 offset:54272
	ds_read_b128 v[212:215], v150 offset:55296
	ds_read_b128 v[216:219], v150 offset:56320
	global_load_lds_dwordx4 v[220:221], off
	s_add_i32 m0, s64, 0x2000
	s_add_u32 s62, s62, 0x40080
	v_lshl_add_u64 v[220:221], v[222:223], 0, s[12:13]
	s_addc_u32 s63, s63, 0
	s_add_i32 s64, s88, s68
	global_load_lds_dwordx4 v[220:221], off
	v_lshl_add_u64 v[220:221], s[62:63], 0, v[130:131]
	s_mov_b32 m0, s64
	s_nop 0
	global_load_lds_dwordx4 v[220:221], off
	v_lshl_add_u64 v[220:221], s[62:63], 0, v[134:135]
	s_add_i32 m0, s64, 0x2000
	s_nop 0
	global_load_lds_dwordx4 v[220:221], off
	v_lshl_add_u64 v[220:221], v[224:225], 0, s[12:13]
	s_mov_b32 m0, s75
	s_nop 0
	global_load_lds_dwordx4 v[220:221], off
	v_lshl_add_u64 v[220:221], v[226:227], 0, s[12:13]
	s_mov_b32 m0, s76
	s_nop 0
	global_load_lds_dwordx4 v[220:221], off
	s_waitcnt vmcnt(8)
	s_waitcnt lgkmcnt(0)
	s_barrier
	s_waitcnt lgkmcnt(0)
	v_mfma_f32_16x16x32_bf16 v[92:95], v[152:155], v[188:191], v[92:95]
	v_mfma_f32_16x16x32_bf16 v[92:95], v[156:159], v[192:195], v[92:95]
	s_setprio 1
	v_mfma_f32_16x16x32_bf16 v[88:91], v[160:163], v[188:191], v[88:91]
	v_mfma_f32_16x16x32_bf16 v[88:91], v[164:167], v[192:195], v[88:91]
	v_mfma_f32_16x16x32_bf16 v[84:87], v[152:155], v[196:199], v[84:87]
	v_mfma_f32_16x16x32_bf16 v[84:87], v[156:159], v[200:203], v[84:87]
	v_mfma_f32_16x16x32_bf16 v[80:83], v[160:163], v[196:199], v[80:83]
	v_mfma_f32_16x16x32_bf16 v[80:83], v[164:167], v[200:203], v[80:83]
	v_mfma_f32_16x16x32_bf16 v[72:75], v[152:155], v[204:207], v[72:75]
	v_mfma_f32_16x16x32_bf16 v[72:75], v[156:159], v[208:211], v[72:75]
	v_mfma_f32_16x16x32_bf16 v[64:67], v[160:163], v[204:207], v[64:67]
	v_mfma_f32_16x16x32_bf16 v[64:67], v[164:167], v[208:211], v[64:67]
	v_mfma_f32_16x16x32_bf16 v[56:59], v[152:155], v[212:215], v[56:59]
	v_mfma_f32_16x16x32_bf16 v[56:59], v[156:159], v[216:219], v[56:59]
	v_mfma_f32_16x16x32_bf16 v[48:51], v[160:163], v[212:215], v[48:51]
	v_mfma_f32_16x16x32_bf16 v[48:51], v[164:167], v[216:219], v[48:51]
	v_mfma_f32_16x16x32_bf16 v[28:31], v[168:171], v[188:191], v[28:31]
	v_mfma_f32_16x16x32_bf16 v[28:31], v[172:175], v[192:195], v[28:31]
	v_mfma_f32_16x16x32_bf16 v[24:27], v[176:179], v[188:191], v[24:27]
	v_mfma_f32_16x16x32_bf16 v[24:27], v[184:187], v[192:195], v[24:27]
	v_mfma_f32_16x16x32_bf16 v[20:23], v[168:171], v[196:199], v[20:23]
	v_mfma_f32_16x16x32_bf16 v[20:23], v[172:175], v[200:203], v[20:23]
	v_mfma_f32_16x16x32_bf16 v[16:19], v[176:179], v[196:199], v[16:19]
	v_mfma_f32_16x16x32_bf16 v[16:19], v[184:187], v[200:203], v[16:19]
	v_mfma_f32_16x16x32_bf16 v[12:15], v[168:171], v[204:207], v[12:15]
	v_mfma_f32_16x16x32_bf16 v[12:15], v[172:175], v[208:211], v[12:15]
	v_mfma_f32_16x16x32_bf16 v[8:11], v[176:179], v[204:207], v[8:11]
	v_mfma_f32_16x16x32_bf16 v[8:11], v[184:187], v[208:211], v[8:11]
	v_mfma_f32_16x16x32_bf16 v[4:7], v[168:171], v[212:215], v[4:7]
	v_mfma_f32_16x16x32_bf16 v[4:7], v[172:175], v[216:219], v[4:7]
	s_barrier
	v_mfma_f32_16x16x32_bf16 v[0:3], v[176:179], v[212:215], v[0:3]
	v_mfma_f32_16x16x32_bf16 v[0:3], v[184:187], v[216:219], v[0:3]
	s_setprio 0
	s_add_i32 s87, s87, 2
	s_add_u32 s60, s60, 0x100
	s_addc_u32 s61, s61, 0
	s_add_u32 s85, s85, 0x100
	s_addc_u32 s86, s86, 0
	s_cmp_gt_u32 s87, 13
	s_cbranch_scc0 .LBB0_935

.Lmid_gemm7:
	s_add_i32 s77, 0, 0x18000
	s_add_i32 s79, 0, 0x1c000
	v_add_u32_e32 v158, s77, v145
	v_add_u32_e32 v174, s79, v145
	ds_read_b128 v[140:143], v158
	ds_read_b128 v[150:153], v158 offset:1024
	ds_read_b128 v[154:157], v158 offset:2048
	ds_read_b128 v[158:161], v158 offset:3072
	ds_read_b128 v[162:165], v174
	ds_read_b128 v[166:169], v174 offset:1024
	ds_read_b128 v[170:173], v174 offset:2048
	ds_read_b128 v[174:177], v174 offset:3072
	s_add_u32 s56, s56, 0x40000
	s_addc_u32 s57, s57, 0
	s_mov_b32 m0, s63
	v_lshl_add_u64 v[222:223], s[56:57], 0, v[130:131]
	ds_read_b128 v[184:187], v149 offset:32768
	ds_read_b128 v[188:191], v149 offset:33792
	ds_read_b128 v[192:195], v149 offset:34816
	ds_read_b128 v[196:199], v149 offset:35840
	ds_read_b128 v[200:203], v149 offset:36864
	ds_read_b128 v[204:207], v149 offset:37888
	ds_read_b128 v[208:211], v149 offset:38912
	ds_read_b128 v[212:215], v149 offset:39936
	global_load_lds_dwordx4 v[222:223], off
	v_lshl_add_u64 v[222:223], s[56:57], 0, v[128:129]
	s_mov_b32 m0, s64
	s_nop 0
	global_load_lds_dwordx4 v[222:223], off
	s_waitcnt vmcnt(8)
	s_waitcnt lgkmcnt(0)
	s_barrier
	s_waitcnt lgkmcnt(0)
	v_mfma_f32_16x16x32_bf16 v[124:127], v[140:143], v[184:187], v[124:127]
	v_mfma_f32_16x16x32_bf16 v[124:127], v[150:153], v[188:191], v[124:127]
	s_setprio 1
	v_mfma_f32_16x16x32_bf16 v[120:123], v[154:157], v[184:187], v[120:123]
	v_mfma_f32_16x16x32_bf16 v[120:123], v[158:161], v[188:191], v[120:123]
	v_mfma_f32_16x16x32_bf16 v[108:111], v[140:143], v[192:195], v[108:111]
	v_mfma_f32_16x16x32_bf16 v[108:111], v[150:153], v[196:199], v[108:111]
	v_mfma_f32_16x16x32_bf16 v[104:107], v[154:157], v[192:195], v[104:107]
	v_mfma_f32_16x16x32_bf16 v[104:107], v[158:161], v[196:199], v[104:107]
	v_mfma_f32_16x16x32_bf16 v[92:95], v[140:143], v[200:203], v[92:95]
	v_mfma_f32_16x16x32_bf16 v[92:95], v[150:153], v[204:207], v[92:95]
	v_mfma_f32_16x16x32_bf16 v[88:91], v[154:157], v[200:203], v[88:91]
	v_mfma_f32_16x16x32_bf16 v[88:91], v[158:161], v[204:207], v[88:91]
	v_mfma_f32_16x16x32_bf16 v[76:79], v[140:143], v[208:211], v[76:79]
	v_mfma_f32_16x16x32_bf16 v[76:79], v[150:153], v[212:215], v[76:79]
	v_mfma_f32_16x16x32_bf16 v[72:75], v[154:157], v[208:211], v[72:75]
	v_mfma_f32_16x16x32_bf16 v[72:75], v[158:161], v[212:215], v[72:75]
	v_mfma_f32_16x16x32_bf16 v[116:119], v[162:165], v[184:187], v[116:119]
	v_mfma_f32_16x16x32_bf16 v[116:119], v[166:169], v[188:191], v[116:119]
	v_mfma_f32_16x16x32_bf16 v[112:115], v[170:173], v[184:187], v[112:115]
	v_mfma_f32_16x16x32_bf16 v[112:115], v[174:177], v[188:191], v[112:115]
	v_mfma_f32_16x16x32_bf16 v[100:103], v[162:165], v[192:195], v[100:103]
	v_mfma_f32_16x16x32_bf16 v[100:103], v[166:169], v[196:199], v[100:103]
	v_mfma_f32_16x16x32_bf16 v[96:99], v[170:173], v[192:195], v[96:99]
	v_mfma_f32_16x16x32_bf16 v[96:99], v[174:177], v[196:199], v[96:99]
	v_mfma_f32_16x16x32_bf16 v[84:87], v[162:165], v[200:203], v[84:87]
	v_mfma_f32_16x16x32_bf16 v[84:87], v[166:169], v[204:207], v[84:87]
	v_mfma_f32_16x16x32_bf16 v[80:83], v[170:173], v[200:203], v[80:83]
	v_mfma_f32_16x16x32_bf16 v[80:83], v[174:177], v[204:207], v[80:83]
	v_mfma_f32_16x16x32_bf16 v[68:71], v[162:165], v[208:211], v[68:71]
	v_mfma_f32_16x16x32_bf16 v[68:71], v[166:169], v[212:215], v[68:71]
	s_barrier
	v_mfma_f32_16x16x32_bf16 v[64:67], v[170:173], v[208:211], v[64:67]
	v_mfma_f32_16x16x32_bf16 v[64:67], v[174:177], v[212:215], v[64:67]
	s_setprio 0
	s_add_i32 s56, s77, s60
	v_lshl_add_u64 v[178:179], v[178:179], 0, s[12:13]
	s_mov_b32 m0, s56
	ds_read_b128 v[184:187], v149 offset:49152
	ds_read_b128 v[188:191], v149 offset:50176
	ds_read_b128 v[192:195], v149 offset:51200
	ds_read_b128 v[196:199], v149 offset:52224
	ds_read_b128 v[200:203], v149 offset:53248
	ds_read_b128 v[204:207], v149 offset:54272
	ds_read_b128 v[208:211], v149 offset:55296
	ds_read_b128 v[212:215], v149 offset:56320
	global_load_lds_dwordx4 v[178:179], off
	s_add_i32 m0, s56, 0x2000
	s_add_u32 s54, s54, 0x40080
	v_lshl_add_u64 v[178:179], v[216:217], 0, s[12:13]
	s_addc_u32 s55, s55, 0
	s_add_i32 s56, s79, s60
	global_load_lds_dwordx4 v[178:179], off
	v_lshl_add_u64 v[178:179], s[54:55], 0, v[130:131]
	s_mov_b32 m0, s56
	s_nop 0
	global_load_lds_dwordx4 v[178:179], off
	v_lshl_add_u64 v[178:179], s[54:55], 0, v[128:129]
	s_add_i32 m0, s56, 0x2000
	s_nop 0
	global_load_lds_dwordx4 v[178:179], off
	v_lshl_add_u64 v[178:179], v[218:219], 0, s[12:13]
	s_mov_b32 m0, s66
	s_nop 0
	global_load_lds_dwordx4 v[178:179], off
	v_lshl_add_u64 v[178:179], v[220:221], 0, s[12:13]
	s_mov_b32 m0, s67
	s_nop 0
	global_load_lds_dwordx4 v[178:179], off
	s_waitcnt vmcnt(8)
	s_waitcnt lgkmcnt(0)
	s_barrier
	s_waitcnt lgkmcnt(0)
	v_mfma_f32_16x16x32_bf16 v[60:63], v[140:143], v[184:187], v[60:63]
	v_mfma_f32_16x16x32_bf16 v[60:63], v[150:153], v[188:191], v[60:63]
	s_setprio 1
	v_mfma_f32_16x16x32_bf16 v[56:59], v[154:157], v[184:187], v[56:59]
	v_mfma_f32_16x16x32_bf16 v[56:59], v[158:161], v[188:191], v[56:59]
	v_mfma_f32_16x16x32_bf16 v[44:47], v[140:143], v[192:195], v[44:47]
	v_mfma_f32_16x16x32_bf16 v[44:47], v[150:153], v[196:199], v[44:47]
	v_mfma_f32_16x16x32_bf16 v[40:43], v[154:157], v[192:195], v[40:43]
	v_mfma_f32_16x16x32_bf16 v[40:43], v[158:161], v[196:199], v[40:43]
	v_mfma_f32_16x16x32_bf16 v[28:31], v[140:143], v[200:203], v[28:31]
	v_mfma_f32_16x16x32_bf16 v[28:31], v[150:153], v[204:207], v[28:31]
	v_mfma_f32_16x16x32_bf16 v[24:27], v[154:157], v[200:203], v[24:27]
	v_mfma_f32_16x16x32_bf16 v[24:27], v[158:161], v[204:207], v[24:27]
	v_mfma_f32_16x16x32_bf16 v[12:15], v[140:143], v[208:211], v[12:15]
	v_mfma_f32_16x16x32_bf16 v[12:15], v[150:153], v[212:215], v[12:15]
	v_mfma_f32_16x16x32_bf16 v[8:11], v[154:157], v[208:211], v[8:11]
	v_mfma_f32_16x16x32_bf16 v[8:11], v[158:161], v[212:215], v[8:11]
	v_mfma_f32_16x16x32_bf16 v[52:55], v[162:165], v[184:187], v[52:55]
	v_mfma_f32_16x16x32_bf16 v[52:55], v[166:169], v[188:191], v[52:55]
	v_mfma_f32_16x16x32_bf16 v[48:51], v[170:173], v[184:187], v[48:51]
	v_mfma_f32_16x16x32_bf16 v[48:51], v[174:177], v[188:191], v[48:51]
	v_mfma_f32_16x16x32_bf16 v[36:39], v[162:165], v[192:195], v[36:39]
	v_mfma_f32_16x16x32_bf16 v[36:39], v[166:169], v[196:199], v[36:39]
	v_mfma_f32_16x16x32_bf16 v[32:35], v[170:173], v[192:195], v[32:35]
	v_mfma_f32_16x16x32_bf16 v[32:35], v[174:177], v[196:199], v[32:35]
	v_mfma_f32_16x16x32_bf16 v[20:23], v[162:165], v[200:203], v[20:23]
	v_mfma_f32_16x16x32_bf16 v[20:23], v[166:169], v[204:207], v[20:23]
	v_mfma_f32_16x16x32_bf16 v[16:19], v[170:173], v[200:203], v[16:19]
	v_mfma_f32_16x16x32_bf16 v[16:19], v[174:177], v[204:207], v[16:19]
	v_mfma_f32_16x16x32_bf16 v[4:7], v[162:165], v[208:211], v[4:7]
	v_mfma_f32_16x16x32_bf16 v[4:7], v[166:169], v[212:215], v[4:7]
	s_barrier
	v_mfma_f32_16x16x32_bf16 v[0:3], v[170:173], v[208:211], v[0:3]
	v_mfma_f32_16x16x32_bf16 v[0:3], v[174:177], v[212:215], v[0:3]
	s_setprio 0
	s_add_i32 s76, s76, 2
	s_add_u32 s52, s52, 0x100
	s_addc_u32 s53, s53, 0
	s_add_u32 s74, s74, 0x100
	s_addc_u32 s75, s75, 0
	s_cmp_gt_u32 s76, 13
	s_cbranch_scc0 .LBB0_951
.LBB0_954:
	s_mov_b64 s[98:99], 0x16000
	s_mov_b64 s[100:101], 0x6e000
	v_mul_f32_e32 v151, 0xbfb8aa3b, v124
	v_exp_f32_e32 v151, v151
	v_mul_f32_e32 v154, 0xbfb8aa3b, v125
	v_exp_f32_e32 v154, v154
	v_lshl_or_b32 v142, s71, 7, v146
	v_add_f32_e32 v151, 1.0, v151
	v_rcp_f32_e32 v151, v151
	v_lshl_add_u32 v150, s48, 8, v144
	v_ashrrev_i32_e32 v143, 31, v142
	v_mov_b64_e32 v[140:141], s[22:23]
	v_mul_f32_e32 v124, v124, v151
	v_mul_f32_e32 v120, v120, v124
	v_add_f32_e32 v124, 1.0, v154
	v_mul_f32_e32 v151, 0xbfb8aa3b, v126
	v_rcp_f32_e32 v124, v124
	v_exp_f32_e32 v151, v151
	v_mul_f32_e32 v154, 0xbfb8aa3b, v127
	v_exp_f32_e32 v154, v154
	v_mul_f32_e32 v124, v125, v124
	v_add_f32_e32 v125, 1.0, v151
	v_rcp_f32_e32 v125, v125
	v_add_f32_e32 v151, 1.0, v154
	v_rcp_f32_e32 v151, v151
	v_mul_f32_e32 v121, v121, v124
	v_mul_f32_e32 v124, v126, v125
	v_mul_f32_e32 v125, 0xbfb8aa3b, v116
	v_exp_f32_e32 v125, v125
	v_mul_f32_e32 v122, v122, v124
	v_mul_f32_e32 v124, v127, v151
	v_mul_f32_e32 v123, v123, v124
	v_cvt_pk_bf16_f32 v120, v120, v121
	v_cvt_pk_bf16_f32 v121, v122, v123
	v_add_f32_e32 v122, 1.0, v125
	v_rcp_f32_e32 v122, v122
	v_mul_f32_e32 v123, 0xbfb8aa3b, v117
	v_exp_f32_e32 v123, v123
	v_mad_i64_i32 v[152:153], s[52:53], v150, s70, v[140:141]
	v_lshlrev_b64 v[142:143], 1, v[142:143]
	v_lshl_add_u64 v[152:153], v[152:153], 0, v[142:143]
	v_mul_f32_e32 v116, v116, v122
	global_store_dwordx2 v[152:153], v[120:121], off
	v_mul_f32_e32 v112, v112, v116
	v_add_f32_e32 v116, 1.0, v123
	v_mul_f32_e32 v120, 0xbfb8aa3b, v118
	v_rcp_f32_e32 v116, v116
	v_exp_f32_e32 v120, v120
	v_mul_f32_e32 v121, 0xbfb8aa3b, v119
	v_exp_f32_e32 v121, v121
	v_mul_f32_e32 v116, v117, v116
	v_add_f32_e32 v117, 1.0, v120
	v_rcp_f32_e32 v117, v117
	v_add_f32_e32 v120, 1.0, v121
	v_rcp_f32_e32 v120, v120
	v_mul_f32_e32 v113, v113, v116
	v_mul_f32_e32 v116, v118, v117
	v_mul_f32_e32 v114, v114, v116
	v_mul_f32_e32 v116, v119, v120
	v_cvt_pk_bf16_f32 v112, v112, v113
	v_mul_f32_e32 v115, v115, v116
	v_cvt_pk_bf16_f32 v113, v114, v115
	global_store_dwordx2 v[152:153], v[112:113], off offset:128
	v_mul_f32_e32 v112, 0xbfb8aa3b, v108
	v_exp_f32_e32 v114, v112
	v_mul_f32_e32 v115, 0xbfb8aa3b, v109
	s_and_b64 vcc, exec, s[16:17]
	s_cbranch_vccz .Lxb_7
	s_barrier

.Lmid_gemm8:
	s_add_i32 s79, 0, 0x18000
	s_add_i32 s89, 0, 0x1c000
	v_add_u32_e32 v164, s79, v147
	v_add_u32_e32 v181, s89, v147
	ds_read_b128 v[152:155], v164
	ds_read_b128 v[156:159], v164 offset:1024
	ds_read_b128 v[160:163], v164 offset:2048
	ds_read_b128 v[164:167], v164 offset:3072
	ds_read_b128 v[168:171], v181
	ds_read_b128 v[172:175], v181 offset:1024
	ds_read_b128 v[176:179], v181 offset:2048
	ds_read_b128 v[184:187], v181 offset:3072
	s_add_u32 s54, s60, 0xb0000
	s_addc_u32 s55, s61, 0
	s_mov_b32 m0, s67
	v_lshl_add_u64 v[226:227], s[54:55], 0, v[128:129]
	ds_read_b128 v[188:191], v151 offset:32768
	ds_read_b128 v[192:195], v151 offset:33792
	ds_read_b128 v[196:199], v151 offset:34816
	ds_read_b128 v[200:203], v151 offset:35840
	ds_read_b128 v[204:207], v151 offset:36864
	ds_read_b128 v[208:211], v151 offset:37888
	ds_read_b128 v[212:215], v151 offset:38912
	ds_read_b128 v[216:219], v151 offset:39936
	global_load_lds_dwordx4 v[226:227], off
	v_lshl_add_u64 v[226:227], s[54:55], 0, v[132:133]
	s_mov_b32 m0, s68
	s_nop 0
	global_load_lds_dwordx4 v[226:227], off
	s_waitcnt vmcnt(8)
	s_waitcnt lgkmcnt(0)
	s_barrier
	s_waitcnt lgkmcnt(0)
	v_mfma_f32_16x16x32_bf16 v[124:127], v[152:155], v[188:191], v[124:127]
	v_mfma_f32_16x16x32_bf16 v[124:127], v[156:159], v[192:195], v[124:127]
	s_setprio 1
	v_mfma_f32_16x16x32_bf16 v[120:123], v[160:163], v[188:191], v[120:123]
	v_mfma_f32_16x16x32_bf16 v[120:123], v[164:167], v[192:195], v[120:123]
	v_mfma_f32_16x16x32_bf16 v[116:119], v[152:155], v[196:199], v[116:119]
	v_mfma_f32_16x16x32_bf16 v[116:119], v[156:159], v[200:203], v[116:119]
	v_mfma_f32_16x16x32_bf16 v[108:111], v[160:163], v[196:199], v[108:111]
	v_mfma_f32_16x16x32_bf16 v[108:111], v[164:167], v[200:203], v[108:111]
	v_mfma_f32_16x16x32_bf16 v[100:103], v[152:155], v[204:207], v[100:103]
	v_mfma_f32_16x16x32_bf16 v[100:103], v[156:159], v[208:211], v[100:103]
	v_mfma_f32_16x16x32_bf16 v[92:95], v[160:163], v[204:207], v[92:95]
	v_mfma_f32_16x16x32_bf16 v[92:95], v[164:167], v[208:211], v[92:95]
	v_mfma_f32_16x16x32_bf16 v[84:87], v[152:155], v[212:215], v[84:87]
	v_mfma_f32_16x16x32_bf16 v[84:87], v[156:159], v[216:219], v[84:87]
	v_mfma_f32_16x16x32_bf16 v[76:79], v[160:163], v[212:215], v[76:79]
	v_mfma_f32_16x16x32_bf16 v[76:79], v[164:167], v[216:219], v[76:79]
	v_mfma_f32_16x16x32_bf16 v[112:115], v[168:171], v[188:191], v[112:115]
	v_mfma_f32_16x16x32_bf16 v[112:115], v[172:175], v[192:195], v[112:115]
	v_mfma_f32_16x16x32_bf16 v[104:107], v[176:179], v[188:191], v[104:107]
	v_mfma_f32_16x16x32_bf16 v[104:107], v[184:187], v[192:195], v[104:107]
	v_mfma_f32_16x16x32_bf16 v[96:99], v[168:171], v[196:199], v[96:99]
	v_mfma_f32_16x16x32_bf16 v[96:99], v[172:175], v[200:203], v[96:99]
	v_mfma_f32_16x16x32_bf16 v[88:91], v[176:179], v[196:199], v[88:91]
	v_mfma_f32_16x16x32_bf16 v[88:91], v[184:187], v[200:203], v[88:91]
	v_mfma_f32_16x16x32_bf16 v[80:83], v[168:171], v[204:207], v[80:83]
	v_mfma_f32_16x16x32_bf16 v[80:83], v[172:175], v[208:211], v[80:83]
	v_mfma_f32_16x16x32_bf16 v[72:75], v[176:179], v[204:207], v[72:75]
	v_mfma_f32_16x16x32_bf16 v[72:75], v[184:187], v[208:211], v[72:75]
	v_mfma_f32_16x16x32_bf16 v[68:71], v[168:171], v[212:215], v[68:71]
	v_mfma_f32_16x16x32_bf16 v[68:71], v[172:175], v[216:219], v[68:71]
	s_barrier
	v_mfma_f32_16x16x32_bf16 v[64:67], v[176:179], v[212:215], v[64:67]
	v_mfma_f32_16x16x32_bf16 v[64:67], v[184:187], v[216:219], v[64:67]
	s_setprio 0
	s_add_i32 s54, s79, s64
	v_lshl_add_u64 v[144:145], v[144:145], 0, s[16:17]
	s_mov_b32 m0, s54
	ds_read_b128 v[188:191], v151 offset:49152
	ds_read_b128 v[192:195], v151 offset:50176
	ds_read_b128 v[196:199], v151 offset:51200
	ds_read_b128 v[200:203], v151 offset:52224
	ds_read_b128 v[204:207], v151 offset:53248
	ds_read_b128 v[208:211], v151 offset:54272
	ds_read_b128 v[212:215], v151 offset:55296
	ds_read_b128 v[216:219], v151 offset:56320
	global_load_lds_dwordx4 v[144:145], off
	s_add_i32 m0, s54, 0x2000
	s_add_u32 s54, s58, 0xb0080
	v_lshl_add_u64 v[144:145], v[220:221], 0, s[16:17]
	s_addc_u32 s55, s59, 0
	s_add_i32 s58, s89, s64
	global_load_lds_dwordx4 v[144:145], off
	v_lshl_add_u64 v[144:145], s[54:55], 0, v[130:131]
	s_mov_b32 m0, s58
	s_nop 0
	global_load_lds_dwordx4 v[144:145], off
	v_lshl_add_u64 v[144:145], s[54:55], 0, v[134:135]
	s_add_i32 m0, s58, 0x2000
	s_nop 0
	global_load_lds_dwordx4 v[144:145], off
	v_lshl_add_u64 v[144:145], v[222:223], 0, s[16:17]
	s_mov_b32 m0, s70
	s_nop 0
	global_load_lds_dwordx4 v[144:145], off
	v_lshl_add_u64 v[144:145], v[224:225], 0, s[16:17]
	s_mov_b32 m0, s71
	s_nop 0
	global_load_lds_dwordx4 v[144:145], off
	s_waitcnt vmcnt(8)
	s_waitcnt lgkmcnt(0)
	s_barrier
	s_waitcnt lgkmcnt(0)
	v_mfma_f32_16x16x32_bf16 v[60:63], v[152:155], v[188:191], v[60:63]
	v_mfma_f32_16x16x32_bf16 v[60:63], v[156:159], v[192:195], v[60:63]
	s_setprio 1
	v_mfma_f32_16x16x32_bf16 v[56:59], v[160:163], v[188:191], v[56:59]
	v_mfma_f32_16x16x32_bf16 v[56:59], v[164:167], v[192:195], v[56:59]
	v_mfma_f32_16x16x32_bf16 v[52:55], v[152:155], v[196:199], v[52:55]
	v_mfma_f32_16x16x32_bf16 v[52:55], v[156:159], v[200:203], v[52:55]
	v_mfma_f32_16x16x32_bf16 v[44:47], v[160:163], v[196:199], v[44:47]
	v_mfma_f32_16x16x32_bf16 v[44:47], v[164:167], v[200:203], v[44:47]
	v_mfma_f32_16x16x32_bf16 v[36:39], v[152:155], v[204:207], v[36:39]
	v_mfma_f32_16x16x32_bf16 v[36:39], v[156:159], v[208:211], v[36:39]
	v_mfma_f32_16x16x32_bf16 v[28:31], v[160:163], v[204:207], v[28:31]
	v_mfma_f32_16x16x32_bf16 v[28:31], v[164:167], v[208:211], v[28:31]
	v_mfma_f32_16x16x32_bf16 v[20:23], v[152:155], v[212:215], v[20:23]
	v_mfma_f32_16x16x32_bf16 v[20:23], v[156:159], v[216:219], v[20:23]
	v_mfma_f32_16x16x32_bf16 v[12:15], v[160:163], v[212:215], v[12:15]
	v_mfma_f32_16x16x32_bf16 v[12:15], v[164:167], v[216:219], v[12:15]
	v_mfma_f32_16x16x32_bf16 v[48:51], v[168:171], v[188:191], v[48:51]
	v_mfma_f32_16x16x32_bf16 v[48:51], v[172:175], v[192:195], v[48:51]
	v_mfma_f32_16x16x32_bf16 v[40:43], v[176:179], v[188:191], v[40:43]
	v_mfma_f32_16x16x32_bf16 v[40:43], v[184:187], v[192:195], v[40:43]
	v_mfma_f32_16x16x32_bf16 v[32:35], v[168:171], v[196:199], v[32:35]
	v_mfma_f32_16x16x32_bf16 v[32:35], v[172:175], v[200:203], v[32:35]
	v_mfma_f32_16x16x32_bf16 v[24:27], v[176:179], v[196:199], v[24:27]
	v_mfma_f32_16x16x32_bf16 v[24:27], v[184:187], v[200:203], v[24:27]
	v_mfma_f32_16x16x32_bf16 v[16:19], v[168:171], v[204:207], v[16:19]
	v_mfma_f32_16x16x32_bf16 v[16:19], v[172:175], v[208:211], v[16:19]
	v_mfma_f32_16x16x32_bf16 v[8:11], v[176:179], v[204:207], v[8:11]
	v_mfma_f32_16x16x32_bf16 v[8:11], v[184:187], v[208:211], v[8:11]
	v_mfma_f32_16x16x32_bf16 v[4:7], v[168:171], v[212:215], v[4:7]
	v_mfma_f32_16x16x32_bf16 v[4:7], v[172:175], v[216:219], v[4:7]
	s_barrier
	v_mfma_f32_16x16x32_bf16 v[0:3], v[176:179], v[212:215], v[0:3]
	v_mfma_f32_16x16x32_bf16 v[0:3], v[184:187], v[216:219], v[0:3]
	s_setprio 0
	s_add_i32 s88, s88, 2
	s_add_u32 s86, s86, 0x100
	s_addc_u32 s87, s87, 0
	s_cmp_gt_u32 s88, 41
	s_mov_b64 s[54:55], s[56:57]
	s_cbranch_scc0 .LBB0_1031

.Lmid_gemm9:
	s_add_i32 s79, 0, 0x18000
	s_add_i32 s88, 0, 0x1c000
	v_add_u32_e32 v164, s79, v147
	v_add_u32_e32 v181, s88, v147
	ds_read_b128 v[152:155], v164
	ds_read_b128 v[156:159], v164 offset:1024
	ds_read_b128 v[160:163], v164 offset:2048
	ds_read_b128 v[164:167], v164 offset:3072
	ds_read_b128 v[168:171], v181
	ds_read_b128 v[172:175], v181 offset:1024
	ds_read_b128 v[176:179], v181 offset:2048
	ds_read_b128 v[184:187], v181 offset:3072
	s_add_u32 s64, s64, 0x40000
	s_addc_u32 s65, s65, 0
	s_mov_b32 m0, s71
	v_lshl_add_u64 v[228:229], s[64:65], 0, v[128:129]
	ds_read_b128 v[188:191], v150 offset:32768
	ds_read_b128 v[192:195], v150 offset:33792
	ds_read_b128 v[196:199], v150 offset:34816
	ds_read_b128 v[200:203], v150 offset:35840
	ds_read_b128 v[204:207], v150 offset:36864
	ds_read_b128 v[208:211], v150 offset:37888
	ds_read_b128 v[212:215], v150 offset:38912
	ds_read_b128 v[216:219], v150 offset:39936
	global_load_lds_dwordx4 v[228:229], off
	v_lshl_add_u64 v[228:229], s[64:65], 0, v[132:133]
	s_mov_b32 m0, s72
	s_nop 0
	global_load_lds_dwordx4 v[228:229], off
	s_waitcnt vmcnt(8)
	s_waitcnt lgkmcnt(0)
	s_barrier
	s_waitcnt lgkmcnt(0)
	v_mfma_f32_16x16x32_bf16 v[124:127], v[152:155], v[188:191], v[124:127]
	v_mfma_f32_16x16x32_bf16 v[124:127], v[156:159], v[192:195], v[124:127]
	s_setprio 1
	v_mfma_f32_16x16x32_bf16 v[120:123], v[160:163], v[188:191], v[120:123]
	v_mfma_f32_16x16x32_bf16 v[120:123], v[164:167], v[192:195], v[120:123]
	v_mfma_f32_16x16x32_bf16 v[116:119], v[152:155], v[196:199], v[116:119]
	v_mfma_f32_16x16x32_bf16 v[116:119], v[156:159], v[200:203], v[116:119]
	v_mfma_f32_16x16x32_bf16 v[112:115], v[160:163], v[196:199], v[112:115]
	v_mfma_f32_16x16x32_bf16 v[112:115], v[164:167], v[200:203], v[112:115]
	v_mfma_f32_16x16x32_bf16 v[108:111], v[152:155], v[204:207], v[108:111]
	v_mfma_f32_16x16x32_bf16 v[108:111], v[156:159], v[208:211], v[108:111]
	v_mfma_f32_16x16x32_bf16 v[104:107], v[160:163], v[204:207], v[104:107]
	v_mfma_f32_16x16x32_bf16 v[104:107], v[164:167], v[208:211], v[104:107]
	v_mfma_f32_16x16x32_bf16 v[100:103], v[152:155], v[212:215], v[100:103]
	v_mfma_f32_16x16x32_bf16 v[100:103], v[156:159], v[216:219], v[100:103]
	v_mfma_f32_16x16x32_bf16 v[96:99], v[160:163], v[212:215], v[96:99]
	v_mfma_f32_16x16x32_bf16 v[96:99], v[164:167], v[216:219], v[96:99]
	v_mfma_f32_16x16x32_bf16 v[68:71], v[168:171], v[188:191], v[68:71]
	v_mfma_f32_16x16x32_bf16 v[68:71], v[172:175], v[192:195], v[68:71]
	v_mfma_f32_16x16x32_bf16 v[64:67], v[176:179], v[188:191], v[64:67]
	v_mfma_f32_16x16x32_bf16 v[64:67], v[184:187], v[192:195], v[64:67]
	v_mfma_f32_16x16x32_bf16 v[52:55], v[168:171], v[196:199], v[52:55]
	v_mfma_f32_16x16x32_bf16 v[52:55], v[172:175], v[200:203], v[52:55]
	v_mfma_f32_16x16x32_bf16 v[48:51], v[176:179], v[196:199], v[48:51]
	v_mfma_f32_16x16x32_bf16 v[48:51], v[184:187], v[200:203], v[48:51]
	v_mfma_f32_16x16x32_bf16 v[44:47], v[168:171], v[204:207], v[44:47]
	v_mfma_f32_16x16x32_bf16 v[44:47], v[172:175], v[208:211], v[44:47]
	v_mfma_f32_16x16x32_bf16 v[40:43], v[176:179], v[204:207], v[40:43]
	v_mfma_f32_16x16x32_bf16 v[40:43], v[184:187], v[208:211], v[40:43]
	v_mfma_f32_16x16x32_bf16 v[36:39], v[168:171], v[212:215], v[36:39]
	v_mfma_f32_16x16x32_bf16 v[36:39], v[172:175], v[216:219], v[36:39]
	s_barrier
	v_mfma_f32_16x16x32_bf16 v[32:35], v[176:179], v[212:215], v[32:35]
	v_mfma_f32_16x16x32_bf16 v[32:35], v[184:187], v[216:219], v[32:35]
	s_setprio 0
	s_add_i32 s64, s79, s68
	v_lshl_add_u64 v[220:221], v[220:221], 0, s[12:13]
	s_mov_b32 m0, s64
	ds_read_b128 v[188:191], v150 offset:49152
	ds_read_b128 v[192:195], v150 offset:50176
	ds_read_b128 v[196:199], v150 offset:51200
	ds_read_b128 v[200:203], v150 offset:52224
	ds_read_b128 v[204:207], v150 offset:53248
	ds_read_b128 v[208:211], v150 offset:54272
	ds_read_b128 v[212:215], v150 offset:55296
	ds_read_b128 v[216:219], v150 offset:56320
	global_load_lds_dwordx4 v[220:221], off
	s_add_i32 m0, s64, 0x2000
	s_add_u32 s62, s62, 0x40080
	v_lshl_add_u64 v[220:221], v[222:223], 0, s[12:13]
	s_addc_u32 s63, s63, 0
	s_add_i32 s64, s88, s68
	global_load_lds_dwordx4 v[220:221], off
	v_lshl_add_u64 v[220:221], s[62:63], 0, v[130:131]
	s_mov_b32 m0, s64
	s_nop 0
	global_load_lds_dwordx4 v[220:221], off
	v_lshl_add_u64 v[220:221], s[62:63], 0, v[134:135]
	s_add_i32 m0, s64, 0x2000
	s_nop 0
	global_load_lds_dwordx4 v[220:221], off
	v_lshl_add_u64 v[220:221], v[224:225], 0, s[12:13]
	s_mov_b32 m0, s75
	s_nop 0
	global_load_lds_dwordx4 v[220:221], off
	v_lshl_add_u64 v[220:221], v[226:227], 0, s[12:13]
	s_mov_b32 m0, s76
	s_nop 0
	global_load_lds_dwordx4 v[220:221], off
	s_waitcnt vmcnt(8)
	s_waitcnt lgkmcnt(0)
	s_barrier
	s_waitcnt lgkmcnt(0)
	v_mfma_f32_16x16x32_bf16 v[92:95], v[152:155], v[188:191], v[92:95]
	v_mfma_f32_16x16x32_bf16 v[92:95], v[156:159], v[192:195], v[92:95]
	s_setprio 1
	v_mfma_f32_16x16x32_bf16 v[88:91], v[160:163], v[188:191], v[88:91]
	v_mfma_f32_16x16x32_bf16 v[88:91], v[164:167], v[192:195], v[88:91]
	v_mfma_f32_16x16x32_bf16 v[84:87], v[152:155], v[196:199], v[84:87]
	v_mfma_f32_16x16x32_bf16 v[84:87], v[156:159], v[200:203], v[84:87]
	v_mfma_f32_16x16x32_bf16 v[80:83], v[160:163], v[196:199], v[80:83]
	v_mfma_f32_16x16x32_bf16 v[80:83], v[164:167], v[200:203], v[80:83]
	v_mfma_f32_16x16x32_bf16 v[76:79], v[152:155], v[204:207], v[76:79]
	v_mfma_f32_16x16x32_bf16 v[76:79], v[156:159], v[208:211], v[76:79]
	v_mfma_f32_16x16x32_bf16 v[72:75], v[160:163], v[204:207], v[72:75]
	v_mfma_f32_16x16x32_bf16 v[72:75], v[164:167], v[208:211], v[72:75]
	v_mfma_f32_16x16x32_bf16 v[60:63], v[152:155], v[212:215], v[60:63]
	v_mfma_f32_16x16x32_bf16 v[60:63], v[156:159], v[216:219], v[60:63]
	v_mfma_f32_16x16x32_bf16 v[56:59], v[160:163], v[212:215], v[56:59]
	v_mfma_f32_16x16x32_bf16 v[56:59], v[164:167], v[216:219], v[56:59]
	v_mfma_f32_16x16x32_bf16 v[28:31], v[168:171], v[188:191], v[28:31]
	v_mfma_f32_16x16x32_bf16 v[28:31], v[172:175], v[192:195], v[28:31]
	v_mfma_f32_16x16x32_bf16 v[24:27], v[176:179], v[188:191], v[24:27]
	v_mfma_f32_16x16x32_bf16 v[24:27], v[184:187], v[192:195], v[24:27]
	v_mfma_f32_16x16x32_bf16 v[20:23], v[168:171], v[196:199], v[20:23]
	v_mfma_f32_16x16x32_bf16 v[20:23], v[172:175], v[200:203], v[20:23]
	v_mfma_f32_16x16x32_bf16 v[16:19], v[176:179], v[196:199], v[16:19]
	v_mfma_f32_16x16x32_bf16 v[16:19], v[184:187], v[200:203], v[16:19]
	v_mfma_f32_16x16x32_bf16 v[12:15], v[168:171], v[204:207], v[12:15]
	v_mfma_f32_16x16x32_bf16 v[12:15], v[172:175], v[208:211], v[12:15]
	v_mfma_f32_16x16x32_bf16 v[8:11], v[176:179], v[204:207], v[8:11]
	v_mfma_f32_16x16x32_bf16 v[8:11], v[184:187], v[208:211], v[8:11]
	v_mfma_f32_16x16x32_bf16 v[4:7], v[168:171], v[212:215], v[4:7]
	v_mfma_f32_16x16x32_bf16 v[4:7], v[172:175], v[216:219], v[4:7]
	s_barrier
	v_mfma_f32_16x16x32_bf16 v[0:3], v[176:179], v[212:215], v[0:3]
	v_mfma_f32_16x16x32_bf16 v[0:3], v[184:187], v[216:219], v[0:3]
	s_setprio 0
	s_add_i32 s87, s87, 2
	s_add_u32 s60, s60, 0x100
	s_addc_u32 s61, s61, 0
	s_add_u32 s85, s85, 0x100
	s_addc_u32 s86, s86, 0
	s_cmp_gt_u32 s87, 13
	s_cbranch_scc0 .LBB0_1162

.Lmid_gemm10:
	s_add_i32 s79, 0, 0x18000
	s_add_i32 s87, 0, 0x1c000
	v_add_u32_e32 v164, s79, v147
	v_add_u32_e32 v181, s87, v147
	ds_read_b128 v[152:155], v164
	ds_read_b128 v[156:159], v164 offset:1024
	ds_read_b128 v[160:163], v164 offset:2048
	ds_read_b128 v[164:167], v164 offset:3072
	ds_read_b128 v[168:171], v181
	ds_read_b128 v[172:175], v181 offset:1024
	ds_read_b128 v[176:179], v181 offset:2048
	ds_read_b128 v[184:187], v181 offset:3072
	s_add_u32 s60, s60, 0x40000
	s_addc_u32 s61, s61, 0
	s_mov_b32 m0, s66
	v_lshl_add_u64 v[226:227], s[60:61], 0, v[128:129]
	ds_read_b128 v[188:191], v151 offset:32768
	ds_read_b128 v[192:195], v151 offset:33792
	ds_read_b128 v[196:199], v151 offset:34816
	ds_read_b128 v[200:203], v151 offset:35840
	ds_read_b128 v[204:207], v151 offset:36864
	ds_read_b128 v[208:211], v151 offset:37888
	ds_read_b128 v[212:215], v151 offset:38912
	ds_read_b128 v[216:219], v151 offset:39936
	global_load_lds_dwordx4 v[226:227], off
	v_lshl_add_u64 v[226:227], s[60:61], 0, v[132:133]
	s_mov_b32 m0, s67
	s_nop 0
	global_load_lds_dwordx4 v[226:227], off
	s_waitcnt vmcnt(8)
	s_waitcnt lgkmcnt(0)
	s_barrier
	s_waitcnt lgkmcnt(0)
	v_mfma_f32_16x16x32_bf16 v[124:127], v[152:155], v[188:191], v[124:127]
	v_mfma_f32_16x16x32_bf16 v[124:127], v[156:159], v[192:195], v[124:127]
	s_setprio 1
	v_mfma_f32_16x16x32_bf16 v[120:123], v[160:163], v[188:191], v[120:123]
	v_mfma_f32_16x16x32_bf16 v[120:123], v[164:167], v[192:195], v[120:123]
	v_mfma_f32_16x16x32_bf16 v[116:119], v[152:155], v[196:199], v[116:119]
	v_mfma_f32_16x16x32_bf16 v[116:119], v[156:159], v[200:203], v[116:119]
	v_mfma_f32_16x16x32_bf16 v[108:111], v[160:163], v[196:199], v[108:111]
	v_mfma_f32_16x16x32_bf16 v[108:111], v[164:167], v[200:203], v[108:111]
	v_mfma_f32_16x16x32_bf16 v[100:103], v[152:155], v[204:207], v[100:103]
	v_mfma_f32_16x16x32_bf16 v[100:103], v[156:159], v[208:211], v[100:103]
	v_mfma_f32_16x16x32_bf16 v[92:95], v[160:163], v[204:207], v[92:95]
	v_mfma_f32_16x16x32_bf16 v[92:95], v[164:167], v[208:211], v[92:95]
	v_mfma_f32_16x16x32_bf16 v[84:87], v[152:155], v[212:215], v[84:87]
	v_mfma_f32_16x16x32_bf16 v[84:87], v[156:159], v[216:219], v[84:87]
	v_mfma_f32_16x16x32_bf16 v[76:79], v[160:163], v[212:215], v[76:79]
	v_mfma_f32_16x16x32_bf16 v[76:79], v[164:167], v[216:219], v[76:79]
	v_mfma_f32_16x16x32_bf16 v[112:115], v[168:171], v[188:191], v[112:115]
	v_mfma_f32_16x16x32_bf16 v[112:115], v[172:175], v[192:195], v[112:115]
	v_mfma_f32_16x16x32_bf16 v[104:107], v[176:179], v[188:191], v[104:107]
	v_mfma_f32_16x16x32_bf16 v[104:107], v[184:187], v[192:195], v[104:107]
	v_mfma_f32_16x16x32_bf16 v[96:99], v[168:171], v[196:199], v[96:99]
	v_mfma_f32_16x16x32_bf16 v[96:99], v[172:175], v[200:203], v[96:99]
	v_mfma_f32_16x16x32_bf16 v[88:91], v[176:179], v[196:199], v[88:91]
	v_mfma_f32_16x16x32_bf16 v[88:91], v[184:187], v[200:203], v[88:91]
	v_mfma_f32_16x16x32_bf16 v[80:83], v[168:171], v[204:207], v[80:83]
	v_mfma_f32_16x16x32_bf16 v[80:83], v[172:175], v[208:211], v[80:83]
	v_mfma_f32_16x16x32_bf16 v[72:75], v[176:179], v[204:207], v[72:75]
	v_mfma_f32_16x16x32_bf16 v[72:75], v[184:187], v[208:211], v[72:75]
	v_mfma_f32_16x16x32_bf16 v[68:71], v[168:171], v[212:215], v[68:71]
	v_mfma_f32_16x16x32_bf16 v[68:71], v[172:175], v[216:219], v[68:71]
	s_barrier
	v_mfma_f32_16x16x32_bf16 v[64:67], v[176:179], v[212:215], v[64:67]
	v_mfma_f32_16x16x32_bf16 v[64:67], v[184:187], v[216:219], v[64:67]
	s_setprio 0
	s_add_i32 s60, s79, s64
	v_lshl_add_u64 v[144:145], v[144:145], 0, s[16:17]
	s_mov_b32 m0, s60
	ds_read_b128 v[188:191], v151 offset:49152
	ds_read_b128 v[192:195], v151 offset:50176
	ds_read_b128 v[196:199], v151 offset:51200
	ds_read_b128 v[200:203], v151 offset:52224
	ds_read_b128 v[204:207], v151 offset:53248
	ds_read_b128 v[208:211], v151 offset:54272
	ds_read_b128 v[212:215], v151 offset:55296
	ds_read_b128 v[216:219], v151 offset:56320
	global_load_lds_dwordx4 v[144:145], off
	s_add_i32 m0, s60, 0x2000
	s_add_u32 s58, s58, 0x40080
	v_lshl_add_u64 v[144:145], v[220:221], 0, s[16:17]
	s_addc_u32 s59, s59, 0
	s_add_i32 s60, s87, s64
	global_load_lds_dwordx4 v[144:145], off
	v_lshl_add_u64 v[144:145], s[58:59], 0, v[130:131]
	s_mov_b32 m0, s60
	s_nop 0
	global_load_lds_dwordx4 v[144:145], off
	v_lshl_add_u64 v[144:145], s[58:59], 0, v[134:135]
	s_add_i32 m0, s60, 0x2000
	s_nop 0
	global_load_lds_dwordx4 v[144:145], off
	v_lshl_add_u64 v[144:145], v[222:223], 0, s[16:17]
	s_mov_b32 m0, s69
	s_nop 0
	global_load_lds_dwordx4 v[144:145], off
	v_lshl_add_u64 v[144:145], v[224:225], 0, s[16:17]
	s_mov_b32 m0, s70
	s_nop 0
	global_load_lds_dwordx4 v[144:145], off
	s_waitcnt vmcnt(8)
	s_waitcnt lgkmcnt(0)
	s_barrier
	s_waitcnt lgkmcnt(0)
	v_mfma_f32_16x16x32_bf16 v[60:63], v[152:155], v[188:191], v[60:63]
	v_mfma_f32_16x16x32_bf16 v[60:63], v[156:159], v[192:195], v[60:63]
	s_setprio 1
	v_mfma_f32_16x16x32_bf16 v[56:59], v[160:163], v[188:191], v[56:59]
	v_mfma_f32_16x16x32_bf16 v[56:59], v[164:167], v[192:195], v[56:59]
	v_mfma_f32_16x16x32_bf16 v[52:55], v[152:155], v[196:199], v[52:55]
	v_mfma_f32_16x16x32_bf16 v[52:55], v[156:159], v[200:203], v[52:55]
	v_mfma_f32_16x16x32_bf16 v[44:47], v[160:163], v[196:199], v[44:47]
	v_mfma_f32_16x16x32_bf16 v[44:47], v[164:167], v[200:203], v[44:47]
	v_mfma_f32_16x16x32_bf16 v[36:39], v[152:155], v[204:207], v[36:39]
	v_mfma_f32_16x16x32_bf16 v[36:39], v[156:159], v[208:211], v[36:39]
	v_mfma_f32_16x16x32_bf16 v[28:31], v[160:163], v[204:207], v[28:31]
	v_mfma_f32_16x16x32_bf16 v[28:31], v[164:167], v[208:211], v[28:31]
	v_mfma_f32_16x16x32_bf16 v[20:23], v[152:155], v[212:215], v[20:23]
	v_mfma_f32_16x16x32_bf16 v[20:23], v[156:159], v[216:219], v[20:23]
	v_mfma_f32_16x16x32_bf16 v[12:15], v[160:163], v[212:215], v[12:15]
	v_mfma_f32_16x16x32_bf16 v[12:15], v[164:167], v[216:219], v[12:15]
	v_mfma_f32_16x16x32_bf16 v[48:51], v[168:171], v[188:191], v[48:51]
	v_mfma_f32_16x16x32_bf16 v[48:51], v[172:175], v[192:195], v[48:51]
	v_mfma_f32_16x16x32_bf16 v[40:43], v[176:179], v[188:191], v[40:43]
	v_mfma_f32_16x16x32_bf16 v[40:43], v[184:187], v[192:195], v[40:43]
	v_mfma_f32_16x16x32_bf16 v[32:35], v[168:171], v[196:199], v[32:35]
	v_mfma_f32_16x16x32_bf16 v[32:35], v[172:175], v[200:203], v[32:35]
	v_mfma_f32_16x16x32_bf16 v[24:27], v[176:179], v[196:199], v[24:27]
	v_mfma_f32_16x16x32_bf16 v[24:27], v[184:187], v[200:203], v[24:27]
	v_mfma_f32_16x16x32_bf16 v[16:19], v[168:171], v[204:207], v[16:19]
	v_mfma_f32_16x16x32_bf16 v[16:19], v[172:175], v[208:211], v[16:19]
	v_mfma_f32_16x16x32_bf16 v[8:11], v[176:179], v[204:207], v[8:11]
	v_mfma_f32_16x16x32_bf16 v[8:11], v[184:187], v[208:211], v[8:11]
	v_mfma_f32_16x16x32_bf16 v[4:7], v[168:171], v[212:215], v[4:7]
	v_mfma_f32_16x16x32_bf16 v[4:7], v[172:175], v[216:219], v[4:7]
	s_barrier
	v_mfma_f32_16x16x32_bf16 v[0:3], v[176:179], v[212:215], v[0:3]
	v_mfma_f32_16x16x32_bf16 v[0:3], v[184:187], v[216:219], v[0:3]
	s_setprio 0
	s_add_i32 s86, s86, 2
	s_add_u32 s56, s56, 0x100
	s_addc_u32 s57, s57, 0
	s_add_u32 s84, s84, 0x100
	s_addc_u32 s85, s85, 0
	s_cmp_gt_u32 s86, 13
	s_cbranch_scc0 .LBB0_1311

.Lmid_gemm11:
	s_add_i32 s71, 0, 0x18000
	s_add_i32 s72, 0, 0x1c000
	v_add_u32_e32 v158, s71, v145
	v_add_u32_e32 v174, s72, v145
	ds_read_b128 v[140:143], v158
	ds_read_b128 v[150:153], v158 offset:1024
	ds_read_b128 v[154:157], v158 offset:2048
	ds_read_b128 v[158:161], v158 offset:3072
	ds_read_b128 v[162:165], v174
	ds_read_b128 v[166:169], v174 offset:1024
	ds_read_b128 v[170:173], v174 offset:2048
	ds_read_b128 v[174:177], v174 offset:3072
	s_add_u32 s50, s50, 0x40000
	s_addc_u32 s51, s51, 0
	s_mov_b32 m0, s57
	v_lshl_add_u64 v[222:223], s[50:51], 0, v[130:131]
	ds_read_b128 v[184:187], v149 offset:32768
	ds_read_b128 v[188:191], v149 offset:33792
	ds_read_b128 v[192:195], v149 offset:34816
	ds_read_b128 v[196:199], v149 offset:35840
	ds_read_b128 v[200:203], v149 offset:36864
	ds_read_b128 v[204:207], v149 offset:37888
	ds_read_b128 v[208:211], v149 offset:38912
	ds_read_b128 v[212:215], v149 offset:39936
	global_load_lds_dwordx4 v[222:223], off
	v_lshl_add_u64 v[222:223], s[50:51], 0, v[128:129]
	s_mov_b32 m0, s58
	s_nop 0
	global_load_lds_dwordx4 v[222:223], off
	s_waitcnt vmcnt(8)
	s_waitcnt lgkmcnt(0)
	s_barrier
	s_waitcnt lgkmcnt(0)
	v_mfma_f32_16x16x32_bf16 v[124:127], v[140:143], v[184:187], v[124:127]
	v_mfma_f32_16x16x32_bf16 v[124:127], v[150:153], v[188:191], v[124:127]
	s_setprio 1
	v_mfma_f32_16x16x32_bf16 v[120:123], v[154:157], v[184:187], v[120:123]
	v_mfma_f32_16x16x32_bf16 v[120:123], v[158:161], v[188:191], v[120:123]
	v_mfma_f32_16x16x32_bf16 v[108:111], v[140:143], v[192:195], v[108:111]
	v_mfma_f32_16x16x32_bf16 v[108:111], v[150:153], v[196:199], v[108:111]
	v_mfma_f32_16x16x32_bf16 v[104:107], v[154:157], v[192:195], v[104:107]
	v_mfma_f32_16x16x32_bf16 v[104:107], v[158:161], v[196:199], v[104:107]
	v_mfma_f32_16x16x32_bf16 v[92:95], v[140:143], v[200:203], v[92:95]
	v_mfma_f32_16x16x32_bf16 v[92:95], v[150:153], v[204:207], v[92:95]
	v_mfma_f32_16x16x32_bf16 v[88:91], v[154:157], v[200:203], v[88:91]
	v_mfma_f32_16x16x32_bf16 v[88:91], v[158:161], v[204:207], v[88:91]
	v_mfma_f32_16x16x32_bf16 v[76:79], v[140:143], v[208:211], v[76:79]
	v_mfma_f32_16x16x32_bf16 v[76:79], v[150:153], v[212:215], v[76:79]
	v_mfma_f32_16x16x32_bf16 v[72:75], v[154:157], v[208:211], v[72:75]
	v_mfma_f32_16x16x32_bf16 v[72:75], v[158:161], v[212:215], v[72:75]
	v_mfma_f32_16x16x32_bf16 v[116:119], v[162:165], v[184:187], v[116:119]
	v_mfma_f32_16x16x32_bf16 v[116:119], v[166:169], v[188:191], v[116:119]
	v_mfma_f32_16x16x32_bf16 v[112:115], v[170:173], v[184:187], v[112:115]
	v_mfma_f32_16x16x32_bf16 v[112:115], v[174:177], v[188:191], v[112:115]
	v_mfma_f32_16x16x32_bf16 v[100:103], v[162:165], v[192:195], v[100:103]
	v_mfma_f32_16x16x32_bf16 v[100:103], v[166:169], v[196:199], v[100:103]
	v_mfma_f32_16x16x32_bf16 v[96:99], v[170:173], v[192:195], v[96:99]
	v_mfma_f32_16x16x32_bf16 v[96:99], v[174:177], v[196:199], v[96:99]
	v_mfma_f32_16x16x32_bf16 v[84:87], v[162:165], v[200:203], v[84:87]
	v_mfma_f32_16x16x32_bf16 v[84:87], v[166:169], v[204:207], v[84:87]
	v_mfma_f32_16x16x32_bf16 v[80:83], v[170:173], v[200:203], v[80:83]
	v_mfma_f32_16x16x32_bf16 v[80:83], v[174:177], v[204:207], v[80:83]
	v_mfma_f32_16x16x32_bf16 v[68:71], v[162:165], v[208:211], v[68:71]
	v_mfma_f32_16x16x32_bf16 v[68:71], v[166:169], v[212:215], v[68:71]
	s_barrier
	v_mfma_f32_16x16x32_bf16 v[64:67], v[170:173], v[208:211], v[64:67]
	v_mfma_f32_16x16x32_bf16 v[64:67], v[174:177], v[212:215], v[64:67]
	s_setprio 0
	s_add_i32 s50, s71, s54
	v_lshl_add_u64 v[178:179], v[178:179], 0, s[10:11]
	s_mov_b32 m0, s50
	ds_read_b128 v[184:187], v149 offset:49152
	ds_read_b128 v[188:191], v149 offset:50176
	ds_read_b128 v[192:195], v149 offset:51200
	ds_read_b128 v[196:199], v149 offset:52224
	ds_read_b128 v[200:203], v149 offset:53248
	ds_read_b128 v[204:207], v149 offset:54272
	ds_read_b128 v[208:211], v149 offset:55296
	ds_read_b128 v[212:215], v149 offset:56320
	global_load_lds_dwordx4 v[178:179], off
	s_add_i32 m0, s50, 0x2000
	s_add_u32 s48, s48, 0x40080
	v_lshl_add_u64 v[178:179], v[216:217], 0, s[10:11]
	s_addc_u32 s49, s49, 0
	s_add_i32 s50, s72, s54
	global_load_lds_dwordx4 v[178:179], off
	v_lshl_add_u64 v[178:179], s[48:49], 0, v[130:131]
	s_mov_b32 m0, s50
	s_nop 0
	global_load_lds_dwordx4 v[178:179], off
	v_lshl_add_u64 v[178:179], s[48:49], 0, v[128:129]
	s_add_i32 m0, s50, 0x2000
	s_nop 0
	global_load_lds_dwordx4 v[178:179], off
	v_lshl_add_u64 v[178:179], v[218:219], 0, s[10:11]
	s_mov_b32 m0, s60
	s_nop 0
	global_load_lds_dwordx4 v[178:179], off
	v_lshl_add_u64 v[178:179], v[220:221], 0, s[10:11]
	s_mov_b32 m0, s61
	s_nop 0
	global_load_lds_dwordx4 v[178:179], off
	s_waitcnt vmcnt(8)
	s_waitcnt lgkmcnt(0)
	s_barrier
	s_waitcnt lgkmcnt(0)
	v_mfma_f32_16x16x32_bf16 v[60:63], v[140:143], v[184:187], v[60:63]
	v_mfma_f32_16x16x32_bf16 v[60:63], v[150:153], v[188:191], v[60:63]
	s_setprio 1
	v_mfma_f32_16x16x32_bf16 v[56:59], v[154:157], v[184:187], v[56:59]
	v_mfma_f32_16x16x32_bf16 v[56:59], v[158:161], v[188:191], v[56:59]
	v_mfma_f32_16x16x32_bf16 v[44:47], v[140:143], v[192:195], v[44:47]
	v_mfma_f32_16x16x32_bf16 v[44:47], v[150:153], v[196:199], v[44:47]
	v_mfma_f32_16x16x32_bf16 v[40:43], v[154:157], v[192:195], v[40:43]
	v_mfma_f32_16x16x32_bf16 v[40:43], v[158:161], v[196:199], v[40:43]
	v_mfma_f32_16x16x32_bf16 v[28:31], v[140:143], v[200:203], v[28:31]
	v_mfma_f32_16x16x32_bf16 v[28:31], v[150:153], v[204:207], v[28:31]
	v_mfma_f32_16x16x32_bf16 v[24:27], v[154:157], v[200:203], v[24:27]
	v_mfma_f32_16x16x32_bf16 v[24:27], v[158:161], v[204:207], v[24:27]
	v_mfma_f32_16x16x32_bf16 v[12:15], v[140:143], v[208:211], v[12:15]
	v_mfma_f32_16x16x32_bf16 v[12:15], v[150:153], v[212:215], v[12:15]
	v_mfma_f32_16x16x32_bf16 v[8:11], v[154:157], v[208:211], v[8:11]
	v_mfma_f32_16x16x32_bf16 v[8:11], v[158:161], v[212:215], v[8:11]
	v_mfma_f32_16x16x32_bf16 v[52:55], v[162:165], v[184:187], v[52:55]
	v_mfma_f32_16x16x32_bf16 v[52:55], v[166:169], v[188:191], v[52:55]
	v_mfma_f32_16x16x32_bf16 v[48:51], v[170:173], v[184:187], v[48:51]
	v_mfma_f32_16x16x32_bf16 v[48:51], v[174:177], v[188:191], v[48:51]
	v_mfma_f32_16x16x32_bf16 v[36:39], v[162:165], v[192:195], v[36:39]
	v_mfma_f32_16x16x32_bf16 v[36:39], v[166:169], v[196:199], v[36:39]
	v_mfma_f32_16x16x32_bf16 v[32:35], v[170:173], v[192:195], v[32:35]
	v_mfma_f32_16x16x32_bf16 v[32:35], v[174:177], v[196:199], v[32:35]
	v_mfma_f32_16x16x32_bf16 v[20:23], v[162:165], v[200:203], v[20:23]
	v_mfma_f32_16x16x32_bf16 v[20:23], v[166:169], v[204:207], v[20:23]
	v_mfma_f32_16x16x32_bf16 v[16:19], v[170:173], v[200:203], v[16:19]
	v_mfma_f32_16x16x32_bf16 v[16:19], v[174:177], v[204:207], v[16:19]
	v_mfma_f32_16x16x32_bf16 v[4:7], v[162:165], v[208:211], v[4:7]
	v_mfma_f32_16x16x32_bf16 v[4:7], v[166:169], v[212:215], v[4:7]
	s_barrier
	v_mfma_f32_16x16x32_bf16 v[0:3], v[170:173], v[208:211], v[0:3]
	v_mfma_f32_16x16x32_bf16 v[0:3], v[174:177], v[212:215], v[0:3]
	s_setprio 0
	s_add_i32 s70, s70, 2
	s_add_u32 s46, s46, 0x100
	s_addc_u32 s47, s47, 0
	s_add_u32 s68, s68, 0x100
	s_addc_u32 s69, s69, 0
	s_cmp_gt_u32 s70, 13
	s_cbranch_scc0 .LBB0_1434
.LBB0_1437:
	s_mov_b64 s[98:99], 0x16000
	s_mov_b64 s[100:101], 0x6e000
	v_mul_f32_e32 v151, 0xbfb8aa3b, v124
	v_exp_f32_e32 v151, v151
	v_mul_f32_e32 v154, 0xbfb8aa3b, v125
	v_exp_f32_e32 v154, v154
	v_lshl_or_b32 v142, s65, 7, v146
	v_add_f32_e32 v151, 1.0, v151
	v_rcp_f32_e32 v151, v151
	v_lshl_add_u32 v150, s44, 8, v144
	v_ashrrev_i32_e32 v143, 31, v142
	v_mov_b64_e32 v[140:141], s[22:23]
	v_mul_f32_e32 v124, v124, v151
	v_mul_f32_e32 v120, v120, v124
	v_add_f32_e32 v124, 1.0, v154
	v_mul_f32_e32 v151, 0xbfb8aa3b, v126
	v_rcp_f32_e32 v124, v124
	v_exp_f32_e32 v151, v151
	v_mul_f32_e32 v154, 0xbfb8aa3b, v127
	v_exp_f32_e32 v154, v154
	v_mul_f32_e32 v124, v125, v124
	v_add_f32_e32 v125, 1.0, v151
	v_rcp_f32_e32 v125, v125
	v_add_f32_e32 v151, 1.0, v154
	v_rcp_f32_e32 v151, v151
	v_mul_f32_e32 v121, v121, v124
	v_mul_f32_e32 v124, v126, v125
	v_mul_f32_e32 v125, 0xbfb8aa3b, v116
	v_exp_f32_e32 v125, v125
	v_mul_f32_e32 v122, v122, v124
	v_mul_f32_e32 v124, v127, v151
	v_mul_f32_e32 v123, v123, v124
	v_cvt_pk_bf16_f32 v120, v120, v121
	v_cvt_pk_bf16_f32 v121, v122, v123
	v_add_f32_e32 v122, 1.0, v125
	v_rcp_f32_e32 v122, v122
	v_mul_f32_e32 v123, 0xbfb8aa3b, v117
	v_exp_f32_e32 v123, v123
	v_mad_i64_i32 v[152:153], s[46:47], v150, s64, v[140:141]
	v_lshlrev_b64 v[142:143], 1, v[142:143]
	v_lshl_add_u64 v[152:153], v[152:153], 0, v[142:143]
	v_mul_f32_e32 v116, v116, v122
	global_store_dwordx2 v[152:153], v[120:121], off
	v_mul_f32_e32 v112, v112, v116
	v_add_f32_e32 v116, 1.0, v123
	v_mul_f32_e32 v120, 0xbfb8aa3b, v118
	v_rcp_f32_e32 v116, v116
	v_exp_f32_e32 v120, v120
	v_mul_f32_e32 v121, 0xbfb8aa3b, v119
	v_exp_f32_e32 v121, v121
	v_mul_f32_e32 v116, v117, v116
	v_add_f32_e32 v117, 1.0, v120
	v_rcp_f32_e32 v117, v117
	v_add_f32_e32 v120, 1.0, v121
	v_rcp_f32_e32 v120, v120
	v_mul_f32_e32 v113, v113, v116
	v_mul_f32_e32 v116, v118, v117
	v_mul_f32_e32 v114, v114, v116
	v_mul_f32_e32 v116, v119, v120
	v_cvt_pk_bf16_f32 v112, v112, v113
	v_mul_f32_e32 v115, v115, v116
	v_cvt_pk_bf16_f32 v113, v114, v115
	global_store_dwordx2 v[152:153], v[112:113], off offset:128
	v_mul_f32_e32 v112, 0xbfb8aa3b, v108
	v_exp_f32_e32 v114, v112
	v_mul_f32_e32 v115, 0xbfb8aa3b, v109
	s_and_b64 vcc, exec, s[12:13]
	s_cbranch_vccz .Lxb_11
	s_barrier
.Lxb_11:
	v_exp_f32_e32 v115, v115
	v_add_f32_e32 v114, 1.0, v114
	v_rcp_f32_e32 v114, v114
	v_lshl_add_u64 v[112:113], v[152:153], 0, s[98:99]
	v_mul_f32_e32 v108, v108, v114
	v_mul_f32_e32 v104, v104, v108
	v_add_f32_e32 v108, 1.0, v115
	v_mul_f32_e32 v114, 0xbfb8aa3b, v110
	v_rcp_f32_e32 v108, v108
	v_exp_f32_e32 v114, v114
	v_mul_f32_e32 v115, 0xbfb8aa3b, v111
	v_exp_f32_e32 v115, v115
	v_mul_f32_e32 v108, v109, v108
	v_add_f32_e32 v109, 1.0, v114
	v_rcp_f32_e32 v109, v109
	v_add_f32_e32 v114, 1.0, v115
	v_rcp_f32_e32 v114, v114
	v_mul_f32_e32 v105, v105, v108
	v_mul_f32_e32 v108, v110, v109
	v_mul_f32_e32 v109, 0xbfb8aa3b, v100
	v_exp_f32_e32 v109, v109
	v_mul_f32_e32 v106, v106, v108
	v_mul_f32_e32 v108, v111, v114
	v_mul_f32_e32 v107, v107, v108
	v_cvt_pk_bf16_f32 v104, v104, v105
	v_cvt_pk_bf16_f32 v105, v106, v107
	v_add_f32_e32 v106, 1.0, v109
	v_rcp_f32_e32 v106, v106
	v_mul_f32_e32 v107, 0xbfb8aa3b, v101
	v_exp_f32_e32 v107, v107
	global_store_dwordx2 v[112:113], v[104:105], off
	v_mul_f32_e32 v100, v100, v106
	v_mul_f32_e32 v96, v96, v100
	v_add_f32_e32 v100, 1.0, v107
	v_mul_f32_e32 v104, 0xbfb8aa3b, v102
	v_rcp_f32_e32 v100, v100
	v_exp_f32_e32 v104, v104
	v_mul_f32_e32 v105, 0xbfb8aa3b, v103
	v_exp_f32_e32 v105, v105
	v_mul_f32_e32 v100, v101, v100
	v_add_f32_e32 v101, 1.0, v104
	v_rcp_f32_e32 v101, v101
	v_add_f32_e32 v104, 1.0, v105
	v_rcp_f32_e32 v104, v104
	v_mul_f32_e32 v97, v97, v100
	v_mul_f32_e32 v100, v102, v101
	v_mul_f32_e32 v98, v98, v100
	v_mul_f32_e32 v100, v103, v104
	v_cvt_pk_bf16_f32 v96, v96, v97
	v_mul_f32_e32 v99, v99, v100
	v_cvt_pk_bf16_f32 v97, v98, v99
	global_store_dwordx2 v[112:113], v[96:97], off offset:128
	v_mul_f32_e32 v96, 0xbfb8aa3b, v92
	v_exp_f32_e32 v98, v96
	v_mul_f32_e32 v99, 0xbfb8aa3b, v93
	v_exp_f32_e32 v99, v99
	v_add_f32_e32 v98, 1.0, v98
	v_rcp_f32_e32 v98, v98
	v_lshl_add_u64 v[96:97], v[112:113], 0, s[98:99]
	v_mul_f32_e32 v92, v92, v98
	v_mul_f32_e32 v88, v88, v92
	v_add_f32_e32 v92, 1.0, v99
	v_mul_f32_e32 v98, 0xbfb8aa3b, v94
	v_rcp_f32_e32 v92, v92
	v_exp_f32_e32 v98, v98
	v_mul_f32_e32 v99, 0xbfb8aa3b, v95
	v_exp_f32_e32 v99, v99
	v_mul_f32_e32 v92, v93, v92
	v_add_f32_e32 v93, 1.0, v98
	v_rcp_f32_e32 v93, v93
	v_add_f32_e32 v98, 1.0, v99
	v_rcp_f32_e32 v98, v98
	v_mul_f32_e32 v89, v89, v92
	v_mul_f32_e32 v92, v94, v93
	v_mul_f32_e32 v93, 0xbfb8aa3b, v84
	v_exp_f32_e32 v93, v93
	v_mul_f32_e32 v90, v90, v92
	v_mul_f32_e32 v92, v95, v98
	v_mul_f32_e32 v91, v91, v92
	v_cvt_pk_bf16_f32 v88, v88, v89
	v_cvt_pk_bf16_f32 v89, v90, v91
	v_add_f32_e32 v90, 1.0, v93
	v_rcp_f32_e32 v90, v90
	v_mul_f32_e32 v91, 0xbfb8aa3b, v85
	v_exp_f32_e32 v91, v91
	global_store_dwordx2 v[96:97], v[88:89], off
	v_mul_f32_e32 v84, v84, v90
	v_mul_f32_e32 v80, v80, v84
	v_add_f32_e32 v84, 1.0, v91
	v_mul_f32_e32 v88, 0xbfb8aa3b, v86
	v_rcp_f32_e32 v84, v84
	v_exp_f32_e32 v88, v88
	v_mul_f32_e32 v89, 0xbfb8aa3b, v87
	v_exp_f32_e32 v89, v89
	v_mul_f32_e32 v84, v85, v84
	v_add_f32_e32 v85, 1.0, v88
	v_rcp_f32_e32 v85, v85
	v_add_f32_e32 v88, 1.0, v89
	v_rcp_f32_e32 v88, v88
	v_mul_f32_e32 v81, v81, v84
	v_mul_f32_e32 v84, v86, v85
	v_mul_f32_e32 v82, v82, v84
	v_mul_f32_e32 v84, v87, v88
	v_cvt_pk_bf16_f32 v80, v80, v81
	v_mul_f32_e32 v83, v83, v84
	v_cvt_pk_bf16_f32 v81, v82, v83
	global_store_dwordx2 v[96:97], v[80:81], off offset:128
	v_mul_f32_e32 v80, 0xbfb8aa3b, v76
	v_exp_f32_e32 v82, v80
	v_mul_f32_e32 v83, 0xbfb8aa3b, v77
	v_exp_f32_e32 v83, v83
	v_add_f32_e32 v82, 1.0, v82
	v_rcp_f32_e32 v82, v82
	v_lshl_add_u64 v[80:81], v[96:97], 0, s[98:99]
	v_mul_f32_e32 v76, v76, v82
	v_mul_f32_e32 v72, v72, v76
	v_add_f32_e32 v76, 1.0, v83
	v_mul_f32_e32 v82, 0xbfb8aa3b, v78
	v_rcp_f32_e32 v76, v76
	v_exp_f32_e32 v82, v82
	v_mul_f32_e32 v83, 0xbfb8aa3b, v79
	v_exp_f32_e32 v83, v83
	v_mul_f32_e32 v76, v77, v76
	v_add_f32_e32 v77, 1.0, v82
	v_rcp_f32_e32 v77, v77
	v_add_f32_e32 v82, 1.0, v83
	v_rcp_f32_e32 v82, v82
	v_mul_f32_e32 v73, v73, v76
	v_mul_f32_e32 v76, v78, v77
	v_mul_f32_e32 v77, 0xbfb8aa3b, v68
	v_exp_f32_e32 v77, v77
	v_mul_f32_e32 v74, v74, v76
	v_mul_f32_e32 v76, v79, v82
	v_mul_f32_e32 v75, v75, v76
	v_cvt_pk_bf16_f32 v72, v72, v73
	v_cvt_pk_bf16_f32 v73, v74, v75
	v_add_f32_e32 v74, 1.0, v77
	v_rcp_f32_e32 v74, v74
	v_mul_f32_e32 v75, 0xbfb8aa3b, v69
	v_exp_f32_e32 v75, v75
	global_store_dwordx2 v[80:81], v[72:73], off
	v_mul_f32_e32 v68, v68, v74
	v_mul_f32_e32 v64, v64, v68
	v_add_f32_e32 v68, 1.0, v75
	v_mul_f32_e32 v72, 0xbfb8aa3b, v70
	v_rcp_f32_e32 v68, v68
	v_exp_f32_e32 v72, v72
	v_mul_f32_e32 v73, 0xbfb8aa3b, v71
	v_exp_f32_e32 v73, v73
	v_mul_f32_e32 v68, v69, v68
	v_add_f32_e32 v69, 1.0, v72
	v_rcp_f32_e32 v69, v69
	v_add_f32_e32 v72, 1.0, v73
	v_rcp_f32_e32 v72, v72
	v_mul_f32_e32 v65, v65, v68
	v_mul_f32_e32 v68, v70, v69
	v_mul_f32_e32 v66, v66, v68
	v_mul_f32_e32 v68, v71, v72
	v_cvt_pk_bf16_f32 v64, v64, v65
	v_mul_f32_e32 v67, v67, v68
	v_cvt_pk_bf16_f32 v65, v66, v67
	global_store_dwordx2 v[80:81], v[64:65], off offset:128
	v_mul_f32_e32 v64, 0xbfb8aa3b, v60
	v_exp_f32_e32 v66, v64
	v_mul_f32_e32 v67, 0xbfb8aa3b, v61
	v_exp_f32_e32 v67, v67
	v_add_f32_e32 v66, 1.0, v66
	v_rcp_f32_e32 v66, v66
	v_lshl_add_u64 v[64:65], v[80:81], 0, s[100:101]
	v_mul_f32_e32 v60, v60, v66
	v_mul_f32_e32 v56, v56, v60
	v_add_f32_e32 v60, 1.0, v67
	v_mul_f32_e32 v66, 0xbfb8aa3b, v62
	v_rcp_f32_e32 v60, v60
	v_exp_f32_e32 v66, v66
	v_mul_f32_e32 v67, 0xbfb8aa3b, v63
	v_exp_f32_e32 v67, v67
	v_mul_f32_e32 v60, v61, v60
	v_add_f32_e32 v61, 1.0, v66
	v_rcp_f32_e32 v61, v61
	v_add_f32_e32 v66, 1.0, v67
	v_rcp_f32_e32 v66, v66
	v_mul_f32_e32 v57, v57, v60
	v_mul_f32_e32 v60, v62, v61
	v_mul_f32_e32 v61, 0xbfb8aa3b, v52
	v_exp_f32_e32 v61, v61
	v_mul_f32_e32 v58, v58, v60
	v_mul_f32_e32 v60, v63, v66
	v_mul_f32_e32 v59, v59, v60
	v_cvt_pk_bf16_f32 v56, v56, v57
	v_cvt_pk_bf16_f32 v57, v58, v59
	v_add_f32_e32 v58, 1.0, v61
	v_rcp_f32_e32 v58, v58
	v_mul_f32_e32 v59, 0xbfb8aa3b, v53
	v_exp_f32_e32 v59, v59
	global_store_dwordx2 v[64:65], v[56:57], off
	v_mul_f32_e32 v52, v52, v58
	v_mul_f32_e32 v48, v48, v52
	v_add_f32_e32 v52, 1.0, v59
	v_mul_f32_e32 v56, 0xbfb8aa3b, v54
	v_rcp_f32_e32 v52, v52
	v_exp_f32_e32 v56, v56
	v_mul_f32_e32 v57, 0xbfb8aa3b, v55
	v_exp_f32_e32 v57, v57
	v_mul_f32_e32 v52, v53, v52
	v_add_f32_e32 v53, 1.0, v56
	v_rcp_f32_e32 v53, v53
	v_add_f32_e32 v56, 1.0, v57
	v_rcp_f32_e32 v56, v56
	v_mul_f32_e32 v49, v49, v52
	v_mul_f32_e32 v52, v54, v53
	v_mul_f32_e32 v50, v50, v52
	v_mul_f32_e32 v52, v55, v56
	v_cvt_pk_bf16_f32 v48, v48, v49
	v_mul_f32_e32 v51, v51, v52
	v_cvt_pk_bf16_f32 v49, v50, v51
	global_store_dwordx2 v[64:65], v[48:49], off offset:128
	v_mul_f32_e32 v48, 0xbfb8aa3b, v44
	v_exp_f32_e32 v50, v48
	v_mul_f32_e32 v51, 0xbfb8aa3b, v45
	v_exp_f32_e32 v51, v51
	v_add_f32_e32 v50, 1.0, v50
	v_rcp_f32_e32 v50, v50
	v_lshl_add_u64 v[48:49], v[64:65], 0, s[98:99]
	v_mul_f32_e32 v44, v44, v50
	v_mul_f32_e32 v40, v40, v44
	v_add_f32_e32 v44, 1.0, v51
	v_mul_f32_e32 v50, 0xbfb8aa3b, v46
	v_rcp_f32_e32 v44, v44
	v_exp_f32_e32 v50, v50
	v_mul_f32_e32 v51, 0xbfb8aa3b, v47
	v_exp_f32_e32 v51, v51
	v_mul_f32_e32 v44, v45, v44
	v_add_f32_e32 v45, 1.0, v50
	v_rcp_f32_e32 v45, v45
	v_add_f32_e32 v50, 1.0, v51
	v_rcp_f32_e32 v50, v50
	v_mul_f32_e32 v41, v41, v44
	v_mul_f32_e32 v44, v46, v45
	v_mul_f32_e32 v45, 0xbfb8aa3b, v36
	v_exp_f32_e32 v45, v45
	v_mul_f32_e32 v42, v42, v44
	v_mul_f32_e32 v44, v47, v50
	v_mul_f32_e32 v43, v43, v44
	v_cvt_pk_bf16_f32 v40, v40, v41
	v_cvt_pk_bf16_f32 v41, v42, v43
	v_add_f32_e32 v42, 1.0, v45
	v_rcp_f32_e32 v42, v42
	v_mul_f32_e32 v43, 0xbfb8aa3b, v37
	v_exp_f32_e32 v43, v43
	global_store_dwordx2 v[48:49], v[40:41], off
	v_mul_f32_e32 v36, v36, v42
	v_mul_f32_e32 v32, v32, v36
	v_add_f32_e32 v36, 1.0, v43
	v_mul_f32_e32 v40, 0xbfb8aa3b, v38
	v_rcp_f32_e32 v36, v36
	v_exp_f32_e32 v40, v40
	v_mul_f32_e32 v41, 0xbfb8aa3b, v39
	v_exp_f32_e32 v41, v41
	v_mul_f32_e32 v36, v37, v36
	v_add_f32_e32 v37, 1.0, v40
	v_rcp_f32_e32 v37, v37
	v_add_f32_e32 v40, 1.0, v41
	v_rcp_f32_e32 v40, v40
	v_mul_f32_e32 v33, v33, v36
	v_mul_f32_e32 v36, v38, v37
	v_mul_f32_e32 v34, v34, v36
	v_mul_f32_e32 v36, v39, v40
	v_cvt_pk_bf16_f32 v32, v32, v33
	v_mul_f32_e32 v35, v35, v36
	v_cvt_pk_bf16_f32 v33, v34, v35
	global_store_dwordx2 v[48:49], v[32:33], off offset:128
	v_mul_f32_e32 v32, 0xbfb8aa3b, v28
	v_exp_f32_e32 v34, v32
	v_mul_f32_e32 v35, 0xbfb8aa3b, v29
	v_exp_f32_e32 v35, v35
	v_add_f32_e32 v34, 1.0, v34
	v_rcp_f32_e32 v34, v34
	v_lshl_add_u64 v[32:33], v[48:49], 0, s[98:99]
	v_mul_f32_e32 v28, v28, v34
	v_mul_f32_e32 v24, v24, v28
	v_add_f32_e32 v28, 1.0, v35
	v_mul_f32_e32 v34, 0xbfb8aa3b, v30
	v_rcp_f32_e32 v28, v28
	v_exp_f32_e32 v34, v34
	v_mul_f32_e32 v35, 0xbfb8aa3b, v31
	v_exp_f32_e32 v35, v35
	v_mul_f32_e32 v28, v29, v28
	v_add_f32_e32 v29, 1.0, v34
	v_rcp_f32_e32 v29, v29
	v_add_f32_e32 v34, 1.0, v35
	v_rcp_f32_e32 v34, v34
	v_mul_f32_e32 v25, v25, v28
	v_mul_f32_e32 v28, v30, v29
	v_mul_f32_e32 v29, 0xbfb8aa3b, v20
	v_exp_f32_e32 v29, v29
	v_mul_f32_e32 v26, v26, v28
	v_mul_f32_e32 v28, v31, v34
	v_mul_f32_e32 v27, v27, v28
	v_cvt_pk_bf16_f32 v24, v24, v25
	v_cvt_pk_bf16_f32 v25, v26, v27
	v_add_f32_e32 v26, 1.0, v29
	v_rcp_f32_e32 v26, v26
	v_mul_f32_e32 v27, 0xbfb8aa3b, v21
	v_exp_f32_e32 v27, v27
	global_store_dwordx2 v[32:33], v[24:25], off
	v_mul_f32_e32 v20, v20, v26
	v_mul_f32_e32 v16, v16, v20
	v_add_f32_e32 v20, 1.0, v27
	v_mul_f32_e32 v24, 0xbfb8aa3b, v22
	v_rcp_f32_e32 v20, v20
	v_exp_f32_e32 v24, v24
	v_mul_f32_e32 v25, 0xbfb8aa3b, v23
	v_exp_f32_e32 v25, v25
	v_mul_f32_e32 v20, v21, v20
	v_add_f32_e32 v21, 1.0, v24
	v_rcp_f32_e32 v21, v21
	v_add_f32_e32 v24, 1.0, v25
	v_rcp_f32_e32 v24, v24
	v_mul_f32_e32 v17, v17, v20
	v_mul_f32_e32 v20, v22, v21
	v_mul_f32_e32 v18, v18, v20
	v_mul_f32_e32 v20, v23, v24
	v_cvt_pk_bf16_f32 v16, v16, v17
	v_mul_f32_e32 v19, v19, v20
	v_cvt_pk_bf16_f32 v17, v18, v19
	global_store_dwordx2 v[32:33], v[16:17], off offset:128
	v_mul_f32_e32 v16, 0xbfb8aa3b, v12
	v_exp_f32_e32 v18, v16
	v_mul_f32_e32 v19, 0xbfb8aa3b, v13
	v_exp_f32_e32 v19, v19
	v_add_f32_e32 v18, 1.0, v18
	v_rcp_f32_e32 v18, v18
	v_lshl_add_u64 v[16:17], v[32:33], 0, s[98:99]
	v_mul_f32_e32 v12, v12, v18
	v_mul_f32_e32 v8, v8, v12
	v_add_f32_e32 v12, 1.0, v19
	v_mul_f32_e32 v18, 0xbfb8aa3b, v14
	v_rcp_f32_e32 v12, v12
	v_exp_f32_e32 v18, v18
	v_mul_f32_e32 v19, 0xbfb8aa3b, v15
	v_exp_f32_e32 v19, v19
	v_mul_f32_e32 v12, v13, v12
	v_add_f32_e32 v13, 1.0, v18
	v_rcp_f32_e32 v13, v13
	v_add_f32_e32 v18, 1.0, v19
	v_rcp_f32_e32 v18, v18
	v_mul_f32_e32 v9, v9, v12
	v_mul_f32_e32 v12, v14, v13
	v_mul_f32_e32 v13, 0xbfb8aa3b, v4
	v_exp_f32_e32 v13, v13
	v_mul_f32_e32 v10, v10, v12
	v_mul_f32_e32 v12, v15, v18
	v_mul_f32_e32 v11, v11, v12
	v_cvt_pk_bf16_f32 v8, v8, v9
	v_cvt_pk_bf16_f32 v9, v10, v11
	v_add_f32_e32 v10, 1.0, v13
	v_rcp_f32_e32 v10, v10
	v_mul_f32_e32 v11, 0xbfb8aa3b, v5
	v_exp_f32_e32 v11, v11
	global_store_dwordx2 v[16:17], v[8:9], off
	v_mul_f32_e32 v4, v4, v10
	v_mul_f32_e32 v0, v0, v4
	v_add_f32_e32 v4, 1.0, v11
	v_mul_f32_e32 v8, 0xbfb8aa3b, v6
	v_rcp_f32_e32 v4, v4
	v_exp_f32_e32 v8, v8
	v_mul_f32_e32 v9, 0xbfb8aa3b, v7
	v_exp_f32_e32 v9, v9
	v_mul_f32_e32 v4, v5, v4
	v_add_f32_e32 v5, 1.0, v8
	v_rcp_f32_e32 v5, v5
	v_add_f32_e32 v8, 1.0, v9
	v_rcp_f32_e32 v8, v8
	v_mul_f32_e32 v1, v1, v4
	v_mul_f32_e32 v4, v6, v5
	v_mul_f32_e32 v2, v2, v4
	v_mul_f32_e32 v4, v7, v8
	s_andn2_b64 vcc, exec, s[8:9]
	s_mov_b64 s[8:9], -1
	v_mul_f32_e32 v3, v3, v4
	v_cvt_pk_bf16_f32 v0, v0, v1
	v_cvt_pk_bf16_f32 v1, v2, v3
	global_store_dwordx2 v[16:17], v[0:1], off offset:128
	s_cbranch_vccnz .LBB0_1430
	s_andn2_b64 vcc, exec, s[0:1]
	s_cbranch_vccnz .LBB0_1429
	s_barrier
	s_branch .LBB0_1429

.Lmid_gemm12:
	s_add_i32 s77, 0, 0x18000
	s_add_i32 s79, 0, 0x1c000
	v_add_u32_e32 v164, s77, v147
	v_add_u32_e32 v181, s79, v147
	ds_read_b128 v[152:155], v164
	ds_read_b128 v[156:159], v164 offset:1024
	ds_read_b128 v[160:163], v164 offset:2048
	ds_read_b128 v[164:167], v164 offset:3072
	ds_read_b128 v[168:171], v181
	ds_read_b128 v[172:175], v181 offset:1024
	ds_read_b128 v[176:179], v181 offset:2048
	ds_read_b128 v[184:187], v181 offset:3072
	s_add_u32 s46, s52, 0xb0000
	s_addc_u32 s47, s53, 0
	s_mov_b32 m0, s59
	v_lshl_add_u64 v[226:227], s[46:47], 0, v[128:129]
	ds_read_b128 v[188:191], v151 offset:32768
	ds_read_b128 v[192:195], v151 offset:33792
	ds_read_b128 v[196:199], v151 offset:34816
	ds_read_b128 v[200:203], v151 offset:35840
	ds_read_b128 v[204:207], v151 offset:36864
	ds_read_b128 v[208:211], v151 offset:37888
	ds_read_b128 v[212:215], v151 offset:38912
	ds_read_b128 v[216:219], v151 offset:39936
	global_load_lds_dwordx4 v[226:227], off
	v_lshl_add_u64 v[226:227], s[46:47], 0, v[132:133]
	s_mov_b32 m0, s60
	s_nop 0
	global_load_lds_dwordx4 v[226:227], off
	s_waitcnt vmcnt(8)
	s_waitcnt lgkmcnt(0)
	s_barrier
	s_waitcnt lgkmcnt(0)
	v_mfma_f32_16x16x32_bf16 v[124:127], v[152:155], v[188:191], v[124:127]
	v_mfma_f32_16x16x32_bf16 v[124:127], v[156:159], v[192:195], v[124:127]
	s_setprio 1
	v_mfma_f32_16x16x32_bf16 v[120:123], v[160:163], v[188:191], v[120:123]
	v_mfma_f32_16x16x32_bf16 v[120:123], v[164:167], v[192:195], v[120:123]
	v_mfma_f32_16x16x32_bf16 v[116:119], v[152:155], v[196:199], v[116:119]
	v_mfma_f32_16x16x32_bf16 v[116:119], v[156:159], v[200:203], v[116:119]
	v_mfma_f32_16x16x32_bf16 v[108:111], v[160:163], v[196:199], v[108:111]
	v_mfma_f32_16x16x32_bf16 v[108:111], v[164:167], v[200:203], v[108:111]
	v_mfma_f32_16x16x32_bf16 v[100:103], v[152:155], v[204:207], v[100:103]
	v_mfma_f32_16x16x32_bf16 v[100:103], v[156:159], v[208:211], v[100:103]
	v_mfma_f32_16x16x32_bf16 v[92:95], v[160:163], v[204:207], v[92:95]
	v_mfma_f32_16x16x32_bf16 v[92:95], v[164:167], v[208:211], v[92:95]
	v_mfma_f32_16x16x32_bf16 v[84:87], v[152:155], v[212:215], v[84:87]
	v_mfma_f32_16x16x32_bf16 v[84:87], v[156:159], v[216:219], v[84:87]
	v_mfma_f32_16x16x32_bf16 v[76:79], v[160:163], v[212:215], v[76:79]
	v_mfma_f32_16x16x32_bf16 v[76:79], v[164:167], v[216:219], v[76:79]
	v_mfma_f32_16x16x32_bf16 v[112:115], v[168:171], v[188:191], v[112:115]
	v_mfma_f32_16x16x32_bf16 v[112:115], v[172:175], v[192:195], v[112:115]
	v_mfma_f32_16x16x32_bf16 v[104:107], v[176:179], v[188:191], v[104:107]
	v_mfma_f32_16x16x32_bf16 v[104:107], v[184:187], v[192:195], v[104:107]
	v_mfma_f32_16x16x32_bf16 v[96:99], v[168:171], v[196:199], v[96:99]
	v_mfma_f32_16x16x32_bf16 v[96:99], v[172:175], v[200:203], v[96:99]
	v_mfma_f32_16x16x32_bf16 v[88:91], v[176:179], v[196:199], v[88:91]
	v_mfma_f32_16x16x32_bf16 v[88:91], v[184:187], v[200:203], v[88:91]
	v_mfma_f32_16x16x32_bf16 v[80:83], v[168:171], v[204:207], v[80:83]
	v_mfma_f32_16x16x32_bf16 v[80:83], v[172:175], v[208:211], v[80:83]
	v_mfma_f32_16x16x32_bf16 v[72:75], v[176:179], v[204:207], v[72:75]
	v_mfma_f32_16x16x32_bf16 v[72:75], v[184:187], v[208:211], v[72:75]
	v_mfma_f32_16x16x32_bf16 v[68:71], v[168:171], v[212:215], v[68:71]
	v_mfma_f32_16x16x32_bf16 v[68:71], v[172:175], v[216:219], v[68:71]
	s_barrier
	v_mfma_f32_16x16x32_bf16 v[64:67], v[176:179], v[212:215], v[64:67]
	v_mfma_f32_16x16x32_bf16 v[64:67], v[184:187], v[216:219], v[64:67]
	s_setprio 0
	s_add_i32 s46, s77, s56
	v_lshl_add_u64 v[144:145], v[144:145], 0, s[10:11]
	s_mov_b32 m0, s46
	ds_read_b128 v[188:191], v151 offset:49152
	ds_read_b128 v[192:195], v151 offset:50176
	ds_read_b128 v[196:199], v151 offset:51200
	ds_read_b128 v[200:203], v151 offset:52224
	ds_read_b128 v[204:207], v151 offset:53248
	ds_read_b128 v[208:211], v151 offset:54272
	ds_read_b128 v[212:215], v151 offset:55296
	ds_read_b128 v[216:219], v151 offset:56320
	global_load_lds_dwordx4 v[144:145], off
	s_add_i32 m0, s46, 0x2000
	s_add_u32 s46, s50, 0xb0080
	v_lshl_add_u64 v[144:145], v[220:221], 0, s[10:11]
	s_addc_u32 s47, s51, 0
	s_add_i32 s50, s79, s56
	global_load_lds_dwordx4 v[144:145], off
	v_lshl_add_u64 v[144:145], s[46:47], 0, v[130:131]
	s_mov_b32 m0, s50
	s_nop 0
	global_load_lds_dwordx4 v[144:145], off
	v_lshl_add_u64 v[144:145], s[46:47], 0, v[134:135]
	s_add_i32 m0, s50, 0x2000
	s_nop 0
	global_load_lds_dwordx4 v[144:145], off
	v_lshl_add_u64 v[144:145], v[222:223], 0, s[10:11]
	s_mov_b32 m0, s62
	s_nop 0
	global_load_lds_dwordx4 v[144:145], off
	v_lshl_add_u64 v[144:145], v[224:225], 0, s[10:11]
	s_mov_b32 m0, s63
	s_nop 0
	global_load_lds_dwordx4 v[144:145], off
	s_waitcnt vmcnt(8)
	s_waitcnt lgkmcnt(0)
	s_barrier
	s_waitcnt lgkmcnt(0)
	v_mfma_f32_16x16x32_bf16 v[60:63], v[152:155], v[188:191], v[60:63]
	v_mfma_f32_16x16x32_bf16 v[60:63], v[156:159], v[192:195], v[60:63]
	s_setprio 1
	v_mfma_f32_16x16x32_bf16 v[56:59], v[160:163], v[188:191], v[56:59]
	v_mfma_f32_16x16x32_bf16 v[56:59], v[164:167], v[192:195], v[56:59]
	v_mfma_f32_16x16x32_bf16 v[52:55], v[152:155], v[196:199], v[52:55]
	v_mfma_f32_16x16x32_bf16 v[52:55], v[156:159], v[200:203], v[52:55]
	v_mfma_f32_16x16x32_bf16 v[44:47], v[160:163], v[196:199], v[44:47]
	v_mfma_f32_16x16x32_bf16 v[44:47], v[164:167], v[200:203], v[44:47]
	v_mfma_f32_16x16x32_bf16 v[36:39], v[152:155], v[204:207], v[36:39]
	v_mfma_f32_16x16x32_bf16 v[36:39], v[156:159], v[208:211], v[36:39]
	v_mfma_f32_16x16x32_bf16 v[28:31], v[160:163], v[204:207], v[28:31]
	v_mfma_f32_16x16x32_bf16 v[28:31], v[164:167], v[208:211], v[28:31]
	v_mfma_f32_16x16x32_bf16 v[20:23], v[152:155], v[212:215], v[20:23]
	v_mfma_f32_16x16x32_bf16 v[20:23], v[156:159], v[216:219], v[20:23]
	v_mfma_f32_16x16x32_bf16 v[12:15], v[160:163], v[212:215], v[12:15]
	v_mfma_f32_16x16x32_bf16 v[12:15], v[164:167], v[216:219], v[12:15]
	v_mfma_f32_16x16x32_bf16 v[48:51], v[168:171], v[188:191], v[48:51]
	v_mfma_f32_16x16x32_bf16 v[48:51], v[172:175], v[192:195], v[48:51]
	v_mfma_f32_16x16x32_bf16 v[40:43], v[176:179], v[188:191], v[40:43]
	v_mfma_f32_16x16x32_bf16 v[40:43], v[184:187], v[192:195], v[40:43]
	v_mfma_f32_16x16x32_bf16 v[32:35], v[168:171], v[196:199], v[32:35]
	v_mfma_f32_16x16x32_bf16 v[32:35], v[172:175], v[200:203], v[32:35]
	v_mfma_f32_16x16x32_bf16 v[24:27], v[176:179], v[196:199], v[24:27]
	v_mfma_f32_16x16x32_bf16 v[24:27], v[184:187], v[200:203], v[24:27]
	v_mfma_f32_16x16x32_bf16 v[16:19], v[168:171], v[204:207], v[16:19]
	v_mfma_f32_16x16x32_bf16 v[16:19], v[172:175], v[208:211], v[16:19]
	v_mfma_f32_16x16x32_bf16 v[8:11], v[176:179], v[204:207], v[8:11]
	v_mfma_f32_16x16x32_bf16 v[8:11], v[184:187], v[208:211], v[8:11]
	v_mfma_f32_16x16x32_bf16 v[4:7], v[168:171], v[212:215], v[4:7]
	v_mfma_f32_16x16x32_bf16 v[4:7], v[172:175], v[216:219], v[4:7]
	s_barrier
	v_mfma_f32_16x16x32_bf16 v[0:3], v[176:179], v[212:215], v[0:3]
	v_mfma_f32_16x16x32_bf16 v[0:3], v[184:187], v[216:219], v[0:3]
	s_setprio 0
	s_add_i32 s76, s76, 2
	s_add_u32 s74, s74, 0x100
	s_addc_u32 s75, s75, 0
	s_cmp_gt_u32 s76, 41
	s_mov_b64 s[46:47], s[48:49]
	s_cbranch_scc0 .LBB0_1514
